# v3 + first K-loop iteration of every GEMM unit peeled with inline-0 C operand on each accumulator's first MFMA; the per-unit accumulator zeroing block is deleted
# speedup vs baseline: 1.0066x; 1.0066x over previous
; #define PG8_STAGE(bufoff, gbase, voff) do { _Pragma("unroll") for (int _i = 0; _i < 2; ++_i) \
;         __builtin_amdgcn_global_load_lds((const unsigned*)((const char*)(gbase) + (voff)[_i]), (PG8_LAS unsigned*)(lds + (bufoff) + ldsw + _i * 8192), 16, 0, 0); } while (0)
; #define PG8_LDA(dst, b, h) do { _Pragma("unroll") for (int m = 0; m < 4; ++m) _Pragma("unroll") for (int k = 0; k < 2; ++k) dst[m][k] = *(const PG8_LAS bf16x8*)(lds + PG8_SA(b, h) + aoff + m * 2048 + k * 1024); } while (0)
; #define PG8_LDB(dst, b, h) do { _Pragma("unroll") for (int n = 0; n < 2; ++n) _Pragma("unroll") for (int k = 0; k < 2; ++k) dst[n][k] = *(const PG8_LAS bf16x8*)(lds + PG8_SB(b, h) + boff + n * 2048 + k * 1024); } while (0)
; #define PG8_MMA(ai, bj, At, Bt) do { __builtin_amdgcn_s_setprio(1); _Pragma("unroll") for (int m = 0; m < 4; ++m) _Pragma("unroll") for (int n = 0; n < 2; ++n) _Pragma("unroll") for (int k = 0; k < 2; ++k) \
;         acc[ai][bj][m][n] = __builtin_amdgcn_mfma_f32_16x16x32_bf16(Bt[n][k], At[m][k], acc[ai][bj][m][n], 0, 0, 0); __builtin_amdgcn_s_setprio(0); } while (0)
; #define PG8_WAIT_V(n) asm volatile("s_waitcnt vmcnt(" #n ")" ::: "memory")
; #define PG8_BAR __builtin_amdgcn_s_barrier()
; template <class Epi, class Sched, bool ALIGN_EPI = false, bool SP2 = false>
; __device__ __forceinline__ void gemm_phase(PG8_LAS unsigned char* lds, const Gemm g, const Sched& S, const Epi& E) {
;     ...
;         for (int t = 0; t < nt; t += 2) {
;             const bool last = (t == nt - 2);
;             const char* a1 = cA + (size_t)(t + 1) * kstep;
;             const char* a2 = last ? nA : cA + (size_t)(t + 2) * kstep; const char* b2 = last ? nB : cB + (size_t)(t + 2) * kstep;
;             const char* a3 = a2 + kstep; const char* b3 = b2 + kstep;
;             if (last && has_next) S.a_ready(nxt);
;             if constexpr (SP2) {
;             PG8_LDB(B0, 0, 0); PG8_LDB(B1, 0, 1); PG8_SCHED; PG8_LDA(At, 0, 0); PG8_STAGE(PG8_SA(1, 1), a1 + hstepA, voffA);
;             PG8_WAIT_V(8); PG8_WAIT_L(0); PG8_BAR; PG8_MMA(0, 0, At, B0); PG8_MMA(0, 1, At, B1); PG8_BAR; PG8_SCHED;
;             PG8_LDA(At, 0, 1); PG8_STAGE(PG8_SB(0, 0), b2, voffB); PG8_STAGE(PG8_SB(0, 1), b2 + hstepB, voffB); PG8_STAGE(PG8_SA(0, 0), a2, voffA);
;             PG8_WAIT_V(8); PG8_WAIT_L(0); PG8_BAR; PG8_MMA(1, 0, At, B0); PG8_MMA(1, 1, At, B1); PG8_BAR; PG8_SCHED;
.LBB0_196:
	s_ashr_i32 s21, s20, 31
	s_lshl_b64 s[22:23], s[20:21], 19
	s_add_u32 s22, s3, s22
	s_addc_u32 s23, s34, s23
	s_and_b64 s[24:25], s[6:7], exec
	s_cselect_b32 s1, s23, s27
	s_cselect_b32 s2, s22, s26
	s_ashr_i32 s19, s18, 31
	s_lshl_b64 s[24:25], s[18:19], 19
	s_add_u32 s24, s35, s24
	s_addc_u32 s25, s36, s25
	s_and_b64 s[30:31], s[6:7], exec
	s_cselect_b32 s5, s25, s29
	s_cselect_b32 s19, s24, s28
	s_add_u32 s26, s26, 0x40080
	s_addc_u32 s27, s27, 0
	s_add_u32 s21, s28, 0x100
	s_addc_u32 s33, s29, 0
	s_mov_b32 s60, -2
	s_waitcnt lgkmcnt(0)
	ds_read_b128 v[168:171], v163
	ds_read_b128 v[176:179], v163 offset:1024
	ds_read_b128 v[184:187], v163 offset:2048
	ds_read_b128 v[188:191], v163 offset:3072
	ds_read_b128 v[192:195], v165
	ds_read_b128 v[196:199], v165 offset:1024
	ds_read_b128 v[200:203], v165 offset:2048
	ds_read_b128 v[204:207], v165 offset:3072
	s_add_u32 s28, s26, 0xfffc0080
	s_addc_u32 s29, s27, -1
	s_cmp_eq_u32 s60, 12
	s_cselect_b32 s31, s1, s29
	s_cselect_b32 s30, s2, s28
	s_cselect_b32 s29, s5, s33
	s_cselect_b32 s28, s19, s21
	v_lshl_add_u64 v[158:159], s[26:27], 0, v[146:147]
	s_add_i32 m0, s40, 0xc000
	ds_read_b128 v[208:211], v167
	ds_read_b128 v[212:215], v167 offset:1024
	ds_read_b128 v[216:219], v167 offset:2048
	ds_read_b128 v[220:223], v167 offset:3072
	ds_read_b128 v[224:227], v167 offset:4096
	ds_read_b128 v[228:231], v167 offset:5120
	ds_read_b128 v[232:235], v167 offset:6144
	ds_read_b128 v[236:239], v167 offset:7168
	global_load_lds_dwordx4 v[158:159], off
	v_lshl_add_u64 v[158:159], s[26:27], 0, v[148:149]
	s_add_i32 m0, s40, 0xe000
	s_nop 0
	global_load_lds_dwordx4 v[158:159], off
	s_waitcnt vmcnt(8)
	s_waitcnt lgkmcnt(0)
	s_barrier
	s_setprio 1
	s_waitcnt lgkmcnt(0)
	v_mfma_f32_16x16x32_bf16 v[126:129], v[168:171], v[208:211], 0
	v_mfma_f32_16x16x32_bf16 v[122:125], v[184:187], v[208:211], 0
	v_mfma_f32_16x16x32_bf16 v[110:113], v[168:171], v[216:219], 0
	v_mfma_f32_16x16x32_bf16 v[106:109], v[184:187], v[216:219], 0
	v_mfma_f32_16x16x32_bf16 v[94:97], v[168:171], v[224:227], 0
	v_mfma_f32_16x16x32_bf16 v[90:93], v[184:187], v[224:227], 0
	v_mfma_f32_16x16x32_bf16 v[78:81], v[168:171], v[232:235], 0
	v_mfma_f32_16x16x32_bf16 v[74:77], v[184:187], v[232:235], 0
	v_mfma_f32_16x16x32_bf16 v[126:129], v[176:179], v[212:215], v[126:129]
	v_mfma_f32_16x16x32_bf16 v[122:125], v[188:191], v[212:215], v[122:125]
	v_mfma_f32_16x16x32_bf16 v[110:113], v[176:179], v[220:223], v[110:113]
	v_mfma_f32_16x16x32_bf16 v[106:109], v[188:191], v[220:223], v[106:109]
	v_mfma_f32_16x16x32_bf16 v[94:97], v[176:179], v[228:231], v[94:97]
	v_mfma_f32_16x16x32_bf16 v[90:93], v[188:191], v[228:231], v[90:93]
	v_mfma_f32_16x16x32_bf16 v[78:81], v[176:179], v[236:239], v[78:81]
	v_mfma_f32_16x16x32_bf16 v[74:77], v[188:191], v[236:239], v[74:77]
	s_setprio 0
	s_setprio 1
	v_mfma_f32_16x16x32_bf16 v[118:121], v[192:195], v[208:211], 0
	v_mfma_f32_16x16x32_bf16 v[114:117], v[200:203], v[208:211], 0
	v_mfma_f32_16x16x32_bf16 v[102:105], v[192:195], v[216:219], 0
	v_mfma_f32_16x16x32_bf16 v[98:101], v[200:203], v[216:219], 0
	v_mfma_f32_16x16x32_bf16 v[86:89], v[192:195], v[224:227], 0
	v_mfma_f32_16x16x32_bf16 v[82:85], v[200:203], v[224:227], 0
	v_mfma_f32_16x16x32_bf16 v[70:73], v[192:195], v[232:235], 0
	v_mfma_f32_16x16x32_bf16 v[66:69], v[200:203], v[232:235], 0
	v_mfma_f32_16x16x32_bf16 v[118:121], v[196:199], v[212:215], v[118:121]
	v_mfma_f32_16x16x32_bf16 v[114:117], v[204:207], v[212:215], v[114:117]
	v_mfma_f32_16x16x32_bf16 v[102:105], v[196:199], v[220:223], v[102:105]
	v_mfma_f32_16x16x32_bf16 v[98:101], v[204:207], v[220:223], v[98:101]
	v_mfma_f32_16x16x32_bf16 v[86:89], v[196:199], v[228:231], v[86:89]
	v_mfma_f32_16x16x32_bf16 v[82:85], v[204:207], v[228:231], v[82:85]
	v_mfma_f32_16x16x32_bf16 v[70:73], v[196:199], v[236:239], v[70:73]
	v_mfma_f32_16x16x32_bf16 v[66:69], v[204:207], v[236:239], v[66:69]
	s_setprio 0
	s_barrier
	s_add_i32 s61, s53, s37
	v_lshl_add_u64 v[158:159], s[28:29], 0, v[134:135]
	s_mov_b32 m0, s61
	ds_read_b128 v[208:211], v167 offset:16384
	ds_read_b128 v[212:215], v167 offset:17408
	ds_read_b128 v[216:219], v167 offset:18432
	ds_read_b128 v[220:223], v167 offset:19456
	ds_read_b128 v[224:227], v167 offset:20480
	ds_read_b128 v[228:231], v167 offset:21504
	ds_read_b128 v[232:235], v167 offset:22528
	ds_read_b128 v[236:239], v167 offset:23552
	global_load_lds_dwordx4 v[158:159], off
	s_add_i32 m0, s61, 0x2000
	s_add_u32 s62, s28, 0x40000
	v_lshl_add_u64 v[180:181], s[28:29], 0, v[130:131]
	s_addc_u32 s63, s29, 0
	s_add_i32 s61, s54, s37
	global_load_lds_dwordx4 v[180:181], off
	v_lshl_add_u64 v[240:241], s[62:63], 0, v[134:135]
	s_mov_b32 m0, s61
	v_lshl_add_u64 v[242:243], s[30:31], 0, v[132:133]
	global_load_lds_dwordx4 v[240:241], off
	v_lshl_add_u64 v[240:241], s[62:63], 0, v[130:131]
	s_add_i32 m0, s61, 0x2000
	s_nop 0
	global_load_lds_dwordx4 v[240:241], off
	v_lshl_add_u64 v[240:241], s[30:31], 0, v[136:137]
	s_mov_b32 m0, s40
	s_nop 0
	global_load_lds_dwordx4 v[240:241], off
	s_mov_b32 m0, s41
	s_nop 0
	global_load_lds_dwordx4 v[242:243], off
	s_waitcnt vmcnt(8)
	s_waitcnt lgkmcnt(0)
	s_barrier
; #define PG8_STAGE(bufoff, gbase, voff) do { _Pragma("unroll") for (int _i = 0; _i < 2; ++_i) \
;         __builtin_amdgcn_global_load_lds((const unsigned*)((const char*)(gbase) + (voff)[_i]), (PG8_LAS unsigned*)(lds + (bufoff) + ldsw + _i * 8192), 16, 0, 0); } while (0)
; #define PG8_LDA(dst, b, h) do { _Pragma("unroll") for (int m = 0; m < 4; ++m) _Pragma("unroll") for (int k = 0; k < 2; ++k) dst[m][k] = *(const PG8_LAS bf16x8*)(lds + PG8_SA(b, h) + aoff + m * 2048 + k * 1024); } while (0)
; #define PG8_LDB(dst, b, h) do { _Pragma("unroll") for (int n = 0; n < 2; ++n) _Pragma("unroll") for (int k = 0; k < 2; ++k) dst[n][k] = *(const PG8_LAS bf16x8*)(lds + PG8_SB(b, h) + boff + n * 2048 + k * 1024); } while (0)
; #define PG8_MMA(ai, bj, At, Bt) do { __builtin_amdgcn_s_setprio(1); _Pragma("unroll") for (int m = 0; m < 4; ++m) _Pragma("unroll") for (int n = 0; n < 2; ++n) _Pragma("unroll") for (int k = 0; k < 2; ++k) \
;         acc[ai][bj][m][n] = __builtin_amdgcn_mfma_f32_16x16x32_bf16(Bt[n][k], At[m][k], acc[ai][bj][m][n], 0, 0, 0); __builtin_amdgcn_s_setprio(0); } while (0)
; #define PG8_WAIT_V(n) asm volatile("s_waitcnt vmcnt(" #n ")" ::: "memory")
; #define PG8_WAIT_L(n) asm volatile("s_waitcnt lgkmcnt(" #n ")" ::: "memory")
; #define PG8_BAR __builtin_amdgcn_s_barrier()
; #define PG8_SCHED __builtin_amdgcn_sched_barrier(0)
; template <class Epi, class Sched, bool ALIGN_EPI = false, bool SP2 = false>
; __device__ __forceinline__ void gemm_phase(PG8_LAS unsigned char* lds, const Gemm g, const Sched& S, const Epi& E) {
;     ...
;             PG8_WAIT_V(8); PG8_WAIT_L(0); PG8_BAR; PG8_MMA(1, 0, At, B0); PG8_MMA(1, 1, At, B1); PG8_BAR; PG8_SCHED;
;             PG8_LDB(B0, 1, 0); PG8_LDB(B1, 1, 1); PG8_SCHED; PG8_LDA(At, 1, 0); PG8_STAGE(PG8_SA(0, 1), a2 + hstepA, voffA);
;             PG8_WAIT_V(8); PG8_WAIT_L(0); PG8_BAR; PG8_MMA(0, 0, At, B0); PG8_MMA(0, 1, At, B1); PG8_BAR; PG8_SCHED;
	s_setprio 1
	s_waitcnt lgkmcnt(0)
	v_mfma_f32_16x16x32_bf16 v[62:65], v[168:171], v[208:211], 0
	v_mfma_f32_16x16x32_bf16 v[58:61], v[184:187], v[208:211], 0
	v_mfma_f32_16x16x32_bf16 v[46:49], v[168:171], v[216:219], 0
	v_mfma_f32_16x16x32_bf16 v[42:45], v[184:187], v[216:219], 0
	v_mfma_f32_16x16x32_bf16 v[30:33], v[168:171], v[224:227], 0
	v_mfma_f32_16x16x32_bf16 v[26:29], v[184:187], v[224:227], 0
	v_mfma_f32_16x16x32_bf16 v[14:17], v[168:171], v[232:235], 0
	v_mfma_f32_16x16x32_bf16 v[10:13], v[184:187], v[232:235], 0
	v_mfma_f32_16x16x32_bf16 v[62:65], v[176:179], v[212:215], v[62:65]
	v_mfma_f32_16x16x32_bf16 v[58:61], v[188:191], v[212:215], v[58:61]
	v_mfma_f32_16x16x32_bf16 v[46:49], v[176:179], v[220:223], v[46:49]
	v_mfma_f32_16x16x32_bf16 v[42:45], v[188:191], v[220:223], v[42:45]
	v_mfma_f32_16x16x32_bf16 v[30:33], v[176:179], v[228:231], v[30:33]
	v_mfma_f32_16x16x32_bf16 v[26:29], v[188:191], v[228:231], v[26:29]
	v_mfma_f32_16x16x32_bf16 v[14:17], v[176:179], v[236:239], v[14:17]
	v_mfma_f32_16x16x32_bf16 v[10:13], v[188:191], v[236:239], v[10:13]
	s_setprio 0
	s_setprio 1
	v_mfma_f32_16x16x32_bf16 v[54:57], v[192:195], v[208:211], 0
	v_mfma_f32_16x16x32_bf16 v[50:53], v[200:203], v[208:211], 0
	v_mfma_f32_16x16x32_bf16 v[38:41], v[192:195], v[216:219], 0
	v_mfma_f32_16x16x32_bf16 v[34:37], v[200:203], v[216:219], 0
	v_mfma_f32_16x16x32_bf16 v[22:25], v[192:195], v[224:227], 0
	v_mfma_f32_16x16x32_bf16 v[18:21], v[200:203], v[224:227], 0
	v_mfma_f32_16x16x32_bf16 v[6:9], v[192:195], v[232:235], 0
	v_mfma_f32_16x16x32_bf16 v[2:5], v[200:203], v[232:235], 0
	v_mfma_f32_16x16x32_bf16 v[54:57], v[196:199], v[212:215], v[54:57]
	v_mfma_f32_16x16x32_bf16 v[50:53], v[204:207], v[212:215], v[50:53]
	v_mfma_f32_16x16x32_bf16 v[38:41], v[196:199], v[220:223], v[38:41]
	v_mfma_f32_16x16x32_bf16 v[34:37], v[204:207], v[220:223], v[34:37]
	v_mfma_f32_16x16x32_bf16 v[22:25], v[196:199], v[228:231], v[22:25]
	v_mfma_f32_16x16x32_bf16 v[18:21], v[204:207], v[228:231], v[18:21]
	v_mfma_f32_16x16x32_bf16 v[6:9], v[196:199], v[236:239], v[6:9]
	v_mfma_f32_16x16x32_bf16 v[2:5], v[204:207], v[236:239], v[2:5]
	s_setprio 0
	s_barrier
	s_add_i32 s61, 0, 0x18000
	v_add_u32_e32 v138, s61, v141
	s_add_i32 s62, 0, 0x1c000
	ds_read_b128 v[168:171], v138
	ds_read_b128 v[176:179], v138 offset:1024
	ds_read_b128 v[184:187], v138 offset:2048
	ds_read_b128 v[188:191], v138 offset:3072
	v_add_u32_e32 v138, s62, v141
	ds_read_b128 v[192:195], v138
	ds_read_b128 v[196:199], v138 offset:1024
	ds_read_b128 v[200:203], v138 offset:2048
	ds_read_b128 v[204:207], v138 offset:3072
	s_add_u32 s30, s30, 0x40000
	s_addc_u32 s31, s31, 0
	s_mov_b32 m0, s42
	v_lshl_add_u64 v[244:245], s[30:31], 0, v[136:137]
	ds_read_b128 v[208:211], v167 offset:32768
	ds_read_b128 v[212:215], v167 offset:33792
	ds_read_b128 v[216:219], v167 offset:34816
	ds_read_b128 v[220:223], v167 offset:35840
	ds_read_b128 v[224:227], v167 offset:36864
	ds_read_b128 v[228:231], v167 offset:37888
	ds_read_b128 v[232:235], v167 offset:38912
	ds_read_b128 v[236:239], v167 offset:39936
	global_load_lds_dwordx4 v[244:245], off
	v_lshl_add_u64 v[244:245], s[30:31], 0, v[132:133]
	s_mov_b32 m0, s43
	s_nop 0
	global_load_lds_dwordx4 v[244:245], off
	s_waitcnt vmcnt(8)
	s_waitcnt lgkmcnt(0)
	s_barrier
	s_setprio 1
	s_waitcnt lgkmcnt(0)
	v_mfma_f32_16x16x32_bf16 v[126:129], v[168:171], v[208:211], v[126:129]
	v_mfma_f32_16x16x32_bf16 v[122:125], v[184:187], v[208:211], v[122:125]
	v_mfma_f32_16x16x32_bf16 v[110:113], v[168:171], v[216:219], v[110:113]
	v_mfma_f32_16x16x32_bf16 v[106:109], v[184:187], v[216:219], v[106:109]
	v_mfma_f32_16x16x32_bf16 v[94:97], v[168:171], v[224:227], v[94:97]
	v_mfma_f32_16x16x32_bf16 v[90:93], v[184:187], v[224:227], v[90:93]
	v_mfma_f32_16x16x32_bf16 v[78:81], v[168:171], v[232:235], v[78:81]
	v_mfma_f32_16x16x32_bf16 v[74:77], v[184:187], v[232:235], v[74:77]
	v_mfma_f32_16x16x32_bf16 v[126:129], v[176:179], v[212:215], v[126:129]
	v_mfma_f32_16x16x32_bf16 v[122:125], v[188:191], v[212:215], v[122:125]
	v_mfma_f32_16x16x32_bf16 v[110:113], v[176:179], v[220:223], v[110:113]
	v_mfma_f32_16x16x32_bf16 v[106:109], v[188:191], v[220:223], v[106:109]
	v_mfma_f32_16x16x32_bf16 v[94:97], v[176:179], v[228:231], v[94:97]
	v_mfma_f32_16x16x32_bf16 v[90:93], v[188:191], v[228:231], v[90:93]
	v_mfma_f32_16x16x32_bf16 v[78:81], v[176:179], v[236:239], v[78:81]
	v_mfma_f32_16x16x32_bf16 v[74:77], v[188:191], v[236:239], v[74:77]
	s_setprio 0
	s_setprio 1
	v_mfma_f32_16x16x32_bf16 v[118:121], v[192:195], v[208:211], v[118:121]
	v_mfma_f32_16x16x32_bf16 v[114:117], v[200:203], v[208:211], v[114:117]
	v_mfma_f32_16x16x32_bf16 v[102:105], v[192:195], v[216:219], v[102:105]
	v_mfma_f32_16x16x32_bf16 v[98:101], v[200:203], v[216:219], v[98:101]
	v_mfma_f32_16x16x32_bf16 v[86:89], v[192:195], v[224:227], v[86:89]
	v_mfma_f32_16x16x32_bf16 v[82:85], v[200:203], v[224:227], v[82:85]
	v_mfma_f32_16x16x32_bf16 v[70:73], v[192:195], v[232:235], v[70:73]
	v_mfma_f32_16x16x32_bf16 v[66:69], v[200:203], v[232:235], v[66:69]
	v_mfma_f32_16x16x32_bf16 v[118:121], v[196:199], v[212:215], v[118:121]
	v_mfma_f32_16x16x32_bf16 v[114:117], v[204:207], v[212:215], v[114:117]
	v_mfma_f32_16x16x32_bf16 v[102:105], v[196:199], v[220:223], v[102:105]
	v_mfma_f32_16x16x32_bf16 v[98:101], v[204:207], v[220:223], v[98:101]
	v_mfma_f32_16x16x32_bf16 v[86:89], v[196:199], v[228:231], v[86:89]
	v_mfma_f32_16x16x32_bf16 v[82:85], v[204:207], v[228:231], v[82:85]
	v_mfma_f32_16x16x32_bf16 v[70:73], v[196:199], v[236:239], v[70:73]
	v_mfma_f32_16x16x32_bf16 v[66:69], v[204:207], v[236:239], v[66:69]
	s_setprio 0
	s_barrier
; #define PG8_STAGE(bufoff, gbase, voff) do { _Pragma("unroll") for (int _i = 0; _i < 2; ++_i) \
;         __builtin_amdgcn_global_load_lds((const unsigned*)((const char*)(gbase) + (voff)[_i]), (PG8_LAS unsigned*)(lds + (bufoff) + ldsw + _i * 8192), 16, 0, 0); } while (0)
; #define PG8_LDA(dst, b, h) do { _Pragma("unroll") for (int m = 0; m < 4; ++m) _Pragma("unroll") for (int k = 0; k < 2; ++k) dst[m][k] = *(const PG8_LAS bf16x8*)(lds + PG8_SA(b, h) + aoff + m * 2048 + k * 1024); } while (0)
; #define PG8_MMA(ai, bj, At, Bt) do { __builtin_amdgcn_s_setprio(1); _Pragma("unroll") for (int m = 0; m < 4; ++m) _Pragma("unroll") for (int n = 0; n < 2; ++n) _Pragma("unroll") for (int k = 0; k < 2; ++k) \
;         acc[ai][bj][m][n] = __builtin_amdgcn_mfma_f32_16x16x32_bf16(Bt[n][k], At[m][k], acc[ai][bj][m][n], 0, 0, 0); __builtin_amdgcn_s_setprio(0); } while (0)
; #define PG8_WAIT_V(n) asm volatile("s_waitcnt vmcnt(" #n ")" ::: "memory")
; #define PG8_WAIT_L(n) asm volatile("s_waitcnt lgkmcnt(" #n ")" ::: "memory")
; #define PG8_BAR __builtin_amdgcn_s_barrier()
; #define PG8_SCHED __builtin_amdgcn_sched_barrier(0)
; template <class Epi, class Sched, bool ALIGN_EPI = false, bool SP2 = false>
; __device__ __forceinline__ void gemm_phase(PG8_LAS unsigned char* lds, const Gemm g, const Sched& S, const Epi& E) {
;     ...
;         for (int t = 0; t < nt; t += 2) {
;     ...
;             PG8_LDA(At, 1, 1); PG8_STAGE(PG8_SB(1, 0), b3, voffB); PG8_STAGE(PG8_SB(1, 1), b3 + hstepB, voffB); PG8_STAGE(PG8_SA(1, 0), a3, voffA);
;             PG8_WAIT_V(8); PG8_WAIT_L(0); PG8_BAR; PG8_MMA(1, 0, At, B0); PG8_MMA(1, 1, At, B1); PG8_BAR; PG8_SCHED;
	s_add_i32 s30, s61, s37
	v_lshl_add_u64 v[158:159], v[158:159], 0, s[14:15]
	s_mov_b32 m0, s30
	ds_read_b128 v[208:211], v167 offset:49152
	ds_read_b128 v[212:215], v167 offset:50176
	ds_read_b128 v[216:219], v167 offset:51200
	ds_read_b128 v[220:223], v167 offset:52224
	ds_read_b128 v[224:227], v167 offset:53248
	ds_read_b128 v[228:231], v167 offset:54272
	ds_read_b128 v[232:235], v167 offset:55296
	ds_read_b128 v[236:239], v167 offset:56320
	global_load_lds_dwordx4 v[158:159], off
	s_add_i32 m0, s30, 0x2000
	s_add_u32 s28, s28, 0x40080
	v_lshl_add_u64 v[158:159], v[180:181], 0, s[14:15]
	s_addc_u32 s29, s29, 0
	s_add_i32 s30, s62, s37
	global_load_lds_dwordx4 v[158:159], off
	v_lshl_add_u64 v[158:159], s[28:29], 0, v[134:135]
	s_mov_b32 m0, s30
	s_nop 0
	global_load_lds_dwordx4 v[158:159], off
	v_lshl_add_u64 v[158:159], s[28:29], 0, v[130:131]
	s_add_i32 m0, s30, 0x2000
	s_nop 0
	global_load_lds_dwordx4 v[158:159], off
	v_lshl_add_u64 v[158:159], v[240:241], 0, s[14:15]
	s_mov_b32 m0, s49
	s_nop 0
	global_load_lds_dwordx4 v[158:159], off
	v_lshl_add_u64 v[158:159], v[242:243], 0, s[14:15]
	s_mov_b32 m0, s50
	s_nop 0
	global_load_lds_dwordx4 v[158:159], off
	s_waitcnt vmcnt(8)
	s_waitcnt lgkmcnt(0)
	s_barrier
	s_setprio 1
	s_waitcnt lgkmcnt(0)
	v_mfma_f32_16x16x32_bf16 v[62:65], v[168:171], v[208:211], v[62:65]
	v_mfma_f32_16x16x32_bf16 v[58:61], v[184:187], v[208:211], v[58:61]
	v_mfma_f32_16x16x32_bf16 v[46:49], v[168:171], v[216:219], v[46:49]
	v_mfma_f32_16x16x32_bf16 v[42:45], v[184:187], v[216:219], v[42:45]
	v_mfma_f32_16x16x32_bf16 v[30:33], v[168:171], v[224:227], v[30:33]
	v_mfma_f32_16x16x32_bf16 v[26:29], v[184:187], v[224:227], v[26:29]
	v_mfma_f32_16x16x32_bf16 v[14:17], v[168:171], v[232:235], v[14:17]
	v_mfma_f32_16x16x32_bf16 v[10:13], v[184:187], v[232:235], v[10:13]
	v_mfma_f32_16x16x32_bf16 v[62:65], v[176:179], v[212:215], v[62:65]
	v_mfma_f32_16x16x32_bf16 v[58:61], v[188:191], v[212:215], v[58:61]
	v_mfma_f32_16x16x32_bf16 v[46:49], v[176:179], v[220:223], v[46:49]
	v_mfma_f32_16x16x32_bf16 v[42:45], v[188:191], v[220:223], v[42:45]
	v_mfma_f32_16x16x32_bf16 v[30:33], v[176:179], v[228:231], v[30:33]
	v_mfma_f32_16x16x32_bf16 v[26:29], v[188:191], v[228:231], v[26:29]
	v_mfma_f32_16x16x32_bf16 v[14:17], v[176:179], v[236:239], v[14:17]
	v_mfma_f32_16x16x32_bf16 v[10:13], v[188:191], v[236:239], v[10:13]
	s_setprio 0
	s_setprio 1
	v_mfma_f32_16x16x32_bf16 v[54:57], v[192:195], v[208:211], v[54:57]
	v_mfma_f32_16x16x32_bf16 v[50:53], v[200:203], v[208:211], v[50:53]
	v_mfma_f32_16x16x32_bf16 v[38:41], v[192:195], v[216:219], v[38:41]
	v_mfma_f32_16x16x32_bf16 v[34:37], v[200:203], v[216:219], v[34:37]
	v_mfma_f32_16x16x32_bf16 v[22:25], v[192:195], v[224:227], v[22:25]
	v_mfma_f32_16x16x32_bf16 v[18:21], v[200:203], v[224:227], v[18:21]
	v_mfma_f32_16x16x32_bf16 v[6:9], v[192:195], v[232:235], v[6:9]
	v_mfma_f32_16x16x32_bf16 v[2:5], v[200:203], v[232:235], v[2:5]
	v_mfma_f32_16x16x32_bf16 v[54:57], v[196:199], v[212:215], v[54:57]
	v_mfma_f32_16x16x32_bf16 v[50:53], v[204:207], v[212:215], v[50:53]
	v_mfma_f32_16x16x32_bf16 v[38:41], v[196:199], v[220:223], v[38:41]
	v_mfma_f32_16x16x32_bf16 v[34:37], v[204:207], v[220:223], v[34:37]
	v_mfma_f32_16x16x32_bf16 v[22:25], v[196:199], v[228:231], v[22:25]
	v_mfma_f32_16x16x32_bf16 v[18:21], v[204:207], v[228:231], v[18:21]
	v_mfma_f32_16x16x32_bf16 v[6:9], v[196:199], v[236:239], v[6:9]
	v_mfma_f32_16x16x32_bf16 v[2:5], v[204:207], v[236:239], v[2:5]
	s_setprio 0
	s_barrier
	s_add_i32 s60, s60, 2
	s_add_u32 s26, s26, 0x100
	s_addc_u32 s27, s27, 0
	s_add_u32 s21, s21, 0x100
	s_addc_u32 s33, s33, 0
	s_cmp_gt_u32 s60, 13

; #define PG8_STAGE(bufoff, gbase, voff) do { _Pragma("unroll") for (int _i = 0; _i < 2; ++_i) \
;         __builtin_amdgcn_global_load_lds((const unsigned*)((const char*)(gbase) + (voff)[_i]), (PG8_LAS unsigned*)(lds + (bufoff) + ldsw + _i * 8192), 16, 0, 0); } while (0)
; #define PG8_LDA(dst, b, h) do { _Pragma("unroll") for (int m = 0; m < 4; ++m) _Pragma("unroll") for (int k = 0; k < 2; ++k) dst[m][k] = *(const PG8_LAS bf16x8*)(lds + PG8_SA(b, h) + aoff + m * 2048 + k * 1024); } while (0)
; #define PG8_LDB(dst, b, h) do { _Pragma("unroll") for (int n = 0; n < 2; ++n) _Pragma("unroll") for (int k = 0; k < 2; ++k) dst[n][k] = *(const PG8_LAS bf16x8*)(lds + PG8_SB(b, h) + boff + n * 2048 + k * 1024); } while (0)
; #define PG8_MMA(ai, bj, At, Bt) do { __builtin_amdgcn_s_setprio(1); _Pragma("unroll") for (int m = 0; m < 4; ++m) _Pragma("unroll") for (int n = 0; n < 2; ++n) _Pragma("unroll") for (int k = 0; k < 2; ++k) \
;         acc[ai][bj][m][n] = __builtin_amdgcn_mfma_f32_16x16x32_bf16(Bt[n][k], At[m][k], acc[ai][bj][m][n], 0, 0, 0); __builtin_amdgcn_s_setprio(0); } while (0)
; #define PG8_WAIT_V(n) asm volatile("s_waitcnt vmcnt(" #n ")" ::: "memory")
; #define PG8_BAR __builtin_amdgcn_s_barrier()
; template <class Epi, class Sched, bool ALIGN_EPI = false, bool SP2 = false>
; __device__ __forceinline__ void gemm_phase(PG8_LAS unsigned char* lds, const Gemm g, const Sched& S, const Epi& E) {
;     ...
;         for (int t = 0; t < nt; t += 2) {
;             const bool last = (t == nt - 2);
;             const char* a1 = cA + (size_t)(t + 1) * kstep;
;             const char* a2 = last ? nA : cA + (size_t)(t + 2) * kstep; const char* b2 = last ? nB : cB + (size_t)(t + 2) * kstep;
;             const char* a3 = a2 + kstep; const char* b3 = b2 + kstep;
;             if (last && has_next) S.a_ready(nxt);
;             if constexpr (SP2) {
;             PG8_LDB(B0, 0, 0); PG8_LDB(B1, 0, 1); PG8_SCHED; PG8_LDA(At, 0, 0); PG8_STAGE(PG8_SA(1, 1), a1 + hstepA, voffA);
;             PG8_WAIT_V(8); PG8_WAIT_L(0); PG8_BAR; PG8_MMA(0, 0, At, B0); PG8_MMA(0, 1, At, B1); PG8_BAR; PG8_SCHED;
;             PG8_LDA(At, 0, 1); PG8_STAGE(PG8_SB(0, 0), b2, voffB); PG8_STAGE(PG8_SB(0, 1), b2 + hstepB, voffB); PG8_STAGE(PG8_SA(0, 0), a2, voffA);
;             PG8_WAIT_V(8); PG8_WAIT_L(0); PG8_BAR; PG8_MMA(1, 0, At, B0); PG8_MMA(1, 1, At, B1); PG8_BAR; PG8_SCHED;
.LBB0_429:
	s_add_u32 s2, s42, 0x100
	s_addc_u32 s5, s43, 0
	s_mov_b32 s33, -2
	ds_read_b128 v[62:65], v168
	ds_read_b128 v[66:69], v168 offset:1024
	ds_read_b128 v[138:141], v168 offset:2048
	ds_read_b128 v[142:145], v168 offset:3072
	ds_read_b128 v[162:165], v169
	ds_read_b128 v[172:175], v169 offset:1024
	ds_read_b128 v[176:179], v169 offset:2048
	ds_read_b128 v[180:183], v169 offset:3072
	s_add_u32 s42, s40, 0x100
	s_addc_u32 s43, s41, 0
	s_cmp_eq_u32 s33, 6
	s_cselect_b32 s47, s37, s43
	s_cselect_b32 s46, s36, s42
	s_cselect_b32 s45, s39, s5
	s_cselect_b32 s44, s38, s2
	v_lshl_add_u64 v[216:217], s[40:41], 0, v[158:159]
	s_add_i32 m0, s51, 0xc000
	ds_read_b128 v[184:187], v170
	ds_read_b128 v[188:191], v170 offset:1024
	ds_read_b128 v[192:195], v170 offset:2048
	ds_read_b128 v[196:199], v170 offset:3072
	ds_read_b128 v[200:203], v170 offset:4096
	ds_read_b128 v[204:207], v170 offset:5120
	ds_read_b128 v[208:211], v170 offset:6144
	ds_read_b128 v[212:215], v170 offset:7168
	global_load_lds_dwordx4 v[216:217], off
	v_lshl_add_u64 v[216:217], s[40:41], 0, v[160:161]
	s_add_i32 m0, s51, 0xe000
	s_nop 0
	global_load_lds_dwordx4 v[216:217], off
	s_waitcnt vmcnt(8)
	s_waitcnt lgkmcnt(0)
	s_barrier
	s_setprio 1
	s_waitcnt lgkmcnt(0)
	v_mfma_f32_16x16x32_bf16 v[134:137], v[62:65], v[184:187], 0
	v_mfma_f32_16x16x32_bf16 v[130:133], v[138:141], v[184:187], 0
	v_mfma_f32_16x16x32_bf16 v[118:121], v[62:65], v[192:195], 0
	v_mfma_f32_16x16x32_bf16 v[114:117], v[138:141], v[192:195], 0
	v_mfma_f32_16x16x32_bf16 v[102:105], v[62:65], v[200:203], 0
	v_mfma_f32_16x16x32_bf16 v[98:101], v[138:141], v[200:203], 0
	v_mfma_f32_16x16x32_bf16 v[86:89], v[62:65], v[208:211], 0
	v_mfma_f32_16x16x32_bf16 v[82:85], v[138:141], v[208:211], 0
	v_mfma_f32_16x16x32_bf16 v[134:137], v[66:69], v[188:191], v[134:137]
	v_mfma_f32_16x16x32_bf16 v[130:133], v[142:145], v[188:191], v[130:133]
	v_mfma_f32_16x16x32_bf16 v[118:121], v[66:69], v[196:199], v[118:121]
	v_mfma_f32_16x16x32_bf16 v[114:117], v[142:145], v[196:199], v[114:117]
	v_mfma_f32_16x16x32_bf16 v[102:105], v[66:69], v[204:207], v[102:105]
	v_mfma_f32_16x16x32_bf16 v[98:101], v[142:145], v[204:207], v[98:101]
	v_mfma_f32_16x16x32_bf16 v[86:89], v[66:69], v[212:215], v[86:89]
	v_mfma_f32_16x16x32_bf16 v[82:85], v[142:145], v[212:215], v[82:85]
	s_setprio 0
	s_setprio 1
	v_mfma_f32_16x16x32_bf16 v[126:129], v[162:165], v[184:187], 0
	v_mfma_f32_16x16x32_bf16 v[122:125], v[176:179], v[184:187], 0
	v_mfma_f32_16x16x32_bf16 v[110:113], v[162:165], v[192:195], 0
	v_mfma_f32_16x16x32_bf16 v[106:109], v[176:179], v[192:195], 0
	v_mfma_f32_16x16x32_bf16 v[94:97], v[162:165], v[200:203], 0
	v_mfma_f32_16x16x32_bf16 v[90:93], v[176:179], v[200:203], 0
	v_mfma_f32_16x16x32_bf16 v[78:81], v[162:165], v[208:211], 0
	v_mfma_f32_16x16x32_bf16 v[74:77], v[176:179], v[208:211], 0
	v_mfma_f32_16x16x32_bf16 v[126:129], v[172:175], v[188:191], v[126:129]
	v_mfma_f32_16x16x32_bf16 v[122:125], v[180:183], v[188:191], v[122:125]
	v_mfma_f32_16x16x32_bf16 v[110:113], v[172:175], v[196:199], v[110:113]
	v_mfma_f32_16x16x32_bf16 v[106:109], v[180:183], v[196:199], v[106:109]
	v_mfma_f32_16x16x32_bf16 v[94:97], v[172:175], v[204:207], v[94:97]
	v_mfma_f32_16x16x32_bf16 v[90:93], v[180:183], v[204:207], v[90:93]
	v_mfma_f32_16x16x32_bf16 v[78:81], v[172:175], v[212:215], v[78:81]
	v_mfma_f32_16x16x32_bf16 v[74:77], v[180:183], v[212:215], v[74:77]
	s_setprio 0
	s_barrier
	s_add_i32 s40, s59, s48
	v_lshl_add_u64 v[216:217], s[44:45], 0, v[150:151]
	s_mov_b32 m0, s40
	ds_read_b128 v[184:187], v170 offset:16384
	ds_read_b128 v[188:191], v170 offset:17408
	ds_read_b128 v[192:195], v170 offset:18432
	ds_read_b128 v[196:199], v170 offset:19456
	ds_read_b128 v[200:203], v170 offset:20480
	ds_read_b128 v[204:207], v170 offset:21504
	ds_read_b128 v[208:211], v170 offset:22528
	ds_read_b128 v[212:215], v170 offset:23552
	global_load_lds_dwordx4 v[216:217], off
	s_add_i32 m0, s40, 0x2000
	s_add_u32 s40, s44, 0x28000
	v_lshl_add_u64 v[218:219], s[44:45], 0, v[146:147]
	s_addc_u32 s41, s45, 0
	s_add_i32 s71, s60, s48
	global_load_lds_dwordx4 v[218:219], off
	v_lshl_add_u64 v[220:221], s[40:41], 0, v[150:151]
	s_mov_b32 m0, s71
	v_lshl_add_u64 v[222:223], s[46:47], 0, v[148:149]
	global_load_lds_dwordx4 v[220:221], off
	v_lshl_add_u64 v[220:221], s[40:41], 0, v[146:147]
	s_add_i32 m0, s71, 0x2000
	s_nop 0
	global_load_lds_dwordx4 v[220:221], off
	v_lshl_add_u64 v[220:221], s[46:47], 0, v[152:153]
	s_mov_b32 m0, s51
	s_nop 0
	global_load_lds_dwordx4 v[220:221], off
	s_mov_b32 m0, s52
	s_nop 0
	global_load_lds_dwordx4 v[222:223], off
	s_waitcnt vmcnt(8)
	s_waitcnt lgkmcnt(0)
	s_barrier
; #define PG8_STAGE(bufoff, gbase, voff) do { _Pragma("unroll") for (int _i = 0; _i < 2; ++_i) \
;         __builtin_amdgcn_global_load_lds((const unsigned*)((const char*)(gbase) + (voff)[_i]), (PG8_LAS unsigned*)(lds + (bufoff) + ldsw + _i * 8192), 16, 0, 0); } while (0)
; #define PG8_LDA(dst, b, h) do { _Pragma("unroll") for (int m = 0; m < 4; ++m) _Pragma("unroll") for (int k = 0; k < 2; ++k) dst[m][k] = *(const PG8_LAS bf16x8*)(lds + PG8_SA(b, h) + aoff + m * 2048 + k * 1024); } while (0)
; #define PG8_LDB(dst, b, h) do { _Pragma("unroll") for (int n = 0; n < 2; ++n) _Pragma("unroll") for (int k = 0; k < 2; ++k) dst[n][k] = *(const PG8_LAS bf16x8*)(lds + PG8_SB(b, h) + boff + n * 2048 + k * 1024); } while (0)
; #define PG8_MMA(ai, bj, At, Bt) do { __builtin_amdgcn_s_setprio(1); _Pragma("unroll") for (int m = 0; m < 4; ++m) _Pragma("unroll") for (int n = 0; n < 2; ++n) _Pragma("unroll") for (int k = 0; k < 2; ++k) \
;         acc[ai][bj][m][n] = __builtin_amdgcn_mfma_f32_16x16x32_bf16(Bt[n][k], At[m][k], acc[ai][bj][m][n], 0, 0, 0); __builtin_amdgcn_s_setprio(0); } while (0)
; #define PG8_WAIT_V(n) asm volatile("s_waitcnt vmcnt(" #n ")" ::: "memory")
; #define PG8_WAIT_L(n) asm volatile("s_waitcnt lgkmcnt(" #n ")" ::: "memory")
; #define PG8_BAR __builtin_amdgcn_s_barrier()
; #define PG8_SCHED __builtin_amdgcn_sched_barrier(0)
; template <class Epi, class Sched, bool ALIGN_EPI = false, bool SP2 = false>
; __device__ __forceinline__ void gemm_phase(PG8_LAS unsigned char* lds, const Gemm g, const Sched& S, const Epi& E) {
;     ...
;             PG8_WAIT_V(8); PG8_WAIT_L(0); PG8_BAR; PG8_MMA(1, 0, At, B0); PG8_MMA(1, 1, At, B1); PG8_BAR; PG8_SCHED;
;             PG8_LDB(B0, 1, 0); PG8_LDB(B1, 1, 1); PG8_SCHED; PG8_LDA(At, 1, 0); PG8_STAGE(PG8_SA(0, 1), a2 + hstepA, voffA);
;             PG8_WAIT_V(8); PG8_WAIT_L(0); PG8_BAR; PG8_MMA(0, 0, At, B0); PG8_MMA(0, 1, At, B1); PG8_BAR; PG8_SCHED;
	s_setprio 1
	s_waitcnt lgkmcnt(0)
	v_mfma_f32_16x16x32_bf16 v[70:73], v[62:65], v[184:187], 0
	v_mfma_f32_16x16x32_bf16 v[58:61], v[138:141], v[184:187], 0
	v_mfma_f32_16x16x32_bf16 v[46:49], v[62:65], v[192:195], 0
	v_mfma_f32_16x16x32_bf16 v[42:45], v[138:141], v[192:195], 0
	v_mfma_f32_16x16x32_bf16 v[30:33], v[62:65], v[200:203], 0
	v_mfma_f32_16x16x32_bf16 v[26:29], v[138:141], v[200:203], 0
	v_mfma_f32_16x16x32_bf16 v[14:17], v[62:65], v[208:211], 0
	v_mfma_f32_16x16x32_bf16 v[10:13], v[138:141], v[208:211], 0
	v_mfma_f32_16x16x32_bf16 v[70:73], v[66:69], v[188:191], v[70:73]
	v_mfma_f32_16x16x32_bf16 v[58:61], v[142:145], v[188:191], v[58:61]
	v_mfma_f32_16x16x32_bf16 v[46:49], v[66:69], v[196:199], v[46:49]
	v_mfma_f32_16x16x32_bf16 v[42:45], v[142:145], v[196:199], v[42:45]
	v_mfma_f32_16x16x32_bf16 v[30:33], v[66:69], v[204:207], v[30:33]
	v_mfma_f32_16x16x32_bf16 v[26:29], v[142:145], v[204:207], v[26:29]
	v_mfma_f32_16x16x32_bf16 v[14:17], v[66:69], v[212:215], v[14:17]
	v_mfma_f32_16x16x32_bf16 v[10:13], v[142:145], v[212:215], v[10:13]
	s_setprio 0
	s_setprio 1
	v_mfma_f32_16x16x32_bf16 v[54:57], v[162:165], v[184:187], 0
	v_mfma_f32_16x16x32_bf16 v[50:53], v[176:179], v[184:187], 0
	v_mfma_f32_16x16x32_bf16 v[38:41], v[162:165], v[192:195], 0
	v_mfma_f32_16x16x32_bf16 v[34:37], v[176:179], v[192:195], 0
	v_mfma_f32_16x16x32_bf16 v[22:25], v[162:165], v[200:203], 0
	v_mfma_f32_16x16x32_bf16 v[18:21], v[176:179], v[200:203], 0
	v_mfma_f32_16x16x32_bf16 v[6:9], v[162:165], v[208:211], 0
	v_mfma_f32_16x16x32_bf16 v[2:5], v[176:179], v[208:211], 0
	v_mfma_f32_16x16x32_bf16 v[54:57], v[172:175], v[188:191], v[54:57]
	v_mfma_f32_16x16x32_bf16 v[50:53], v[180:183], v[188:191], v[50:53]
	v_mfma_f32_16x16x32_bf16 v[38:41], v[172:175], v[196:199], v[38:41]
	v_mfma_f32_16x16x32_bf16 v[34:37], v[180:183], v[196:199], v[34:37]
	v_mfma_f32_16x16x32_bf16 v[22:25], v[172:175], v[204:207], v[22:25]
	v_mfma_f32_16x16x32_bf16 v[18:21], v[180:183], v[204:207], v[18:21]
	v_mfma_f32_16x16x32_bf16 v[6:9], v[172:175], v[212:215], v[6:9]
	v_mfma_f32_16x16x32_bf16 v[2:5], v[180:183], v[212:215], v[2:5]
	s_setprio 0
	s_barrier
	s_add_i32 s71, 0, 0x18000
	s_add_i32 s72, 0, 0x1c000
	v_add_u32_e32 v142, s71, v166
	v_add_u32_e32 v180, s72, v166
	ds_read_b128 v[62:65], v142
	ds_read_b128 v[66:69], v142 offset:1024
	ds_read_b128 v[138:141], v142 offset:2048
	ds_read_b128 v[142:145], v142 offset:3072
	ds_read_b128 v[162:165], v180
	ds_read_b128 v[172:175], v180 offset:1024
	ds_read_b128 v[176:179], v180 offset:2048
	ds_read_b128 v[180:183], v180 offset:3072
	s_add_u32 s40, s46, 0x28000
	s_addc_u32 s41, s47, 0
	s_mov_b32 m0, s53
	v_lshl_add_u64 v[224:225], s[40:41], 0, v[152:153]
	ds_read_b128 v[184:187], v170 offset:32768
	ds_read_b128 v[188:191], v170 offset:33792
	ds_read_b128 v[192:195], v170 offset:34816
	ds_read_b128 v[196:199], v170 offset:35840
	ds_read_b128 v[200:203], v170 offset:36864
	ds_read_b128 v[204:207], v170 offset:37888
	ds_read_b128 v[208:211], v170 offset:38912
	ds_read_b128 v[212:215], v170 offset:39936
	global_load_lds_dwordx4 v[224:225], off
	v_lshl_add_u64 v[224:225], s[40:41], 0, v[148:149]
	s_mov_b32 m0, s54
	s_nop 0
	global_load_lds_dwordx4 v[224:225], off
	s_waitcnt vmcnt(8)
	s_waitcnt lgkmcnt(0)
	s_barrier
	s_setprio 1
	s_waitcnt lgkmcnt(0)
	v_mfma_f32_16x16x32_bf16 v[134:137], v[62:65], v[184:187], v[134:137]
	v_mfma_f32_16x16x32_bf16 v[130:133], v[138:141], v[184:187], v[130:133]
	v_mfma_f32_16x16x32_bf16 v[118:121], v[62:65], v[192:195], v[118:121]
	v_mfma_f32_16x16x32_bf16 v[114:117], v[138:141], v[192:195], v[114:117]
	v_mfma_f32_16x16x32_bf16 v[102:105], v[62:65], v[200:203], v[102:105]
	v_mfma_f32_16x16x32_bf16 v[98:101], v[138:141], v[200:203], v[98:101]
	v_mfma_f32_16x16x32_bf16 v[86:89], v[62:65], v[208:211], v[86:89]
	v_mfma_f32_16x16x32_bf16 v[82:85], v[138:141], v[208:211], v[82:85]
	v_mfma_f32_16x16x32_bf16 v[134:137], v[66:69], v[188:191], v[134:137]
	v_mfma_f32_16x16x32_bf16 v[130:133], v[142:145], v[188:191], v[130:133]
	v_mfma_f32_16x16x32_bf16 v[118:121], v[66:69], v[196:199], v[118:121]
	v_mfma_f32_16x16x32_bf16 v[114:117], v[142:145], v[196:199], v[114:117]
	v_mfma_f32_16x16x32_bf16 v[102:105], v[66:69], v[204:207], v[102:105]
	v_mfma_f32_16x16x32_bf16 v[98:101], v[142:145], v[204:207], v[98:101]
	v_mfma_f32_16x16x32_bf16 v[86:89], v[66:69], v[212:215], v[86:89]
	v_mfma_f32_16x16x32_bf16 v[82:85], v[142:145], v[212:215], v[82:85]
	s_setprio 0
	s_setprio 1
	v_mfma_f32_16x16x32_bf16 v[126:129], v[162:165], v[184:187], v[126:129]
	v_mfma_f32_16x16x32_bf16 v[122:125], v[176:179], v[184:187], v[122:125]
	v_mfma_f32_16x16x32_bf16 v[110:113], v[162:165], v[192:195], v[110:113]
	v_mfma_f32_16x16x32_bf16 v[106:109], v[176:179], v[192:195], v[106:109]
	v_mfma_f32_16x16x32_bf16 v[94:97], v[162:165], v[200:203], v[94:97]
	v_mfma_f32_16x16x32_bf16 v[90:93], v[176:179], v[200:203], v[90:93]
	v_mfma_f32_16x16x32_bf16 v[78:81], v[162:165], v[208:211], v[78:81]
	v_mfma_f32_16x16x32_bf16 v[74:77], v[176:179], v[208:211], v[74:77]
	v_mfma_f32_16x16x32_bf16 v[126:129], v[172:175], v[188:191], v[126:129]
	v_mfma_f32_16x16x32_bf16 v[122:125], v[180:183], v[188:191], v[122:125]
	v_mfma_f32_16x16x32_bf16 v[110:113], v[172:175], v[196:199], v[110:113]
	v_mfma_f32_16x16x32_bf16 v[106:109], v[180:183], v[196:199], v[106:109]
	v_mfma_f32_16x16x32_bf16 v[94:97], v[172:175], v[204:207], v[94:97]
	v_mfma_f32_16x16x32_bf16 v[90:93], v[180:183], v[204:207], v[90:93]
	v_mfma_f32_16x16x32_bf16 v[78:81], v[172:175], v[212:215], v[78:81]
	v_mfma_f32_16x16x32_bf16 v[74:77], v[180:183], v[212:215], v[74:77]
	s_setprio 0
	s_barrier
; #define PG8_STAGE(bufoff, gbase, voff) do { _Pragma("unroll") for (int _i = 0; _i < 2; ++_i) \
;         __builtin_amdgcn_global_load_lds((const unsigned*)((const char*)(gbase) + (voff)[_i]), (PG8_LAS unsigned*)(lds + (bufoff) + ldsw + _i * 8192), 16, 0, 0); } while (0)
; #define PG8_LDA(dst, b, h) do { _Pragma("unroll") for (int m = 0; m < 4; ++m) _Pragma("unroll") for (int k = 0; k < 2; ++k) dst[m][k] = *(const PG8_LAS bf16x8*)(lds + PG8_SA(b, h) + aoff + m * 2048 + k * 1024); } while (0)
; #define PG8_MMA(ai, bj, At, Bt) do { __builtin_amdgcn_s_setprio(1); _Pragma("unroll") for (int m = 0; m < 4; ++m) _Pragma("unroll") for (int n = 0; n < 2; ++n) _Pragma("unroll") for (int k = 0; k < 2; ++k) \
;         acc[ai][bj][m][n] = __builtin_amdgcn_mfma_f32_16x16x32_bf16(Bt[n][k], At[m][k], acc[ai][bj][m][n], 0, 0, 0); __builtin_amdgcn_s_setprio(0); } while (0)
; #define PG8_WAIT_V(n) asm volatile("s_waitcnt vmcnt(" #n ")" ::: "memory")
; #define PG8_WAIT_L(n) asm volatile("s_waitcnt lgkmcnt(" #n ")" ::: "memory")
; #define PG8_BAR __builtin_amdgcn_s_barrier()
; #define PG8_SCHED __builtin_amdgcn_sched_barrier(0)
; template <class Epi, class Sched, bool ALIGN_EPI = false, bool SP2 = false>
; __device__ __forceinline__ void gemm_phase(PG8_LAS unsigned char* lds, const Gemm g, const Sched& S, const Epi& E) {
;     ...
;         for (int t = 0; t < nt; t += 2) {
;     ...
;             PG8_LDA(At, 1, 1); PG8_STAGE(PG8_SB(1, 0), b3, voffB); PG8_STAGE(PG8_SB(1, 1), b3 + hstepB, voffB); PG8_STAGE(PG8_SA(1, 0), a3, voffA);
;             PG8_WAIT_V(8); PG8_WAIT_L(0); PG8_BAR; PG8_MMA(1, 0, At, B0); PG8_MMA(1, 1, At, B1); PG8_BAR; PG8_SCHED;
	s_add_i32 s40, s71, s48
	v_lshl_add_u64 v[216:217], v[216:217], 0, s[16:17]
	s_mov_b32 m0, s40
	ds_read_b128 v[184:187], v170 offset:49152
	ds_read_b128 v[188:191], v170 offset:50176
	ds_read_b128 v[192:195], v170 offset:51200
	ds_read_b128 v[196:199], v170 offset:52224
	ds_read_b128 v[200:203], v170 offset:53248
	ds_read_b128 v[204:207], v170 offset:54272
	ds_read_b128 v[208:211], v170 offset:55296
	ds_read_b128 v[212:215], v170 offset:56320
	global_load_lds_dwordx4 v[216:217], off
	s_add_i32 m0, s40, 0x2000
	s_add_u32 s40, s44, 0x28080
	v_lshl_add_u64 v[216:217], v[218:219], 0, s[16:17]
	s_addc_u32 s41, s45, 0
	s_add_i32 s44, s72, s48
	global_load_lds_dwordx4 v[216:217], off
	v_lshl_add_u64 v[216:217], s[40:41], 0, v[150:151]
	s_mov_b32 m0, s44
	s_nop 0
	global_load_lds_dwordx4 v[216:217], off
	v_lshl_add_u64 v[216:217], s[40:41], 0, v[146:147]
	s_add_i32 m0, s44, 0x2000
	s_nop 0
	global_load_lds_dwordx4 v[216:217], off
	v_lshl_add_u64 v[216:217], v[220:221], 0, s[16:17]
	s_mov_b32 m0, s56
	s_nop 0
	global_load_lds_dwordx4 v[216:217], off
	v_lshl_add_u64 v[216:217], v[222:223], 0, s[16:17]
	s_mov_b32 m0, s57
	s_nop 0
	global_load_lds_dwordx4 v[216:217], off
	s_waitcnt vmcnt(8)
	s_waitcnt lgkmcnt(0)
	s_barrier
	s_setprio 1
	s_waitcnt lgkmcnt(0)
	v_mfma_f32_16x16x32_bf16 v[70:73], v[62:65], v[184:187], v[70:73]
	v_mfma_f32_16x16x32_bf16 v[58:61], v[138:141], v[184:187], v[58:61]
	v_mfma_f32_16x16x32_bf16 v[46:49], v[62:65], v[192:195], v[46:49]
	v_mfma_f32_16x16x32_bf16 v[42:45], v[138:141], v[192:195], v[42:45]
	v_mfma_f32_16x16x32_bf16 v[30:33], v[62:65], v[200:203], v[30:33]
	v_mfma_f32_16x16x32_bf16 v[26:29], v[138:141], v[200:203], v[26:29]
	v_mfma_f32_16x16x32_bf16 v[14:17], v[62:65], v[208:211], v[14:17]
	v_mfma_f32_16x16x32_bf16 v[10:13], v[138:141], v[208:211], v[10:13]
	v_mfma_f32_16x16x32_bf16 v[70:73], v[66:69], v[188:191], v[70:73]
	v_mfma_f32_16x16x32_bf16 v[58:61], v[142:145], v[188:191], v[58:61]
	v_mfma_f32_16x16x32_bf16 v[46:49], v[66:69], v[196:199], v[46:49]
	v_mfma_f32_16x16x32_bf16 v[42:45], v[142:145], v[196:199], v[42:45]
	v_mfma_f32_16x16x32_bf16 v[30:33], v[66:69], v[204:207], v[30:33]
	v_mfma_f32_16x16x32_bf16 v[26:29], v[142:145], v[204:207], v[26:29]
	v_mfma_f32_16x16x32_bf16 v[14:17], v[66:69], v[212:215], v[14:17]
	v_mfma_f32_16x16x32_bf16 v[10:13], v[142:145], v[212:215], v[10:13]
	s_setprio 0
	s_setprio 1
	v_mfma_f32_16x16x32_bf16 v[54:57], v[162:165], v[184:187], v[54:57]
	v_mfma_f32_16x16x32_bf16 v[50:53], v[176:179], v[184:187], v[50:53]
	v_mfma_f32_16x16x32_bf16 v[38:41], v[162:165], v[192:195], v[38:41]
	v_mfma_f32_16x16x32_bf16 v[34:37], v[176:179], v[192:195], v[34:37]
	v_mfma_f32_16x16x32_bf16 v[22:25], v[162:165], v[200:203], v[22:25]
	v_mfma_f32_16x16x32_bf16 v[18:21], v[176:179], v[200:203], v[18:21]
	v_mfma_f32_16x16x32_bf16 v[6:9], v[162:165], v[208:211], v[6:9]
	v_mfma_f32_16x16x32_bf16 v[2:5], v[176:179], v[208:211], v[2:5]
	v_mfma_f32_16x16x32_bf16 v[54:57], v[172:175], v[188:191], v[54:57]
	v_mfma_f32_16x16x32_bf16 v[50:53], v[180:183], v[188:191], v[50:53]
	v_mfma_f32_16x16x32_bf16 v[38:41], v[172:175], v[196:199], v[38:41]
	v_mfma_f32_16x16x32_bf16 v[34:37], v[180:183], v[196:199], v[34:37]
	v_mfma_f32_16x16x32_bf16 v[22:25], v[172:175], v[204:207], v[22:25]
	v_mfma_f32_16x16x32_bf16 v[18:21], v[180:183], v[204:207], v[18:21]
	v_mfma_f32_16x16x32_bf16 v[6:9], v[172:175], v[212:215], v[6:9]
	v_mfma_f32_16x16x32_bf16 v[2:5], v[180:183], v[212:215], v[2:5]
	s_setprio 0
	s_barrier
	s_add_i32 s33, s33, 2
	s_add_u32 s2, s2, 0x100
	s_addc_u32 s5, s5, 0
	s_cmp_gt_u32 s33, 7
	s_mov_b64 s[40:41], s[42:43]

; #define PG8_STAGE(bufoff, gbase, voff) do { _Pragma("unroll") for (int _i = 0; _i < 2; ++_i) \
;         __builtin_amdgcn_global_load_lds((const unsigned*)((const char*)(gbase) + (voff)[_i]), (PG8_LAS unsigned*)(lds + (bufoff) + ldsw + _i * 8192), 16, 0, 0); } while (0)
; #define PG8_LDA(dst, b, h) do { _Pragma("unroll") for (int m = 0; m < 4; ++m) _Pragma("unroll") for (int k = 0; k < 2; ++k) dst[m][k] = *(const PG8_LAS bf16x8*)(lds + PG8_SA(b, h) + aoff + m * 2048 + k * 1024); } while (0)
; #define PG8_LDB(dst, b, h) do { _Pragma("unroll") for (int n = 0; n < 2; ++n) _Pragma("unroll") for (int k = 0; k < 2; ++k) dst[n][k] = *(const PG8_LAS bf16x8*)(lds + PG8_SB(b, h) + boff + n * 2048 + k * 1024); } while (0)
; #define PG8_MMA(ai, bj, At, Bt) do { __builtin_amdgcn_s_setprio(1); _Pragma("unroll") for (int m = 0; m < 4; ++m) _Pragma("unroll") for (int n = 0; n < 2; ++n) _Pragma("unroll") for (int k = 0; k < 2; ++k) \
;         acc[ai][bj][m][n] = __builtin_amdgcn_mfma_f32_16x16x32_bf16(Bt[n][k], At[m][k], acc[ai][bj][m][n], 0, 0, 0); __builtin_amdgcn_s_setprio(0); } while (0)
; #define PG8_WAIT_V(n) asm volatile("s_waitcnt vmcnt(" #n ")" ::: "memory")
; #define PG8_BAR __builtin_amdgcn_s_barrier()
; template <class Epi, class Sched, bool ALIGN_EPI = false, bool SP2 = false>
; __device__ __forceinline__ void gemm_phase(PG8_LAS unsigned char* lds, const Gemm g, const Sched& S, const Epi& E) {
;     ...
;         for (int t = 0; t < nt; t += 2) {
;             const bool last = (t == nt - 2);
;             const char* a1 = cA + (size_t)(t + 1) * kstep;
;             const char* a2 = last ? nA : cA + (size_t)(t + 2) * kstep; const char* b2 = last ? nB : cB + (size_t)(t + 2) * kstep;
;             const char* a3 = a2 + kstep; const char* b3 = b2 + kstep;
;             if (last && has_next) S.a_ready(nxt);
;             if constexpr (SP2) {
;             PG8_LDB(B0, 0, 0); PG8_LDB(B1, 0, 1); PG8_SCHED; PG8_LDA(At, 0, 0); PG8_STAGE(PG8_SA(1, 1), a1 + hstepA, voffA);
;             PG8_WAIT_V(8); PG8_WAIT_L(0); PG8_BAR; PG8_MMA(0, 0, At, B0); PG8_MMA(0, 1, At, B1); PG8_BAR; PG8_SCHED;
;             PG8_LDA(At, 0, 1); PG8_STAGE(PG8_SB(0, 0), b2, voffB); PG8_STAGE(PG8_SB(0, 1), b2 + hstepB, voffB); PG8_STAGE(PG8_SA(0, 0), a2, voffA);
;             PG8_WAIT_V(8); PG8_WAIT_L(0); PG8_BAR; PG8_MMA(1, 0, At, B0); PG8_MMA(1, 1, At, B1); PG8_BAR; PG8_SCHED;
.LBB0_522:
	s_ashr_i32 s19, s18, 31
	s_lshl_b64 s[20:21], s[18:19], 18
	s_add_u32 s20, s8, s20
	s_addc_u32 s21, s9, s21
	s_and_b64 s[22:23], s[6:7], exec
	s_cselect_b32 s19, s21, s27
	s_cselect_b32 s44, s20, s26
	s_ashr_i32 s17, s16, 31
	s_lshl_b64 s[22:23], s[16:17], 18
	s_add_u32 s22, s33, s22
	s_addc_u32 s23, s34, s23
	s_and_b64 s[30:31], s[6:7], exec
	s_cselect_b32 s17, s23, s29
	s_cselect_b32 s45, s22, s28
	s_add_u32 s26, s26, 0x20080
	s_addc_u32 s27, s27, 0
	s_add_u32 s46, s28, 0x100
	s_addc_u32 s47, s29, 0
	s_mov_b32 s48, -2
	s_waitcnt lgkmcnt(0)
	ds_read_b128 v[146:149], v152
	ds_read_b128 v[156:159], v152 offset:1024
	ds_read_b128 v[160:163], v152 offset:2048
	ds_read_b128 v[164:167], v152 offset:3072
	ds_read_b128 v[168:171], v153
	ds_read_b128 v[172:175], v153 offset:1024
	ds_read_b128 v[176:179], v153 offset:2048
	ds_read_b128 v[180:183], v153 offset:3072
	s_add_u32 s28, s26, 0xfffe0080
	s_addc_u32 s29, s27, -1
	s_cmp_eq_u32 s48, 4
	s_cselect_b32 s31, s19, s29
	s_cselect_b32 s30, s44, s28
	s_cselect_b32 s29, s17, s47
	s_cselect_b32 s28, s45, s46
	v_lshl_add_u64 v[216:217], s[26:27], 0, v[138:139]
	s_add_i32 m0, s25, 0xc000
	ds_read_b128 v[184:187], v154
	ds_read_b128 v[188:191], v154 offset:1024
	ds_read_b128 v[192:195], v154 offset:2048
	ds_read_b128 v[196:199], v154 offset:3072
	ds_read_b128 v[200:203], v154 offset:4096
	ds_read_b128 v[204:207], v154 offset:5120
	ds_read_b128 v[208:211], v154 offset:6144
	ds_read_b128 v[212:215], v154 offset:7168
	global_load_lds_dwordx4 v[216:217], off
	v_lshl_add_u64 v[216:217], s[26:27], 0, v[140:141]
	s_add_i32 m0, s25, 0xe000
	s_nop 0
	global_load_lds_dwordx4 v[216:217], off
	s_waitcnt vmcnt(8)
	s_waitcnt lgkmcnt(0)
	s_barrier
	s_setprio 1
	s_waitcnt lgkmcnt(0)
	v_mfma_f32_16x16x32_bf16 v[126:129], v[146:149], v[184:187], 0
	v_mfma_f32_16x16x32_bf16 v[122:125], v[160:163], v[184:187], 0
	v_mfma_f32_16x16x32_bf16 v[110:113], v[146:149], v[192:195], 0
	v_mfma_f32_16x16x32_bf16 v[106:109], v[160:163], v[192:195], 0
	v_mfma_f32_16x16x32_bf16 v[94:97], v[146:149], v[200:203], 0
	v_mfma_f32_16x16x32_bf16 v[90:93], v[160:163], v[200:203], 0
	v_mfma_f32_16x16x32_bf16 v[78:81], v[146:149], v[208:211], 0
	v_mfma_f32_16x16x32_bf16 v[74:77], v[160:163], v[208:211], 0
	v_mfma_f32_16x16x32_bf16 v[126:129], v[156:159], v[188:191], v[126:129]
	v_mfma_f32_16x16x32_bf16 v[122:125], v[164:167], v[188:191], v[122:125]
	v_mfma_f32_16x16x32_bf16 v[110:113], v[156:159], v[196:199], v[110:113]
	v_mfma_f32_16x16x32_bf16 v[106:109], v[164:167], v[196:199], v[106:109]
	v_mfma_f32_16x16x32_bf16 v[94:97], v[156:159], v[204:207], v[94:97]
	v_mfma_f32_16x16x32_bf16 v[90:93], v[164:167], v[204:207], v[90:93]
	v_mfma_f32_16x16x32_bf16 v[78:81], v[156:159], v[212:215], v[78:81]
	v_mfma_f32_16x16x32_bf16 v[74:77], v[164:167], v[212:215], v[74:77]
	s_setprio 0
	s_setprio 1
	v_mfma_f32_16x16x32_bf16 v[118:121], v[168:171], v[184:187], 0
	v_mfma_f32_16x16x32_bf16 v[114:117], v[176:179], v[184:187], 0
	v_mfma_f32_16x16x32_bf16 v[102:105], v[168:171], v[192:195], 0
	v_mfma_f32_16x16x32_bf16 v[98:101], v[176:179], v[192:195], 0
	v_mfma_f32_16x16x32_bf16 v[86:89], v[168:171], v[200:203], 0
	v_mfma_f32_16x16x32_bf16 v[82:85], v[176:179], v[200:203], 0
	v_mfma_f32_16x16x32_bf16 v[70:73], v[168:171], v[208:211], 0
	v_mfma_f32_16x16x32_bf16 v[66:69], v[176:179], v[208:211], 0
	v_mfma_f32_16x16x32_bf16 v[118:121], v[172:175], v[188:191], v[118:121]
	v_mfma_f32_16x16x32_bf16 v[114:117], v[180:183], v[188:191], v[114:117]
	v_mfma_f32_16x16x32_bf16 v[102:105], v[172:175], v[196:199], v[102:105]
	v_mfma_f32_16x16x32_bf16 v[98:101], v[180:183], v[196:199], v[98:101]
	v_mfma_f32_16x16x32_bf16 v[86:89], v[172:175], v[204:207], v[86:89]
	v_mfma_f32_16x16x32_bf16 v[82:85], v[180:183], v[204:207], v[82:85]
	v_mfma_f32_16x16x32_bf16 v[70:73], v[172:175], v[212:215], v[70:73]
	v_mfma_f32_16x16x32_bf16 v[66:69], v[180:183], v[212:215], v[66:69]
	s_setprio 0
	s_barrier
	s_add_i32 s49, s41, s2
	v_lshl_add_u64 v[216:217], s[28:29], 0, v[132:133]
	s_mov_b32 m0, s49
	ds_read_b128 v[184:187], v154 offset:16384
	ds_read_b128 v[188:191], v154 offset:17408
	ds_read_b128 v[192:195], v154 offset:18432
	ds_read_b128 v[196:199], v154 offset:19456
	ds_read_b128 v[200:203], v154 offset:20480
	ds_read_b128 v[204:207], v154 offset:21504
	ds_read_b128 v[208:211], v154 offset:22528
	ds_read_b128 v[212:215], v154 offset:23552
	global_load_lds_dwordx4 v[216:217], off
	s_add_i32 m0, s49, 0x2000
	s_add_u32 s50, s28, 0x20000
	v_lshl_add_u64 v[218:219], s[28:29], 0, v[136:137]
	s_addc_u32 s51, s29, 0
	s_add_i32 s49, s42, s2
	global_load_lds_dwordx4 v[218:219], off
	v_lshl_add_u64 v[220:221], s[50:51], 0, v[132:133]
	s_mov_b32 m0, s49
	v_lshl_add_u64 v[222:223], s[30:31], 0, v[134:135]
	global_load_lds_dwordx4 v[220:221], off
	v_lshl_add_u64 v[220:221], s[50:51], 0, v[136:137]
	s_add_i32 m0, s49, 0x2000
	s_nop 0
	global_load_lds_dwordx4 v[220:221], off
	v_lshl_add_u64 v[220:221], s[30:31], 0, v[130:131]
	s_mov_b32 m0, s25
	s_nop 0
	global_load_lds_dwordx4 v[220:221], off
	s_mov_b32 m0, s35
	s_nop 0
	global_load_lds_dwordx4 v[222:223], off
	s_waitcnt vmcnt(8)
	s_waitcnt lgkmcnt(0)
	s_barrier
; #define PG8_STAGE(bufoff, gbase, voff) do { _Pragma("unroll") for (int _i = 0; _i < 2; ++_i) \
;         __builtin_amdgcn_global_load_lds((const unsigned*)((const char*)(gbase) + (voff)[_i]), (PG8_LAS unsigned*)(lds + (bufoff) + ldsw + _i * 8192), 16, 0, 0); } while (0)
; #define PG8_LDA(dst, b, h) do { _Pragma("unroll") for (int m = 0; m < 4; ++m) _Pragma("unroll") for (int k = 0; k < 2; ++k) dst[m][k] = *(const PG8_LAS bf16x8*)(lds + PG8_SA(b, h) + aoff + m * 2048 + k * 1024); } while (0)
; #define PG8_LDB(dst, b, h) do { _Pragma("unroll") for (int n = 0; n < 2; ++n) _Pragma("unroll") for (int k = 0; k < 2; ++k) dst[n][k] = *(const PG8_LAS bf16x8*)(lds + PG8_SB(b, h) + boff + n * 2048 + k * 1024); } while (0)
; #define PG8_MMA(ai, bj, At, Bt) do { __builtin_amdgcn_s_setprio(1); _Pragma("unroll") for (int m = 0; m < 4; ++m) _Pragma("unroll") for (int n = 0; n < 2; ++n) _Pragma("unroll") for (int k = 0; k < 2; ++k) \
;         acc[ai][bj][m][n] = __builtin_amdgcn_mfma_f32_16x16x32_bf16(Bt[n][k], At[m][k], acc[ai][bj][m][n], 0, 0, 0); __builtin_amdgcn_s_setprio(0); } while (0)
; #define PG8_WAIT_V(n) asm volatile("s_waitcnt vmcnt(" #n ")" ::: "memory")
; #define PG8_WAIT_L(n) asm volatile("s_waitcnt lgkmcnt(" #n ")" ::: "memory")
; #define PG8_BAR __builtin_amdgcn_s_barrier()
; #define PG8_SCHED __builtin_amdgcn_sched_barrier(0)
; template <class Epi, class Sched, bool ALIGN_EPI = false, bool SP2 = false>
; __device__ __forceinline__ void gemm_phase(PG8_LAS unsigned char* lds, const Gemm g, const Sched& S, const Epi& E) {
;     ...
;             PG8_WAIT_V(8); PG8_WAIT_L(0); PG8_BAR; PG8_MMA(1, 0, At, B0); PG8_MMA(1, 1, At, B1); PG8_BAR; PG8_SCHED;
;             PG8_LDB(B0, 1, 0); PG8_LDB(B1, 1, 1); PG8_SCHED; PG8_LDA(At, 1, 0); PG8_STAGE(PG8_SA(0, 1), a2 + hstepA, voffA);
;             PG8_WAIT_V(8); PG8_WAIT_L(0); PG8_BAR; PG8_MMA(0, 0, At, B0); PG8_MMA(0, 1, At, B1); PG8_BAR; PG8_SCHED;
	s_setprio 1
	s_waitcnt lgkmcnt(0)
	v_mfma_f32_16x16x32_bf16 v[62:65], v[146:149], v[184:187], 0
	v_mfma_f32_16x16x32_bf16 v[58:61], v[160:163], v[184:187], 0
	v_mfma_f32_16x16x32_bf16 v[46:49], v[146:149], v[192:195], 0
	v_mfma_f32_16x16x32_bf16 v[42:45], v[160:163], v[192:195], 0
	v_mfma_f32_16x16x32_bf16 v[30:33], v[146:149], v[200:203], 0
	v_mfma_f32_16x16x32_bf16 v[26:29], v[160:163], v[200:203], 0
	v_mfma_f32_16x16x32_bf16 v[14:17], v[146:149], v[208:211], 0
	v_mfma_f32_16x16x32_bf16 v[10:13], v[160:163], v[208:211], 0
	v_mfma_f32_16x16x32_bf16 v[62:65], v[156:159], v[188:191], v[62:65]
	v_mfma_f32_16x16x32_bf16 v[58:61], v[164:167], v[188:191], v[58:61]
	v_mfma_f32_16x16x32_bf16 v[46:49], v[156:159], v[196:199], v[46:49]
	v_mfma_f32_16x16x32_bf16 v[42:45], v[164:167], v[196:199], v[42:45]
	v_mfma_f32_16x16x32_bf16 v[30:33], v[156:159], v[204:207], v[30:33]
	v_mfma_f32_16x16x32_bf16 v[26:29], v[164:167], v[204:207], v[26:29]
	v_mfma_f32_16x16x32_bf16 v[14:17], v[156:159], v[212:215], v[14:17]
	v_mfma_f32_16x16x32_bf16 v[10:13], v[164:167], v[212:215], v[10:13]
	s_setprio 0
	s_setprio 1
	v_mfma_f32_16x16x32_bf16 v[54:57], v[168:171], v[184:187], 0
	v_mfma_f32_16x16x32_bf16 v[50:53], v[176:179], v[184:187], 0
	v_mfma_f32_16x16x32_bf16 v[38:41], v[168:171], v[192:195], 0
	v_mfma_f32_16x16x32_bf16 v[34:37], v[176:179], v[192:195], 0
	v_mfma_f32_16x16x32_bf16 v[22:25], v[168:171], v[200:203], 0
	v_mfma_f32_16x16x32_bf16 v[18:21], v[176:179], v[200:203], 0
	v_mfma_f32_16x16x32_bf16 v[6:9], v[168:171], v[208:211], 0
	v_mfma_f32_16x16x32_bf16 v[2:5], v[176:179], v[208:211], 0
	v_mfma_f32_16x16x32_bf16 v[54:57], v[172:175], v[188:191], v[54:57]
	v_mfma_f32_16x16x32_bf16 v[50:53], v[180:183], v[188:191], v[50:53]
	v_mfma_f32_16x16x32_bf16 v[38:41], v[172:175], v[196:199], v[38:41]
	v_mfma_f32_16x16x32_bf16 v[34:37], v[180:183], v[196:199], v[34:37]
	v_mfma_f32_16x16x32_bf16 v[22:25], v[172:175], v[204:207], v[22:25]
	v_mfma_f32_16x16x32_bf16 v[18:21], v[180:183], v[204:207], v[18:21]
	v_mfma_f32_16x16x32_bf16 v[6:9], v[172:175], v[212:215], v[6:9]
	v_mfma_f32_16x16x32_bf16 v[2:5], v[180:183], v[212:215], v[2:5]
	s_setprio 0
	s_barrier
	s_add_i32 s49, 0, 0x18000
	v_add_u32_e32 v155, s49, v150
	s_add_i32 s50, 0, 0x1c000
	ds_read_b128 v[146:149], v155
	ds_read_b128 v[156:159], v155 offset:1024
	ds_read_b128 v[160:163], v155 offset:2048
	ds_read_b128 v[164:167], v155 offset:3072
	v_add_u32_e32 v155, s50, v150
	ds_read_b128 v[168:171], v155
	ds_read_b128 v[172:175], v155 offset:1024
	ds_read_b128 v[176:179], v155 offset:2048
	ds_read_b128 v[180:183], v155 offset:3072
	s_add_u32 s30, s30, 0x20000
	s_addc_u32 s31, s31, 0
	s_mov_b32 m0, s36
	v_lshl_add_u64 v[224:225], s[30:31], 0, v[130:131]
	ds_read_b128 v[184:187], v154 offset:32768
	ds_read_b128 v[188:191], v154 offset:33792
	ds_read_b128 v[192:195], v154 offset:34816
	ds_read_b128 v[196:199], v154 offset:35840
	ds_read_b128 v[200:203], v154 offset:36864
	ds_read_b128 v[204:207], v154 offset:37888
	ds_read_b128 v[208:211], v154 offset:38912
	ds_read_b128 v[212:215], v154 offset:39936
	global_load_lds_dwordx4 v[224:225], off
	v_lshl_add_u64 v[224:225], s[30:31], 0, v[134:135]
	s_mov_b32 m0, s37
	s_nop 0
	global_load_lds_dwordx4 v[224:225], off
	s_waitcnt vmcnt(8)
	s_waitcnt lgkmcnt(0)
	s_barrier
	s_setprio 1
	s_waitcnt lgkmcnt(0)
	v_mfma_f32_16x16x32_bf16 v[126:129], v[146:149], v[184:187], v[126:129]
	v_mfma_f32_16x16x32_bf16 v[122:125], v[160:163], v[184:187], v[122:125]
	v_mfma_f32_16x16x32_bf16 v[110:113], v[146:149], v[192:195], v[110:113]
	v_mfma_f32_16x16x32_bf16 v[106:109], v[160:163], v[192:195], v[106:109]
	v_mfma_f32_16x16x32_bf16 v[94:97], v[146:149], v[200:203], v[94:97]
	v_mfma_f32_16x16x32_bf16 v[90:93], v[160:163], v[200:203], v[90:93]
	v_mfma_f32_16x16x32_bf16 v[78:81], v[146:149], v[208:211], v[78:81]
	v_mfma_f32_16x16x32_bf16 v[74:77], v[160:163], v[208:211], v[74:77]
	v_mfma_f32_16x16x32_bf16 v[126:129], v[156:159], v[188:191], v[126:129]
	v_mfma_f32_16x16x32_bf16 v[122:125], v[164:167], v[188:191], v[122:125]
	v_mfma_f32_16x16x32_bf16 v[110:113], v[156:159], v[196:199], v[110:113]
	v_mfma_f32_16x16x32_bf16 v[106:109], v[164:167], v[196:199], v[106:109]
	v_mfma_f32_16x16x32_bf16 v[94:97], v[156:159], v[204:207], v[94:97]
	v_mfma_f32_16x16x32_bf16 v[90:93], v[164:167], v[204:207], v[90:93]
	v_mfma_f32_16x16x32_bf16 v[78:81], v[156:159], v[212:215], v[78:81]
	v_mfma_f32_16x16x32_bf16 v[74:77], v[164:167], v[212:215], v[74:77]
	s_setprio 0
	s_setprio 1
	v_mfma_f32_16x16x32_bf16 v[118:121], v[168:171], v[184:187], v[118:121]
	v_mfma_f32_16x16x32_bf16 v[114:117], v[176:179], v[184:187], v[114:117]
	v_mfma_f32_16x16x32_bf16 v[102:105], v[168:171], v[192:195], v[102:105]
	v_mfma_f32_16x16x32_bf16 v[98:101], v[176:179], v[192:195], v[98:101]
	v_mfma_f32_16x16x32_bf16 v[86:89], v[168:171], v[200:203], v[86:89]
	v_mfma_f32_16x16x32_bf16 v[82:85], v[176:179], v[200:203], v[82:85]
	v_mfma_f32_16x16x32_bf16 v[70:73], v[168:171], v[208:211], v[70:73]
	v_mfma_f32_16x16x32_bf16 v[66:69], v[176:179], v[208:211], v[66:69]
	v_mfma_f32_16x16x32_bf16 v[118:121], v[172:175], v[188:191], v[118:121]
	v_mfma_f32_16x16x32_bf16 v[114:117], v[180:183], v[188:191], v[114:117]
	v_mfma_f32_16x16x32_bf16 v[102:105], v[172:175], v[196:199], v[102:105]
	v_mfma_f32_16x16x32_bf16 v[98:101], v[180:183], v[196:199], v[98:101]
	v_mfma_f32_16x16x32_bf16 v[86:89], v[172:175], v[204:207], v[86:89]
	v_mfma_f32_16x16x32_bf16 v[82:85], v[180:183], v[204:207], v[82:85]
	v_mfma_f32_16x16x32_bf16 v[70:73], v[172:175], v[212:215], v[70:73]
	v_mfma_f32_16x16x32_bf16 v[66:69], v[180:183], v[212:215], v[66:69]
	s_setprio 0
	s_barrier
; #define PG8_STAGE(bufoff, gbase, voff) do { _Pragma("unroll") for (int _i = 0; _i < 2; ++_i) \
;         __builtin_amdgcn_global_load_lds((const unsigned*)((const char*)(gbase) + (voff)[_i]), (PG8_LAS unsigned*)(lds + (bufoff) + ldsw + _i * 8192), 16, 0, 0); } while (0)
; #define PG8_LDA(dst, b, h) do { _Pragma("unroll") for (int m = 0; m < 4; ++m) _Pragma("unroll") for (int k = 0; k < 2; ++k) dst[m][k] = *(const PG8_LAS bf16x8*)(lds + PG8_SA(b, h) + aoff + m * 2048 + k * 1024); } while (0)
; #define PG8_MMA(ai, bj, At, Bt) do { __builtin_amdgcn_s_setprio(1); _Pragma("unroll") for (int m = 0; m < 4; ++m) _Pragma("unroll") for (int n = 0; n < 2; ++n) _Pragma("unroll") for (int k = 0; k < 2; ++k) \
;         acc[ai][bj][m][n] = __builtin_amdgcn_mfma_f32_16x16x32_bf16(Bt[n][k], At[m][k], acc[ai][bj][m][n], 0, 0, 0); __builtin_amdgcn_s_setprio(0); } while (0)
; #define PG8_WAIT_V(n) asm volatile("s_waitcnt vmcnt(" #n ")" ::: "memory")
; #define PG8_WAIT_L(n) asm volatile("s_waitcnt lgkmcnt(" #n ")" ::: "memory")
; #define PG8_BAR __builtin_amdgcn_s_barrier()
; #define PG8_SCHED __builtin_amdgcn_sched_barrier(0)
; template <class Epi, class Sched, bool ALIGN_EPI = false, bool SP2 = false>
; __device__ __forceinline__ void gemm_phase(PG8_LAS unsigned char* lds, const Gemm g, const Sched& S, const Epi& E) {
;     ...
;         for (int t = 0; t < nt; t += 2) {
;     ...
;             PG8_LDA(At, 1, 1); PG8_STAGE(PG8_SB(1, 0), b3, voffB); PG8_STAGE(PG8_SB(1, 1), b3 + hstepB, voffB); PG8_STAGE(PG8_SA(1, 0), a3, voffA);
;             PG8_WAIT_V(8); PG8_WAIT_L(0); PG8_BAR; PG8_MMA(1, 0, At, B0); PG8_MMA(1, 1, At, B1); PG8_BAR; PG8_SCHED;
	s_add_i32 s30, s49, s2
	v_lshl_add_u64 v[216:217], v[216:217], 0, s[14:15]
	s_mov_b32 m0, s30
	ds_read_b128 v[184:187], v154 offset:49152
	ds_read_b128 v[188:191], v154 offset:50176
	ds_read_b128 v[192:195], v154 offset:51200
	ds_read_b128 v[196:199], v154 offset:52224
	ds_read_b128 v[200:203], v154 offset:53248
	ds_read_b128 v[204:207], v154 offset:54272
	ds_read_b128 v[208:211], v154 offset:55296
	ds_read_b128 v[212:215], v154 offset:56320
	global_load_lds_dwordx4 v[216:217], off
	s_add_i32 m0, s30, 0x2000
	s_add_u32 s28, s28, 0x20080
	v_lshl_add_u64 v[216:217], v[218:219], 0, s[14:15]
	s_addc_u32 s29, s29, 0
	s_add_i32 s30, s50, s2
	global_load_lds_dwordx4 v[216:217], off
	v_lshl_add_u64 v[216:217], s[28:29], 0, v[132:133]
	s_mov_b32 m0, s30
	s_nop 0
	global_load_lds_dwordx4 v[216:217], off
	v_lshl_add_u64 v[216:217], s[28:29], 0, v[136:137]
	s_add_i32 m0, s30, 0x2000
	s_nop 0
	global_load_lds_dwordx4 v[216:217], off
	v_lshl_add_u64 v[216:217], v[220:221], 0, s[14:15]
	s_mov_b32 m0, s39
	s_nop 0
	global_load_lds_dwordx4 v[216:217], off
	v_lshl_add_u64 v[216:217], v[222:223], 0, s[14:15]
	s_mov_b32 m0, s40
	s_nop 0
	global_load_lds_dwordx4 v[216:217], off
	s_waitcnt vmcnt(8)
	s_waitcnt lgkmcnt(0)
	s_barrier
	s_setprio 1
	s_waitcnt lgkmcnt(0)
	v_mfma_f32_16x16x32_bf16 v[62:65], v[146:149], v[184:187], v[62:65]
	v_mfma_f32_16x16x32_bf16 v[58:61], v[160:163], v[184:187], v[58:61]
	v_mfma_f32_16x16x32_bf16 v[46:49], v[146:149], v[192:195], v[46:49]
	v_mfma_f32_16x16x32_bf16 v[42:45], v[160:163], v[192:195], v[42:45]
	v_mfma_f32_16x16x32_bf16 v[30:33], v[146:149], v[200:203], v[30:33]
	v_mfma_f32_16x16x32_bf16 v[26:29], v[160:163], v[200:203], v[26:29]
	v_mfma_f32_16x16x32_bf16 v[14:17], v[146:149], v[208:211], v[14:17]
	v_mfma_f32_16x16x32_bf16 v[10:13], v[160:163], v[208:211], v[10:13]
	v_mfma_f32_16x16x32_bf16 v[62:65], v[156:159], v[188:191], v[62:65]
	v_mfma_f32_16x16x32_bf16 v[58:61], v[164:167], v[188:191], v[58:61]
	v_mfma_f32_16x16x32_bf16 v[46:49], v[156:159], v[196:199], v[46:49]
	v_mfma_f32_16x16x32_bf16 v[42:45], v[164:167], v[196:199], v[42:45]
	v_mfma_f32_16x16x32_bf16 v[30:33], v[156:159], v[204:207], v[30:33]
	v_mfma_f32_16x16x32_bf16 v[26:29], v[164:167], v[204:207], v[26:29]
	v_mfma_f32_16x16x32_bf16 v[14:17], v[156:159], v[212:215], v[14:17]
	v_mfma_f32_16x16x32_bf16 v[10:13], v[164:167], v[212:215], v[10:13]
	s_setprio 0
	s_setprio 1
	v_mfma_f32_16x16x32_bf16 v[54:57], v[168:171], v[184:187], v[54:57]
	v_mfma_f32_16x16x32_bf16 v[50:53], v[176:179], v[184:187], v[50:53]
	v_mfma_f32_16x16x32_bf16 v[38:41], v[168:171], v[192:195], v[38:41]
	v_mfma_f32_16x16x32_bf16 v[34:37], v[176:179], v[192:195], v[34:37]
	v_mfma_f32_16x16x32_bf16 v[22:25], v[168:171], v[200:203], v[22:25]
	v_mfma_f32_16x16x32_bf16 v[18:21], v[176:179], v[200:203], v[18:21]
	v_mfma_f32_16x16x32_bf16 v[6:9], v[168:171], v[208:211], v[6:9]
	v_mfma_f32_16x16x32_bf16 v[2:5], v[176:179], v[208:211], v[2:5]
	v_mfma_f32_16x16x32_bf16 v[54:57], v[172:175], v[188:191], v[54:57]
	v_mfma_f32_16x16x32_bf16 v[50:53], v[180:183], v[188:191], v[50:53]
	v_mfma_f32_16x16x32_bf16 v[38:41], v[172:175], v[196:199], v[38:41]
	v_mfma_f32_16x16x32_bf16 v[34:37], v[180:183], v[196:199], v[34:37]
	v_mfma_f32_16x16x32_bf16 v[22:25], v[172:175], v[204:207], v[22:25]
	v_mfma_f32_16x16x32_bf16 v[18:21], v[180:183], v[204:207], v[18:21]
	v_mfma_f32_16x16x32_bf16 v[6:9], v[172:175], v[212:215], v[6:9]
	v_mfma_f32_16x16x32_bf16 v[2:5], v[180:183], v[212:215], v[2:5]
	s_setprio 0
	s_barrier
	s_add_i32 s48, s48, 2
	s_add_u32 s26, s26, 0x100
	s_addc_u32 s27, s27, 0
	s_add_u32 s46, s46, 0x100
	s_addc_u32 s47, s47, 0
	s_cmp_gt_u32 s48, 5

; #define PG8_STAGE(bufoff, gbase, voff) do { _Pragma("unroll") for (int _i = 0; _i < 2; ++_i) \
;         __builtin_amdgcn_global_load_lds((const unsigned*)((const char*)(gbase) + (voff)[_i]), (PG8_LAS unsigned*)(lds + (bufoff) + ldsw + _i * 8192), 16, 0, 0); } while (0)
; #define PG8_LDA(dst, b, h) do { _Pragma("unroll") for (int m = 0; m < 4; ++m) _Pragma("unroll") for (int k = 0; k < 2; ++k) dst[m][k] = *(const PG8_LAS bf16x8*)(lds + PG8_SA(b, h) + aoff + m * 2048 + k * 1024); } while (0)
; #define PG8_LDB(dst, b, h) do { _Pragma("unroll") for (int n = 0; n < 2; ++n) _Pragma("unroll") for (int k = 0; k < 2; ++k) dst[n][k] = *(const PG8_LAS bf16x8*)(lds + PG8_SB(b, h) + boff + n * 2048 + k * 1024); } while (0)
; #define PG8_MMA(ai, bj, At, Bt) do { __builtin_amdgcn_s_setprio(1); _Pragma("unroll") for (int m = 0; m < 4; ++m) _Pragma("unroll") for (int n = 0; n < 2; ++n) _Pragma("unroll") for (int k = 0; k < 2; ++k) \
;         acc[ai][bj][m][n] = __builtin_amdgcn_mfma_f32_16x16x32_bf16(Bt[n][k], At[m][k], acc[ai][bj][m][n], 0, 0, 0); __builtin_amdgcn_s_setprio(0); } while (0)
; #define PG8_WAIT_V(n) asm volatile("s_waitcnt vmcnt(" #n ")" ::: "memory")
; #define PG8_BAR __builtin_amdgcn_s_barrier()
; template <class Epi, class Sched, bool ALIGN_EPI = false, bool SP2 = false>
; __device__ __forceinline__ void gemm_phase(PG8_LAS unsigned char* lds, const Gemm g, const Sched& S, const Epi& E) {
;     ...
;         for (int t = 0; t < nt; t += 2) {
;             const bool last = (t == nt - 2);
;             const char* a1 = cA + (size_t)(t + 1) * kstep;
;             const char* a2 = last ? nA : cA + (size_t)(t + 2) * kstep; const char* b2 = last ? nB : cB + (size_t)(t + 2) * kstep;
;             const char* a3 = a2 + kstep; const char* b3 = b2 + kstep;
;             if (last && has_next) S.a_ready(nxt);
;             if constexpr (SP2) {
;             PG8_LDB(B0, 0, 0); PG8_LDB(B1, 0, 1); PG8_SCHED; PG8_LDA(At, 0, 0); PG8_STAGE(PG8_SA(1, 1), a1 + hstepA, voffA);
;             PG8_WAIT_V(8); PG8_WAIT_L(0); PG8_BAR; PG8_MMA(0, 0, At, B0); PG8_MMA(0, 1, At, B1); PG8_BAR; PG8_SCHED;
;             PG8_LDA(At, 0, 1); PG8_STAGE(PG8_SB(0, 0), b2, voffB); PG8_STAGE(PG8_SB(0, 1), b2 + hstepB, voffB); PG8_STAGE(PG8_SA(0, 0), a2, voffA);
;             PG8_WAIT_V(8); PG8_WAIT_L(0); PG8_BAR; PG8_MMA(1, 0, At, B0); PG8_MMA(1, 1, At, B1); PG8_BAR; PG8_SCHED;
.LBB0_604:
	s_ashr_i32 s25, s24, 31
	s_lshl_b64 s[26:27], s[24:25], 19
	s_add_u32 s26, s0, s26
	s_addc_u32 s27, s1, s27
	s_and_b64 s[28:29], s[8:9], exec
	s_cselect_b32 s25, s27, s35
	s_cselect_b32 s31, s26, s34
	s_ashr_i32 s23, s22, 31
	s_lshl_b64 s[28:29], s[22:23], 19
	s_add_u32 s28, s2, s28
	s_addc_u32 s29, s3, s29
	s_and_b64 s[38:39], s[8:9], exec
	s_cselect_b32 s23, s29, s37
	s_cselect_b32 s53, s28, s36
	s_add_u32 s34, s34, 0x40080
	s_addc_u32 s35, s35, 0
	s_add_u32 s54, s36, 0x100
	s_addc_u32 s55, s37, 0
	s_mov_b32 s56, -2
	s_waitcnt lgkmcnt(0)
	s_waitcnt lgkmcnt(0)
	ds_read_b128 v[130:133], v172
	ds_read_b128 v[134:137], v172 offset:1024
	ds_read_b128 v[138:141], v172 offset:2048
	ds_read_b128 v[142:145], v172 offset:3072
	ds_read_b128 v[162:165], v173
	ds_read_b128 v[166:169], v173 offset:1024
	ds_read_b128 v[176:179], v173 offset:2048
	ds_read_b128 v[180:183], v173 offset:3072
	s_add_u32 s36, s34, 0xfffc0080
	s_addc_u32 s37, s35, -1
	s_cmp_eq_u32 s56, 12
	s_cselect_b32 s39, s25, s37
	s_cselect_b32 s38, s31, s36
	s_cselect_b32 s37, s23, s55
	s_cselect_b32 s36, s53, s54
	v_lshl_add_u64 v[216:217], s[34:35], 0, v[154:155]
	s_add_i32 m0, s40, 0xc000
	ds_read_b128 v[184:187], v174
	ds_read_b128 v[188:191], v174 offset:1024
	ds_read_b128 v[192:195], v174 offset:2048
	ds_read_b128 v[196:199], v174 offset:3072
	ds_read_b128 v[200:203], v174 offset:4096
	ds_read_b128 v[204:207], v174 offset:5120
	ds_read_b128 v[208:211], v174 offset:6144
	ds_read_b128 v[212:215], v174 offset:7168
	global_load_lds_dwordx4 v[216:217], off
	v_lshl_add_u64 v[216:217], s[34:35], 0, v[156:157]
	s_add_i32 m0, s40, 0xe000
	s_nop 0
	global_load_lds_dwordx4 v[216:217], off
	s_waitcnt vmcnt(8)
	s_waitcnt lgkmcnt(0)
	s_barrier
	s_setprio 1
	s_waitcnt lgkmcnt(0)
	v_mfma_f32_16x16x32_bf16 v[126:129], v[130:133], v[184:187], 0
	v_mfma_f32_16x16x32_bf16 v[122:125], v[138:141], v[184:187], 0
	v_mfma_f32_16x16x32_bf16 v[110:113], v[130:133], v[192:195], 0
	v_mfma_f32_16x16x32_bf16 v[106:109], v[138:141], v[192:195], 0
	v_mfma_f32_16x16x32_bf16 v[94:97], v[130:133], v[200:203], 0
	v_mfma_f32_16x16x32_bf16 v[90:93], v[138:141], v[200:203], 0
	v_mfma_f32_16x16x32_bf16 v[78:81], v[130:133], v[208:211], 0
	v_mfma_f32_16x16x32_bf16 v[74:77], v[138:141], v[208:211], 0
	v_mfma_f32_16x16x32_bf16 v[126:129], v[134:137], v[188:191], v[126:129]
	v_mfma_f32_16x16x32_bf16 v[122:125], v[142:145], v[188:191], v[122:125]
	v_mfma_f32_16x16x32_bf16 v[110:113], v[134:137], v[196:199], v[110:113]
	v_mfma_f32_16x16x32_bf16 v[106:109], v[142:145], v[196:199], v[106:109]
	v_mfma_f32_16x16x32_bf16 v[94:97], v[134:137], v[204:207], v[94:97]
	v_mfma_f32_16x16x32_bf16 v[90:93], v[142:145], v[204:207], v[90:93]
	v_mfma_f32_16x16x32_bf16 v[78:81], v[134:137], v[212:215], v[78:81]
	v_mfma_f32_16x16x32_bf16 v[74:77], v[142:145], v[212:215], v[74:77]
	s_setprio 0
	s_setprio 1
	v_mfma_f32_16x16x32_bf16 v[118:121], v[162:165], v[184:187], 0
	v_mfma_f32_16x16x32_bf16 v[114:117], v[176:179], v[184:187], 0
	v_mfma_f32_16x16x32_bf16 v[102:105], v[162:165], v[192:195], 0
	v_mfma_f32_16x16x32_bf16 v[98:101], v[176:179], v[192:195], 0
	v_mfma_f32_16x16x32_bf16 v[86:89], v[162:165], v[200:203], 0
	v_mfma_f32_16x16x32_bf16 v[82:85], v[176:179], v[200:203], 0
	v_mfma_f32_16x16x32_bf16 v[70:73], v[162:165], v[208:211], 0
	v_mfma_f32_16x16x32_bf16 v[66:69], v[176:179], v[208:211], 0
	v_mfma_f32_16x16x32_bf16 v[118:121], v[166:169], v[188:191], v[118:121]
	v_mfma_f32_16x16x32_bf16 v[114:117], v[180:183], v[188:191], v[114:117]
	v_mfma_f32_16x16x32_bf16 v[102:105], v[166:169], v[196:199], v[102:105]
	v_mfma_f32_16x16x32_bf16 v[98:101], v[180:183], v[196:199], v[98:101]
	v_mfma_f32_16x16x32_bf16 v[86:89], v[166:169], v[204:207], v[86:89]
	v_mfma_f32_16x16x32_bf16 v[82:85], v[180:183], v[204:207], v[82:85]
	v_mfma_f32_16x16x32_bf16 v[70:73], v[166:169], v[212:215], v[70:73]
	v_mfma_f32_16x16x32_bf16 v[66:69], v[180:183], v[212:215], v[66:69]
	s_setprio 0
	s_barrier
	s_add_i32 s57, s50, s33
	v_lshl_add_u64 v[216:217], s[36:37], 0, v[148:149]
	s_mov_b32 m0, s57
	ds_read_b128 v[184:187], v174 offset:16384
	ds_read_b128 v[188:191], v174 offset:17408
	ds_read_b128 v[192:195], v174 offset:18432
	ds_read_b128 v[196:199], v174 offset:19456
	ds_read_b128 v[200:203], v174 offset:20480
	ds_read_b128 v[204:207], v174 offset:21504
	ds_read_b128 v[208:211], v174 offset:22528
	ds_read_b128 v[212:215], v174 offset:23552
	global_load_lds_dwordx4 v[216:217], off
	s_add_i32 m0, s57, 0x2000
	s_add_u32 s58, s36, 0x40000
	v_lshl_add_u64 v[218:219], s[36:37], 0, v[152:153]
	s_addc_u32 s59, s37, 0
	s_add_i32 s57, s51, s33
	global_load_lds_dwordx4 v[218:219], off
	v_lshl_add_u64 v[220:221], s[58:59], 0, v[148:149]
	s_mov_b32 m0, s57
	v_lshl_add_u64 v[222:223], s[38:39], 0, v[150:151]
	global_load_lds_dwordx4 v[220:221], off
	v_lshl_add_u64 v[220:221], s[58:59], 0, v[152:153]
	s_add_i32 m0, s57, 0x2000
	s_nop 0
	global_load_lds_dwordx4 v[220:221], off
	v_lshl_add_u64 v[220:221], s[38:39], 0, v[146:147]
	s_mov_b32 m0, s40
	s_nop 0
	global_load_lds_dwordx4 v[220:221], off
	s_mov_b32 m0, s41
	s_nop 0
	global_load_lds_dwordx4 v[222:223], off
	s_waitcnt vmcnt(8)
	s_waitcnt lgkmcnt(0)
	s_barrier
; #define PG8_STAGE(bufoff, gbase, voff) do { _Pragma("unroll") for (int _i = 0; _i < 2; ++_i) \
;         __builtin_amdgcn_global_load_lds((const unsigned*)((const char*)(gbase) + (voff)[_i]), (PG8_LAS unsigned*)(lds + (bufoff) + ldsw + _i * 8192), 16, 0, 0); } while (0)
; #define PG8_LDA(dst, b, h) do { _Pragma("unroll") for (int m = 0; m < 4; ++m) _Pragma("unroll") for (int k = 0; k < 2; ++k) dst[m][k] = *(const PG8_LAS bf16x8*)(lds + PG8_SA(b, h) + aoff + m * 2048 + k * 1024); } while (0)
; #define PG8_LDB(dst, b, h) do { _Pragma("unroll") for (int n = 0; n < 2; ++n) _Pragma("unroll") for (int k = 0; k < 2; ++k) dst[n][k] = *(const PG8_LAS bf16x8*)(lds + PG8_SB(b, h) + boff + n * 2048 + k * 1024); } while (0)
; #define PG8_MMA(ai, bj, At, Bt) do { __builtin_amdgcn_s_setprio(1); _Pragma("unroll") for (int m = 0; m < 4; ++m) _Pragma("unroll") for (int n = 0; n < 2; ++n) _Pragma("unroll") for (int k = 0; k < 2; ++k) \
;         acc[ai][bj][m][n] = __builtin_amdgcn_mfma_f32_16x16x32_bf16(Bt[n][k], At[m][k], acc[ai][bj][m][n], 0, 0, 0); __builtin_amdgcn_s_setprio(0); } while (0)
; #define PG8_WAIT_V(n) asm volatile("s_waitcnt vmcnt(" #n ")" ::: "memory")
; #define PG8_WAIT_L(n) asm volatile("s_waitcnt lgkmcnt(" #n ")" ::: "memory")
; #define PG8_BAR __builtin_amdgcn_s_barrier()
; #define PG8_SCHED __builtin_amdgcn_sched_barrier(0)
; template <class Epi, class Sched, bool ALIGN_EPI = false, bool SP2 = false>
; __device__ __forceinline__ void gemm_phase(PG8_LAS unsigned char* lds, const Gemm g, const Sched& S, const Epi& E) {
;     ...
;             PG8_WAIT_V(8); PG8_WAIT_L(0); PG8_BAR; PG8_MMA(1, 0, At, B0); PG8_MMA(1, 1, At, B1); PG8_BAR; PG8_SCHED;
;             PG8_LDB(B0, 1, 0); PG8_LDB(B1, 1, 1); PG8_SCHED; PG8_LDA(At, 1, 0); PG8_STAGE(PG8_SA(0, 1), a2 + hstepA, voffA);
;             PG8_WAIT_V(8); PG8_WAIT_L(0); PG8_BAR; PG8_MMA(0, 0, At, B0); PG8_MMA(0, 1, At, B1); PG8_BAR; PG8_SCHED;
	s_setprio 1
	s_waitcnt lgkmcnt(0)
	v_mfma_f32_16x16x32_bf16 v[62:65], v[130:133], v[184:187], 0
	v_mfma_f32_16x16x32_bf16 v[58:61], v[138:141], v[184:187], 0
	v_mfma_f32_16x16x32_bf16 v[46:49], v[130:133], v[192:195], 0
	v_mfma_f32_16x16x32_bf16 v[42:45], v[138:141], v[192:195], 0
	v_mfma_f32_16x16x32_bf16 v[30:33], v[130:133], v[200:203], 0
	v_mfma_f32_16x16x32_bf16 v[26:29], v[138:141], v[200:203], 0
	v_mfma_f32_16x16x32_bf16 v[14:17], v[130:133], v[208:211], 0
	v_mfma_f32_16x16x32_bf16 v[10:13], v[138:141], v[208:211], 0
	v_mfma_f32_16x16x32_bf16 v[62:65], v[134:137], v[188:191], v[62:65]
	v_mfma_f32_16x16x32_bf16 v[58:61], v[142:145], v[188:191], v[58:61]
	v_mfma_f32_16x16x32_bf16 v[46:49], v[134:137], v[196:199], v[46:49]
	v_mfma_f32_16x16x32_bf16 v[42:45], v[142:145], v[196:199], v[42:45]
	v_mfma_f32_16x16x32_bf16 v[30:33], v[134:137], v[204:207], v[30:33]
	v_mfma_f32_16x16x32_bf16 v[26:29], v[142:145], v[204:207], v[26:29]
	v_mfma_f32_16x16x32_bf16 v[14:17], v[134:137], v[212:215], v[14:17]
	v_mfma_f32_16x16x32_bf16 v[10:13], v[142:145], v[212:215], v[10:13]
	s_setprio 0
	s_setprio 1
	v_mfma_f32_16x16x32_bf16 v[54:57], v[162:165], v[184:187], 0
	v_mfma_f32_16x16x32_bf16 v[50:53], v[176:179], v[184:187], 0
	v_mfma_f32_16x16x32_bf16 v[38:41], v[162:165], v[192:195], 0
	v_mfma_f32_16x16x32_bf16 v[34:37], v[176:179], v[192:195], 0
	v_mfma_f32_16x16x32_bf16 v[22:25], v[162:165], v[200:203], 0
	v_mfma_f32_16x16x32_bf16 v[18:21], v[176:179], v[200:203], 0
	v_mfma_f32_16x16x32_bf16 v[6:9], v[162:165], v[208:211], 0
	v_mfma_f32_16x16x32_bf16 v[2:5], v[176:179], v[208:211], 0
	v_mfma_f32_16x16x32_bf16 v[54:57], v[166:169], v[188:191], v[54:57]
	v_mfma_f32_16x16x32_bf16 v[50:53], v[180:183], v[188:191], v[50:53]
	v_mfma_f32_16x16x32_bf16 v[38:41], v[166:169], v[196:199], v[38:41]
	v_mfma_f32_16x16x32_bf16 v[34:37], v[180:183], v[196:199], v[34:37]
	v_mfma_f32_16x16x32_bf16 v[22:25], v[166:169], v[204:207], v[22:25]
	v_mfma_f32_16x16x32_bf16 v[18:21], v[180:183], v[204:207], v[18:21]
	v_mfma_f32_16x16x32_bf16 v[6:9], v[166:169], v[212:215], v[6:9]
	v_mfma_f32_16x16x32_bf16 v[2:5], v[180:183], v[212:215], v[2:5]
	s_setprio 0
	s_barrier
	s_add_i32 s57, 0, 0x18000
	s_add_i32 s58, 0, 0x1c000
	v_add_u32_e32 v142, s57, v170
	v_add_u32_e32 v180, s58, v170
	ds_read_b128 v[130:133], v142
	ds_read_b128 v[134:137], v142 offset:1024
	ds_read_b128 v[138:141], v142 offset:2048
	ds_read_b128 v[142:145], v142 offset:3072
	ds_read_b128 v[162:165], v180
	ds_read_b128 v[166:169], v180 offset:1024
	ds_read_b128 v[176:179], v180 offset:2048
	ds_read_b128 v[180:183], v180 offset:3072
	s_add_u32 s38, s38, 0x40000
	s_addc_u32 s39, s39, 0
	s_mov_b32 m0, s42
	v_lshl_add_u64 v[224:225], s[38:39], 0, v[146:147]
	ds_read_b128 v[184:187], v174 offset:32768
	ds_read_b128 v[188:191], v174 offset:33792
	ds_read_b128 v[192:195], v174 offset:34816
	ds_read_b128 v[196:199], v174 offset:35840
	ds_read_b128 v[200:203], v174 offset:36864
	ds_read_b128 v[204:207], v174 offset:37888
	ds_read_b128 v[208:211], v174 offset:38912
	ds_read_b128 v[212:215], v174 offset:39936
	global_load_lds_dwordx4 v[224:225], off
	v_lshl_add_u64 v[224:225], s[38:39], 0, v[150:151]
	s_mov_b32 m0, s43
	s_nop 0
	global_load_lds_dwordx4 v[224:225], off
	s_waitcnt vmcnt(8)
	s_waitcnt lgkmcnt(0)
	s_barrier
	s_setprio 1
	s_waitcnt lgkmcnt(0)
	v_mfma_f32_16x16x32_bf16 v[126:129], v[130:133], v[184:187], v[126:129]
	v_mfma_f32_16x16x32_bf16 v[122:125], v[138:141], v[184:187], v[122:125]
	v_mfma_f32_16x16x32_bf16 v[110:113], v[130:133], v[192:195], v[110:113]
	v_mfma_f32_16x16x32_bf16 v[106:109], v[138:141], v[192:195], v[106:109]
	v_mfma_f32_16x16x32_bf16 v[94:97], v[130:133], v[200:203], v[94:97]
	v_mfma_f32_16x16x32_bf16 v[90:93], v[138:141], v[200:203], v[90:93]
	v_mfma_f32_16x16x32_bf16 v[78:81], v[130:133], v[208:211], v[78:81]
	v_mfma_f32_16x16x32_bf16 v[74:77], v[138:141], v[208:211], v[74:77]
	v_mfma_f32_16x16x32_bf16 v[126:129], v[134:137], v[188:191], v[126:129]
	v_mfma_f32_16x16x32_bf16 v[122:125], v[142:145], v[188:191], v[122:125]
	v_mfma_f32_16x16x32_bf16 v[110:113], v[134:137], v[196:199], v[110:113]
	v_mfma_f32_16x16x32_bf16 v[106:109], v[142:145], v[196:199], v[106:109]
	v_mfma_f32_16x16x32_bf16 v[94:97], v[134:137], v[204:207], v[94:97]
	v_mfma_f32_16x16x32_bf16 v[90:93], v[142:145], v[204:207], v[90:93]
	v_mfma_f32_16x16x32_bf16 v[78:81], v[134:137], v[212:215], v[78:81]
	v_mfma_f32_16x16x32_bf16 v[74:77], v[142:145], v[212:215], v[74:77]
	s_setprio 0
	s_setprio 1
	v_mfma_f32_16x16x32_bf16 v[118:121], v[162:165], v[184:187], v[118:121]
	v_mfma_f32_16x16x32_bf16 v[114:117], v[176:179], v[184:187], v[114:117]
	v_mfma_f32_16x16x32_bf16 v[102:105], v[162:165], v[192:195], v[102:105]
	v_mfma_f32_16x16x32_bf16 v[98:101], v[176:179], v[192:195], v[98:101]
	v_mfma_f32_16x16x32_bf16 v[86:89], v[162:165], v[200:203], v[86:89]
	v_mfma_f32_16x16x32_bf16 v[82:85], v[176:179], v[200:203], v[82:85]
	v_mfma_f32_16x16x32_bf16 v[70:73], v[162:165], v[208:211], v[70:73]
	v_mfma_f32_16x16x32_bf16 v[66:69], v[176:179], v[208:211], v[66:69]
	v_mfma_f32_16x16x32_bf16 v[118:121], v[166:169], v[188:191], v[118:121]
	v_mfma_f32_16x16x32_bf16 v[114:117], v[180:183], v[188:191], v[114:117]
	v_mfma_f32_16x16x32_bf16 v[102:105], v[166:169], v[196:199], v[102:105]
	v_mfma_f32_16x16x32_bf16 v[98:101], v[180:183], v[196:199], v[98:101]
	v_mfma_f32_16x16x32_bf16 v[86:89], v[166:169], v[204:207], v[86:89]
	v_mfma_f32_16x16x32_bf16 v[82:85], v[180:183], v[204:207], v[82:85]
	v_mfma_f32_16x16x32_bf16 v[70:73], v[166:169], v[212:215], v[70:73]
	v_mfma_f32_16x16x32_bf16 v[66:69], v[180:183], v[212:215], v[66:69]
	s_setprio 0
	s_barrier
; #define PG8_STAGE(bufoff, gbase, voff) do { _Pragma("unroll") for (int _i = 0; _i < 2; ++_i) \
;         __builtin_amdgcn_global_load_lds((const unsigned*)((const char*)(gbase) + (voff)[_i]), (PG8_LAS unsigned*)(lds + (bufoff) + ldsw + _i * 8192), 16, 0, 0); } while (0)
; #define PG8_LDA(dst, b, h) do { _Pragma("unroll") for (int m = 0; m < 4; ++m) _Pragma("unroll") for (int k = 0; k < 2; ++k) dst[m][k] = *(const PG8_LAS bf16x8*)(lds + PG8_SA(b, h) + aoff + m * 2048 + k * 1024); } while (0)
; #define PG8_MMA(ai, bj, At, Bt) do { __builtin_amdgcn_s_setprio(1); _Pragma("unroll") for (int m = 0; m < 4; ++m) _Pragma("unroll") for (int n = 0; n < 2; ++n) _Pragma("unroll") for (int k = 0; k < 2; ++k) \
;         acc[ai][bj][m][n] = __builtin_amdgcn_mfma_f32_16x16x32_bf16(Bt[n][k], At[m][k], acc[ai][bj][m][n], 0, 0, 0); __builtin_amdgcn_s_setprio(0); } while (0)
; #define PG8_WAIT_V(n) asm volatile("s_waitcnt vmcnt(" #n ")" ::: "memory")
; #define PG8_WAIT_L(n) asm volatile("s_waitcnt lgkmcnt(" #n ")" ::: "memory")
; #define PG8_BAR __builtin_amdgcn_s_barrier()
; #define PG8_SCHED __builtin_amdgcn_sched_barrier(0)
; template <class Epi, class Sched, bool ALIGN_EPI = false, bool SP2 = false>
; __device__ __forceinline__ void gemm_phase(PG8_LAS unsigned char* lds, const Gemm g, const Sched& S, const Epi& E) {
;     ...
;         for (int t = 0; t < nt; t += 2) {
;     ...
;             PG8_LDA(At, 1, 1); PG8_STAGE(PG8_SB(1, 0), b3, voffB); PG8_STAGE(PG8_SB(1, 1), b3 + hstepB, voffB); PG8_STAGE(PG8_SA(1, 0), a3, voffA);
;             PG8_WAIT_V(8); PG8_WAIT_L(0); PG8_BAR; PG8_MMA(1, 0, At, B0); PG8_MMA(1, 1, At, B1); PG8_BAR; PG8_SCHED;
	s_add_i32 s38, s57, s33
	v_lshl_add_u64 v[216:217], v[216:217], 0, s[18:19]
	s_mov_b32 m0, s38
	ds_read_b128 v[184:187], v174 offset:49152
	ds_read_b128 v[188:191], v174 offset:50176
	ds_read_b128 v[192:195], v174 offset:51200
	ds_read_b128 v[196:199], v174 offset:52224
	ds_read_b128 v[200:203], v174 offset:53248
	ds_read_b128 v[204:207], v174 offset:54272
	ds_read_b128 v[208:211], v174 offset:55296
	ds_read_b128 v[212:215], v174 offset:56320
	global_load_lds_dwordx4 v[216:217], off
	s_add_i32 m0, s38, 0x2000
	s_add_u32 s36, s36, 0x40080
	v_lshl_add_u64 v[216:217], v[218:219], 0, s[18:19]
	s_addc_u32 s37, s37, 0
	s_add_i32 s38, s58, s33
	global_load_lds_dwordx4 v[216:217], off
	v_lshl_add_u64 v[216:217], s[36:37], 0, v[148:149]
	s_mov_b32 m0, s38
	s_nop 0
	global_load_lds_dwordx4 v[216:217], off
	v_lshl_add_u64 v[216:217], s[36:37], 0, v[152:153]
	s_add_i32 m0, s38, 0x2000
	s_nop 0
	global_load_lds_dwordx4 v[216:217], off
	v_lshl_add_u64 v[216:217], v[220:221], 0, s[18:19]
	s_mov_b32 m0, s45
	s_nop 0
	global_load_lds_dwordx4 v[216:217], off
	v_lshl_add_u64 v[216:217], v[222:223], 0, s[18:19]
	s_mov_b32 m0, s46
	s_nop 0
	global_load_lds_dwordx4 v[216:217], off
	s_waitcnt vmcnt(8)
	s_waitcnt lgkmcnt(0)
	s_barrier
	s_setprio 1
	s_waitcnt lgkmcnt(0)
	v_mfma_f32_16x16x32_bf16 v[62:65], v[130:133], v[184:187], v[62:65]
	v_mfma_f32_16x16x32_bf16 v[58:61], v[138:141], v[184:187], v[58:61]
	v_mfma_f32_16x16x32_bf16 v[46:49], v[130:133], v[192:195], v[46:49]
	v_mfma_f32_16x16x32_bf16 v[42:45], v[138:141], v[192:195], v[42:45]
	v_mfma_f32_16x16x32_bf16 v[30:33], v[130:133], v[200:203], v[30:33]
	v_mfma_f32_16x16x32_bf16 v[26:29], v[138:141], v[200:203], v[26:29]
	v_mfma_f32_16x16x32_bf16 v[14:17], v[130:133], v[208:211], v[14:17]
	v_mfma_f32_16x16x32_bf16 v[10:13], v[138:141], v[208:211], v[10:13]
	v_mfma_f32_16x16x32_bf16 v[62:65], v[134:137], v[188:191], v[62:65]
	v_mfma_f32_16x16x32_bf16 v[58:61], v[142:145], v[188:191], v[58:61]
	v_mfma_f32_16x16x32_bf16 v[46:49], v[134:137], v[196:199], v[46:49]
	v_mfma_f32_16x16x32_bf16 v[42:45], v[142:145], v[196:199], v[42:45]
	v_mfma_f32_16x16x32_bf16 v[30:33], v[134:137], v[204:207], v[30:33]
	v_mfma_f32_16x16x32_bf16 v[26:29], v[142:145], v[204:207], v[26:29]
	v_mfma_f32_16x16x32_bf16 v[14:17], v[134:137], v[212:215], v[14:17]
	v_mfma_f32_16x16x32_bf16 v[10:13], v[142:145], v[212:215], v[10:13]
	s_setprio 0
	s_setprio 1
	v_mfma_f32_16x16x32_bf16 v[54:57], v[162:165], v[184:187], v[54:57]
	v_mfma_f32_16x16x32_bf16 v[50:53], v[176:179], v[184:187], v[50:53]
	v_mfma_f32_16x16x32_bf16 v[38:41], v[162:165], v[192:195], v[38:41]
	v_mfma_f32_16x16x32_bf16 v[34:37], v[176:179], v[192:195], v[34:37]
	v_mfma_f32_16x16x32_bf16 v[22:25], v[162:165], v[200:203], v[22:25]
	v_mfma_f32_16x16x32_bf16 v[18:21], v[176:179], v[200:203], v[18:21]
	v_mfma_f32_16x16x32_bf16 v[6:9], v[162:165], v[208:211], v[6:9]
	v_mfma_f32_16x16x32_bf16 v[2:5], v[176:179], v[208:211], v[2:5]
	v_mfma_f32_16x16x32_bf16 v[54:57], v[166:169], v[188:191], v[54:57]
	v_mfma_f32_16x16x32_bf16 v[50:53], v[180:183], v[188:191], v[50:53]
	v_mfma_f32_16x16x32_bf16 v[38:41], v[166:169], v[196:199], v[38:41]
	v_mfma_f32_16x16x32_bf16 v[34:37], v[180:183], v[196:199], v[34:37]
	v_mfma_f32_16x16x32_bf16 v[22:25], v[166:169], v[204:207], v[22:25]
	v_mfma_f32_16x16x32_bf16 v[18:21], v[180:183], v[204:207], v[18:21]
	v_mfma_f32_16x16x32_bf16 v[6:9], v[166:169], v[212:215], v[6:9]
	v_mfma_f32_16x16x32_bf16 v[2:5], v[180:183], v[212:215], v[2:5]
	s_setprio 0
	s_barrier
	s_add_i32 s56, s56, 2
	s_add_u32 s34, s34, 0x100
	s_addc_u32 s35, s35, 0
	s_add_u32 s54, s54, 0x100
	s_addc_u32 s55, s55, 0
	s_cmp_gt_u32 s56, 13

; #define PG8_STAGE(bufoff, gbase, voff) do { _Pragma("unroll") for (int _i = 0; _i < 2; ++_i) \
;         __builtin_amdgcn_global_load_lds((const unsigned*)((const char*)(gbase) + (voff)[_i]), (PG8_LAS unsigned*)(lds + (bufoff) + ldsw + _i * 8192), 16, 0, 0); } while (0)
; #define PG8_LDA(dst, b, h) do { _Pragma("unroll") for (int m = 0; m < 4; ++m) _Pragma("unroll") for (int k = 0; k < 2; ++k) dst[m][k] = *(const PG8_LAS bf16x8*)(lds + PG8_SA(b, h) + aoff + m * 2048 + k * 1024); } while (0)
; #define PG8_LDB(dst, b, h) do { _Pragma("unroll") for (int n = 0; n < 2; ++n) _Pragma("unroll") for (int k = 0; k < 2; ++k) dst[n][k] = *(const PG8_LAS bf16x8*)(lds + PG8_SB(b, h) + boff + n * 2048 + k * 1024); } while (0)
; #define PG8_MMA(ai, bj, At, Bt) do { __builtin_amdgcn_s_setprio(1); _Pragma("unroll") for (int m = 0; m < 4; ++m) _Pragma("unroll") for (int n = 0; n < 2; ++n) _Pragma("unroll") for (int k = 0; k < 2; ++k) \
;         acc[ai][bj][m][n] = __builtin_amdgcn_mfma_f32_16x16x32_bf16(Bt[n][k], At[m][k], acc[ai][bj][m][n], 0, 0, 0); __builtin_amdgcn_s_setprio(0); } while (0)
; #define PG8_WAIT_V(n) asm volatile("s_waitcnt vmcnt(" #n ")" ::: "memory")
; #define PG8_BAR __builtin_amdgcn_s_barrier()
; template <class Epi, class Sched, bool ALIGN_EPI = false, bool SP2 = false>
; __device__ __forceinline__ void gemm_phase(PG8_LAS unsigned char* lds, const Gemm g, const Sched& S, const Epi& E) {
;     ...
;         for (int t = 0; t < nt; t += 2) {
;             const bool last = (t == nt - 2);
;             const char* a1 = cA + (size_t)(t + 1) * kstep;
;             const char* a2 = last ? nA : cA + (size_t)(t + 2) * kstep; const char* b2 = last ? nB : cB + (size_t)(t + 2) * kstep;
;             const char* a3 = a2 + kstep; const char* b3 = b2 + kstep;
;             if (last && has_next) S.a_ready(nxt);
;             if constexpr (SP2) {
;             PG8_LDB(B0, 0, 0); PG8_LDB(B1, 0, 1); PG8_SCHED; PG8_LDA(At, 0, 0); PG8_STAGE(PG8_SA(1, 1), a1 + hstepA, voffA);
;             PG8_WAIT_V(8); PG8_WAIT_L(0); PG8_BAR; PG8_MMA(0, 0, At, B0); PG8_MMA(0, 1, At, B1); PG8_BAR; PG8_SCHED;
;             PG8_LDA(At, 0, 1); PG8_STAGE(PG8_SB(0, 0), b2, voffB); PG8_STAGE(PG8_SB(0, 1), b2 + hstepB, voffB); PG8_STAGE(PG8_SA(0, 0), a2, voffA);
;             PG8_WAIT_V(8); PG8_WAIT_L(0); PG8_BAR; PG8_MMA(1, 0, At, B0); PG8_MMA(1, 1, At, B1); PG8_BAR; PG8_SCHED;
.LBB0_690:
	s_ashr_i32 s17, s16, 31
	s_lshl_b64 s[18:19], s[16:17], 19
	s_add_u32 s18, s0, s18
	s_addc_u32 s19, s1, s19
	s_and_b64 s[20:21], s[6:7], exec
	s_cselect_b32 s17, s19, s25
	s_cselect_b32 s46, s18, s24
	s_ashr_i32 s15, s14, 31
	s_lshl_b64 s[20:21], s[14:15], 19
	s_add_u32 s20, s2, s20
	s_addc_u32 s21, s3, s21
	s_and_b64 s[28:29], s[6:7], exec
	s_cselect_b32 s15, s21, s27
	s_cselect_b32 s47, s20, s26
	s_add_u32 s24, s24, 0x40080
	s_addc_u32 s25, s25, 0
	s_add_u32 s48, s26, 0x100
	s_addc_u32 s49, s27, 0
	s_mov_b32 s50, -2
	ds_read_b128 v[148:151], v168
	ds_read_b128 v[152:155], v168 offset:1024
	ds_read_b128 v[156:159], v168 offset:2048
	ds_read_b128 v[160:163], v168 offset:3072
	ds_read_b128 v[174:177], v169
	ds_read_b128 v[178:181], v169 offset:1024
	ds_read_b128 v[182:185], v169 offset:2048
	ds_read_b128 v[186:189], v169 offset:3072
	s_add_u32 s26, s24, 0xfffc0080
	s_addc_u32 s27, s25, -1
	s_cmp_eq_u32 s50, 12
	s_cselect_b32 s29, s17, s27
	s_cselect_b32 s28, s46, s26
	s_cselect_b32 s27, s15, s49
	s_cselect_b32 s26, s47, s48
	v_lshl_add_u64 v[164:165], s[24:25], 0, v[140:141]
	s_add_i32 m0, s23, 0xc000
	ds_read_b128 v[190:193], v170
	ds_read_b128 v[194:197], v170 offset:1024
	ds_read_b128 v[198:201], v170 offset:2048
	ds_read_b128 v[202:205], v170 offset:3072
	ds_read_b128 v[206:209], v170 offset:4096
	ds_read_b128 v[210:213], v170 offset:5120
	ds_read_b128 v[214:217], v170 offset:6144
	ds_read_b128 v[218:221], v170 offset:7168
	global_load_lds_dwordx4 v[164:165], off
	v_lshl_add_u64 v[164:165], s[24:25], 0, v[142:143]
	s_add_i32 m0, s23, 0xe000
	s_nop 0
	global_load_lds_dwordx4 v[164:165], off
	s_waitcnt vmcnt(8)
	s_waitcnt lgkmcnt(0)
	s_barrier
	s_setprio 1
	s_waitcnt lgkmcnt(0)
	v_mfma_f32_16x16x32_bf16 v[126:129], v[148:151], v[190:193], 0
	v_mfma_f32_16x16x32_bf16 v[118:121], v[156:159], v[190:193], 0
	v_mfma_f32_16x16x32_bf16 v[110:113], v[148:151], v[198:201], 0
	v_mfma_f32_16x16x32_bf16 v[102:105], v[156:159], v[198:201], 0
	v_mfma_f32_16x16x32_bf16 v[94:97], v[148:151], v[206:209], 0
	v_mfma_f32_16x16x32_bf16 v[86:89], v[156:159], v[206:209], 0
	v_mfma_f32_16x16x32_bf16 v[78:81], v[148:151], v[214:217], 0
	v_mfma_f32_16x16x32_bf16 v[70:73], v[156:159], v[214:217], 0
	v_mfma_f32_16x16x32_bf16 v[126:129], v[152:155], v[194:197], v[126:129]
	v_mfma_f32_16x16x32_bf16 v[118:121], v[160:163], v[194:197], v[118:121]
	v_mfma_f32_16x16x32_bf16 v[110:113], v[152:155], v[202:205], v[110:113]
	v_mfma_f32_16x16x32_bf16 v[102:105], v[160:163], v[202:205], v[102:105]
	v_mfma_f32_16x16x32_bf16 v[94:97], v[152:155], v[210:213], v[94:97]
	v_mfma_f32_16x16x32_bf16 v[86:89], v[160:163], v[210:213], v[86:89]
	v_mfma_f32_16x16x32_bf16 v[78:81], v[152:155], v[218:221], v[78:81]
	v_mfma_f32_16x16x32_bf16 v[70:73], v[160:163], v[218:221], v[70:73]
	s_setprio 0
	s_setprio 1
	v_mfma_f32_16x16x32_bf16 v[122:125], v[174:177], v[190:193], 0
	v_mfma_f32_16x16x32_bf16 v[114:117], v[182:185], v[190:193], 0
	v_mfma_f32_16x16x32_bf16 v[106:109], v[174:177], v[198:201], 0
	v_mfma_f32_16x16x32_bf16 v[98:101], v[182:185], v[198:201], 0
	v_mfma_f32_16x16x32_bf16 v[90:93], v[174:177], v[206:209], 0
	v_mfma_f32_16x16x32_bf16 v[82:85], v[182:185], v[206:209], 0
	v_mfma_f32_16x16x32_bf16 v[74:77], v[174:177], v[214:217], 0
	v_mfma_f32_16x16x32_bf16 v[66:69], v[182:185], v[214:217], 0
	v_mfma_f32_16x16x32_bf16 v[122:125], v[178:181], v[194:197], v[122:125]
	v_mfma_f32_16x16x32_bf16 v[114:117], v[186:189], v[194:197], v[114:117]
	v_mfma_f32_16x16x32_bf16 v[106:109], v[178:181], v[202:205], v[106:109]
	v_mfma_f32_16x16x32_bf16 v[98:101], v[186:189], v[202:205], v[98:101]
	v_mfma_f32_16x16x32_bf16 v[90:93], v[178:181], v[210:213], v[90:93]
	v_mfma_f32_16x16x32_bf16 v[82:85], v[186:189], v[210:213], v[82:85]
	v_mfma_f32_16x16x32_bf16 v[74:77], v[178:181], v[218:221], v[74:77]
	v_mfma_f32_16x16x32_bf16 v[66:69], v[186:189], v[218:221], v[66:69]
	s_setprio 0
	s_barrier
	s_add_i32 s51, s42, s30
	v_lshl_add_u64 v[164:165], s[26:27], 0, v[134:135]
	s_mov_b32 m0, s51
	ds_read_b128 v[190:193], v170 offset:16384
	ds_read_b128 v[194:197], v170 offset:17408
	ds_read_b128 v[198:201], v170 offset:18432
	ds_read_b128 v[202:205], v170 offset:19456
	ds_read_b128 v[206:209], v170 offset:20480
	ds_read_b128 v[210:213], v170 offset:21504
	ds_read_b128 v[214:217], v170 offset:22528
	ds_read_b128 v[218:221], v170 offset:23552
	global_load_lds_dwordx4 v[164:165], off
	s_add_i32 m0, s51, 0x2000
	s_add_u32 s52, s26, 0x40000
	v_lshl_add_u64 v[222:223], s[26:27], 0, v[130:131]
	s_addc_u32 s53, s27, 0
	s_add_i32 s51, s43, s30
	global_load_lds_dwordx4 v[222:223], off
	v_lshl_add_u64 v[224:225], s[52:53], 0, v[134:135]
	s_mov_b32 m0, s51
	v_lshl_add_u64 v[226:227], s[28:29], 0, v[132:133]
	global_load_lds_dwordx4 v[224:225], off
	v_lshl_add_u64 v[224:225], s[52:53], 0, v[130:131]
	s_add_i32 m0, s51, 0x2000
	s_nop 0
	global_load_lds_dwordx4 v[224:225], off
	v_lshl_add_u64 v[224:225], s[28:29], 0, v[136:137]
	s_mov_b32 m0, s23
	s_nop 0
	global_load_lds_dwordx4 v[224:225], off
	s_mov_b32 m0, s34
	s_nop 0
	global_load_lds_dwordx4 v[226:227], off
	s_waitcnt vmcnt(8)
	s_waitcnt lgkmcnt(0)
	s_barrier
; #define PG8_STAGE(bufoff, gbase, voff) do { _Pragma("unroll") for (int _i = 0; _i < 2; ++_i) \
;         __builtin_amdgcn_global_load_lds((const unsigned*)((const char*)(gbase) + (voff)[_i]), (PG8_LAS unsigned*)(lds + (bufoff) + ldsw + _i * 8192), 16, 0, 0); } while (0)
; #define PG8_LDA(dst, b, h) do { _Pragma("unroll") for (int m = 0; m < 4; ++m) _Pragma("unroll") for (int k = 0; k < 2; ++k) dst[m][k] = *(const PG8_LAS bf16x8*)(lds + PG8_SA(b, h) + aoff + m * 2048 + k * 1024); } while (0)
; #define PG8_LDB(dst, b, h) do { _Pragma("unroll") for (int n = 0; n < 2; ++n) _Pragma("unroll") for (int k = 0; k < 2; ++k) dst[n][k] = *(const PG8_LAS bf16x8*)(lds + PG8_SB(b, h) + boff + n * 2048 + k * 1024); } while (0)
; #define PG8_MMA(ai, bj, At, Bt) do { __builtin_amdgcn_s_setprio(1); _Pragma("unroll") for (int m = 0; m < 4; ++m) _Pragma("unroll") for (int n = 0; n < 2; ++n) _Pragma("unroll") for (int k = 0; k < 2; ++k) \
;         acc[ai][bj][m][n] = __builtin_amdgcn_mfma_f32_16x16x32_bf16(Bt[n][k], At[m][k], acc[ai][bj][m][n], 0, 0, 0); __builtin_amdgcn_s_setprio(0); } while (0)
; #define PG8_WAIT_V(n) asm volatile("s_waitcnt vmcnt(" #n ")" ::: "memory")
; #define PG8_WAIT_L(n) asm volatile("s_waitcnt lgkmcnt(" #n ")" ::: "memory")
; #define PG8_BAR __builtin_amdgcn_s_barrier()
; #define PG8_SCHED __builtin_amdgcn_sched_barrier(0)
; template <class Epi, class Sched, bool ALIGN_EPI = false, bool SP2 = false>
; __device__ __forceinline__ void gemm_phase(PG8_LAS unsigned char* lds, const Gemm g, const Sched& S, const Epi& E) {
;     ...
;             PG8_WAIT_V(8); PG8_WAIT_L(0); PG8_BAR; PG8_MMA(1, 0, At, B0); PG8_MMA(1, 1, At, B1); PG8_BAR; PG8_SCHED;
;             PG8_LDB(B0, 1, 0); PG8_LDB(B1, 1, 1); PG8_SCHED; PG8_LDA(At, 1, 0); PG8_STAGE(PG8_SA(0, 1), a2 + hstepA, voffA);
;             PG8_WAIT_V(8); PG8_WAIT_L(0); PG8_BAR; PG8_MMA(0, 0, At, B0); PG8_MMA(0, 1, At, B1); PG8_BAR; PG8_SCHED;
	s_setprio 1
	s_waitcnt lgkmcnt(0)
	v_mfma_f32_16x16x32_bf16 v[62:65], v[148:151], v[190:193], 0
	v_mfma_f32_16x16x32_bf16 v[54:57], v[156:159], v[190:193], 0
	v_mfma_f32_16x16x32_bf16 v[46:49], v[148:151], v[198:201], 0
	v_mfma_f32_16x16x32_bf16 v[38:41], v[156:159], v[198:201], 0
	v_mfma_f32_16x16x32_bf16 v[30:33], v[148:151], v[206:209], 0
	v_mfma_f32_16x16x32_bf16 v[22:25], v[156:159], v[206:209], 0
	v_mfma_f32_16x16x32_bf16 v[14:17], v[148:151], v[214:217], 0
	v_mfma_f32_16x16x32_bf16 v[6:9], v[156:159], v[214:217], 0
	v_mfma_f32_16x16x32_bf16 v[62:65], v[152:155], v[194:197], v[62:65]
	v_mfma_f32_16x16x32_bf16 v[54:57], v[160:163], v[194:197], v[54:57]
	v_mfma_f32_16x16x32_bf16 v[46:49], v[152:155], v[202:205], v[46:49]
	v_mfma_f32_16x16x32_bf16 v[38:41], v[160:163], v[202:205], v[38:41]
	v_mfma_f32_16x16x32_bf16 v[30:33], v[152:155], v[210:213], v[30:33]
	v_mfma_f32_16x16x32_bf16 v[22:25], v[160:163], v[210:213], v[22:25]
	v_mfma_f32_16x16x32_bf16 v[14:17], v[152:155], v[218:221], v[14:17]
	v_mfma_f32_16x16x32_bf16 v[6:9], v[160:163], v[218:221], v[6:9]
	s_setprio 0
	s_setprio 1
	v_mfma_f32_16x16x32_bf16 v[58:61], v[174:177], v[190:193], 0
	v_mfma_f32_16x16x32_bf16 v[50:53], v[182:185], v[190:193], 0
	v_mfma_f32_16x16x32_bf16 v[42:45], v[174:177], v[198:201], 0
	v_mfma_f32_16x16x32_bf16 v[34:37], v[182:185], v[198:201], 0
	v_mfma_f32_16x16x32_bf16 v[26:29], v[174:177], v[206:209], 0
	v_mfma_f32_16x16x32_bf16 v[18:21], v[182:185], v[206:209], 0
	v_mfma_f32_16x16x32_bf16 v[10:13], v[174:177], v[214:217], 0
	v_mfma_f32_16x16x32_bf16 v[2:5], v[182:185], v[214:217], 0
	v_mfma_f32_16x16x32_bf16 v[58:61], v[178:181], v[194:197], v[58:61]
	v_mfma_f32_16x16x32_bf16 v[50:53], v[186:189], v[194:197], v[50:53]
	v_mfma_f32_16x16x32_bf16 v[42:45], v[178:181], v[202:205], v[42:45]
	v_mfma_f32_16x16x32_bf16 v[34:37], v[186:189], v[202:205], v[34:37]
	v_mfma_f32_16x16x32_bf16 v[26:29], v[178:181], v[210:213], v[26:29]
	v_mfma_f32_16x16x32_bf16 v[18:21], v[186:189], v[210:213], v[18:21]
	v_mfma_f32_16x16x32_bf16 v[10:13], v[178:181], v[218:221], v[10:13]
	v_mfma_f32_16x16x32_bf16 v[2:5], v[186:189], v[218:221], v[2:5]
	s_setprio 0
	s_barrier
	s_add_i32 s51, 0, 0x18000
	s_add_i32 s52, 0, 0x1c000
	v_add_u32_e32 v160, s51, v166
	v_add_u32_e32 v173, s52, v166
	ds_read_b128 v[148:151], v160
	ds_read_b128 v[152:155], v160 offset:1024
	ds_read_b128 v[156:159], v160 offset:2048
	ds_read_b128 v[160:163], v160 offset:3072
	ds_read_b128 v[174:177], v173
	ds_read_b128 v[178:181], v173 offset:1024
	ds_read_b128 v[182:185], v173 offset:2048
	ds_read_b128 v[186:189], v173 offset:3072
	s_add_u32 s28, s28, 0x40000
	s_addc_u32 s29, s29, 0
	s_mov_b32 m0, s35
	v_lshl_add_u64 v[228:229], s[28:29], 0, v[136:137]
	ds_read_b128 v[190:193], v170 offset:32768
	ds_read_b128 v[194:197], v170 offset:33792
	ds_read_b128 v[198:201], v170 offset:34816
	ds_read_b128 v[202:205], v170 offset:35840
	ds_read_b128 v[206:209], v170 offset:36864
	ds_read_b128 v[210:213], v170 offset:37888
	ds_read_b128 v[214:217], v170 offset:38912
	ds_read_b128 v[218:221], v170 offset:39936
	global_load_lds_dwordx4 v[228:229], off
	v_lshl_add_u64 v[228:229], s[28:29], 0, v[132:133]
	s_mov_b32 m0, s36
	s_nop 0
	global_load_lds_dwordx4 v[228:229], off
	s_waitcnt vmcnt(8)
	s_waitcnt lgkmcnt(0)
	s_barrier
	s_setprio 1
	s_waitcnt lgkmcnt(0)
	v_mfma_f32_16x16x32_bf16 v[126:129], v[148:151], v[190:193], v[126:129]
	v_mfma_f32_16x16x32_bf16 v[118:121], v[156:159], v[190:193], v[118:121]
	v_mfma_f32_16x16x32_bf16 v[110:113], v[148:151], v[198:201], v[110:113]
	v_mfma_f32_16x16x32_bf16 v[102:105], v[156:159], v[198:201], v[102:105]
	v_mfma_f32_16x16x32_bf16 v[94:97], v[148:151], v[206:209], v[94:97]
	v_mfma_f32_16x16x32_bf16 v[86:89], v[156:159], v[206:209], v[86:89]
	v_mfma_f32_16x16x32_bf16 v[78:81], v[148:151], v[214:217], v[78:81]
	v_mfma_f32_16x16x32_bf16 v[70:73], v[156:159], v[214:217], v[70:73]
	v_mfma_f32_16x16x32_bf16 v[126:129], v[152:155], v[194:197], v[126:129]
	v_mfma_f32_16x16x32_bf16 v[118:121], v[160:163], v[194:197], v[118:121]
	v_mfma_f32_16x16x32_bf16 v[110:113], v[152:155], v[202:205], v[110:113]
	v_mfma_f32_16x16x32_bf16 v[102:105], v[160:163], v[202:205], v[102:105]
	v_mfma_f32_16x16x32_bf16 v[94:97], v[152:155], v[210:213], v[94:97]
	v_mfma_f32_16x16x32_bf16 v[86:89], v[160:163], v[210:213], v[86:89]
	v_mfma_f32_16x16x32_bf16 v[78:81], v[152:155], v[218:221], v[78:81]
	v_mfma_f32_16x16x32_bf16 v[70:73], v[160:163], v[218:221], v[70:73]
	s_setprio 0
	s_setprio 1
	v_mfma_f32_16x16x32_bf16 v[122:125], v[174:177], v[190:193], v[122:125]
	v_mfma_f32_16x16x32_bf16 v[114:117], v[182:185], v[190:193], v[114:117]
	v_mfma_f32_16x16x32_bf16 v[106:109], v[174:177], v[198:201], v[106:109]
	v_mfma_f32_16x16x32_bf16 v[98:101], v[182:185], v[198:201], v[98:101]
	v_mfma_f32_16x16x32_bf16 v[90:93], v[174:177], v[206:209], v[90:93]
	v_mfma_f32_16x16x32_bf16 v[82:85], v[182:185], v[206:209], v[82:85]
	v_mfma_f32_16x16x32_bf16 v[74:77], v[174:177], v[214:217], v[74:77]
	v_mfma_f32_16x16x32_bf16 v[66:69], v[182:185], v[214:217], v[66:69]
	v_mfma_f32_16x16x32_bf16 v[122:125], v[178:181], v[194:197], v[122:125]
	v_mfma_f32_16x16x32_bf16 v[114:117], v[186:189], v[194:197], v[114:117]
	v_mfma_f32_16x16x32_bf16 v[106:109], v[178:181], v[202:205], v[106:109]
	v_mfma_f32_16x16x32_bf16 v[98:101], v[186:189], v[202:205], v[98:101]
	v_mfma_f32_16x16x32_bf16 v[90:93], v[178:181], v[210:213], v[90:93]
	v_mfma_f32_16x16x32_bf16 v[82:85], v[186:189], v[210:213], v[82:85]
	v_mfma_f32_16x16x32_bf16 v[74:77], v[178:181], v[218:221], v[74:77]
	v_mfma_f32_16x16x32_bf16 v[66:69], v[186:189], v[218:221], v[66:69]
	s_setprio 0
	s_barrier
; #define PG8_STAGE(bufoff, gbase, voff) do { _Pragma("unroll") for (int _i = 0; _i < 2; ++_i) \
;         __builtin_amdgcn_global_load_lds((const unsigned*)((const char*)(gbase) + (voff)[_i]), (PG8_LAS unsigned*)(lds + (bufoff) + ldsw + _i * 8192), 16, 0, 0); } while (0)
; #define PG8_LDA(dst, b, h) do { _Pragma("unroll") for (int m = 0; m < 4; ++m) _Pragma("unroll") for (int k = 0; k < 2; ++k) dst[m][k] = *(const PG8_LAS bf16x8*)(lds + PG8_SA(b, h) + aoff + m * 2048 + k * 1024); } while (0)
; #define PG8_MMA(ai, bj, At, Bt) do { __builtin_amdgcn_s_setprio(1); _Pragma("unroll") for (int m = 0; m < 4; ++m) _Pragma("unroll") for (int n = 0; n < 2; ++n) _Pragma("unroll") for (int k = 0; k < 2; ++k) \
;         acc[ai][bj][m][n] = __builtin_amdgcn_mfma_f32_16x16x32_bf16(Bt[n][k], At[m][k], acc[ai][bj][m][n], 0, 0, 0); __builtin_amdgcn_s_setprio(0); } while (0)
; #define PG8_WAIT_V(n) asm volatile("s_waitcnt vmcnt(" #n ")" ::: "memory")
; #define PG8_WAIT_L(n) asm volatile("s_waitcnt lgkmcnt(" #n ")" ::: "memory")
; #define PG8_BAR __builtin_amdgcn_s_barrier()
; #define PG8_SCHED __builtin_amdgcn_sched_barrier(0)
; template <class Epi, class Sched, bool ALIGN_EPI = false, bool SP2 = false>
; __device__ __forceinline__ void gemm_phase(PG8_LAS unsigned char* lds, const Gemm g, const Sched& S, const Epi& E) {
;     ...
;         for (int t = 0; t < nt; t += 2) {
;     ...
;             PG8_LDA(At, 1, 1); PG8_STAGE(PG8_SB(1, 0), b3, voffB); PG8_STAGE(PG8_SB(1, 1), b3 + hstepB, voffB); PG8_STAGE(PG8_SA(1, 0), a3, voffA);
;             PG8_WAIT_V(8); PG8_WAIT_L(0); PG8_BAR; PG8_MMA(1, 0, At, B0); PG8_MMA(1, 1, At, B1); PG8_BAR; PG8_SCHED;
	s_add_i32 s28, s51, s30
	v_lshl_add_u64 v[164:165], v[164:165], 0, s[10:11]
	s_mov_b32 m0, s28
	ds_read_b128 v[190:193], v170 offset:49152
	ds_read_b128 v[194:197], v170 offset:50176
	ds_read_b128 v[198:201], v170 offset:51200
	ds_read_b128 v[202:205], v170 offset:52224
	ds_read_b128 v[206:209], v170 offset:53248
	ds_read_b128 v[210:213], v170 offset:54272
	ds_read_b128 v[214:217], v170 offset:55296
	ds_read_b128 v[218:221], v170 offset:56320
	global_load_lds_dwordx4 v[164:165], off
	s_add_i32 m0, s28, 0x2000
	s_add_u32 s26, s26, 0x40080
	v_lshl_add_u64 v[164:165], v[222:223], 0, s[10:11]
	s_addc_u32 s27, s27, 0
	s_add_i32 s28, s52, s30
	global_load_lds_dwordx4 v[164:165], off
	v_lshl_add_u64 v[164:165], s[26:27], 0, v[134:135]
	s_mov_b32 m0, s28
	s_nop 0
	global_load_lds_dwordx4 v[164:165], off
	v_lshl_add_u64 v[164:165], s[26:27], 0, v[130:131]
	s_add_i32 m0, s28, 0x2000
	s_nop 0
	global_load_lds_dwordx4 v[164:165], off
	v_lshl_add_u64 v[164:165], v[224:225], 0, s[10:11]
	s_mov_b32 m0, s38
	s_nop 0
	global_load_lds_dwordx4 v[164:165], off
	v_lshl_add_u64 v[164:165], v[226:227], 0, s[10:11]
	s_mov_b32 m0, s39
	s_nop 0
	global_load_lds_dwordx4 v[164:165], off
	s_waitcnt vmcnt(8)
	s_waitcnt lgkmcnt(0)
	s_barrier
	s_setprio 1
	s_waitcnt lgkmcnt(0)
	v_mfma_f32_16x16x32_bf16 v[62:65], v[148:151], v[190:193], v[62:65]
	v_mfma_f32_16x16x32_bf16 v[54:57], v[156:159], v[190:193], v[54:57]
	v_mfma_f32_16x16x32_bf16 v[46:49], v[148:151], v[198:201], v[46:49]
	v_mfma_f32_16x16x32_bf16 v[38:41], v[156:159], v[198:201], v[38:41]
	v_mfma_f32_16x16x32_bf16 v[30:33], v[148:151], v[206:209], v[30:33]
	v_mfma_f32_16x16x32_bf16 v[22:25], v[156:159], v[206:209], v[22:25]
	v_mfma_f32_16x16x32_bf16 v[14:17], v[148:151], v[214:217], v[14:17]
	v_mfma_f32_16x16x32_bf16 v[6:9], v[156:159], v[214:217], v[6:9]
	v_mfma_f32_16x16x32_bf16 v[62:65], v[152:155], v[194:197], v[62:65]
	v_mfma_f32_16x16x32_bf16 v[54:57], v[160:163], v[194:197], v[54:57]
	v_mfma_f32_16x16x32_bf16 v[46:49], v[152:155], v[202:205], v[46:49]
	v_mfma_f32_16x16x32_bf16 v[38:41], v[160:163], v[202:205], v[38:41]
	v_mfma_f32_16x16x32_bf16 v[30:33], v[152:155], v[210:213], v[30:33]
	v_mfma_f32_16x16x32_bf16 v[22:25], v[160:163], v[210:213], v[22:25]
	v_mfma_f32_16x16x32_bf16 v[14:17], v[152:155], v[218:221], v[14:17]
	v_mfma_f32_16x16x32_bf16 v[6:9], v[160:163], v[218:221], v[6:9]
	s_setprio 0
	s_setprio 1
	v_mfma_f32_16x16x32_bf16 v[58:61], v[174:177], v[190:193], v[58:61]
	v_mfma_f32_16x16x32_bf16 v[50:53], v[182:185], v[190:193], v[50:53]
	v_mfma_f32_16x16x32_bf16 v[42:45], v[174:177], v[198:201], v[42:45]
	v_mfma_f32_16x16x32_bf16 v[34:37], v[182:185], v[198:201], v[34:37]
	v_mfma_f32_16x16x32_bf16 v[26:29], v[174:177], v[206:209], v[26:29]
	v_mfma_f32_16x16x32_bf16 v[18:21], v[182:185], v[206:209], v[18:21]
	v_mfma_f32_16x16x32_bf16 v[10:13], v[174:177], v[214:217], v[10:13]
	v_mfma_f32_16x16x32_bf16 v[2:5], v[182:185], v[214:217], v[2:5]
	v_mfma_f32_16x16x32_bf16 v[58:61], v[178:181], v[194:197], v[58:61]
	v_mfma_f32_16x16x32_bf16 v[50:53], v[186:189], v[194:197], v[50:53]
	v_mfma_f32_16x16x32_bf16 v[42:45], v[178:181], v[202:205], v[42:45]
	v_mfma_f32_16x16x32_bf16 v[34:37], v[186:189], v[202:205], v[34:37]
	v_mfma_f32_16x16x32_bf16 v[26:29], v[178:181], v[210:213], v[26:29]
	v_mfma_f32_16x16x32_bf16 v[18:21], v[186:189], v[210:213], v[18:21]
	v_mfma_f32_16x16x32_bf16 v[10:13], v[178:181], v[218:221], v[10:13]
	v_mfma_f32_16x16x32_bf16 v[2:5], v[186:189], v[218:221], v[2:5]
	s_setprio 0
	s_barrier
	s_add_i32 s50, s50, 2
	s_add_u32 s24, s24, 0x100
	s_addc_u32 s25, s25, 0
	s_add_u32 s48, s48, 0x100
	s_addc_u32 s49, s49, 0
	s_cmp_gt_u32 s50, 13

; #define PG8_STAGE(bufoff, gbase, voff) do { _Pragma("unroll") for (int _i = 0; _i < 2; ++_i) \
;         __builtin_amdgcn_global_load_lds((const unsigned*)((const char*)(gbase) + (voff)[_i]), (PG8_LAS unsigned*)(lds + (bufoff) + ldsw + _i * 8192), 16, 0, 0); } while (0)
; #define PG8_LDA(dst, b, h) do { _Pragma("unroll") for (int m = 0; m < 4; ++m) _Pragma("unroll") for (int k = 0; k < 2; ++k) dst[m][k] = *(const PG8_LAS bf16x8*)(lds + PG8_SA(b, h) + aoff + m * 2048 + k * 1024); } while (0)
; #define PG8_LDB(dst, b, h) do { _Pragma("unroll") for (int n = 0; n < 2; ++n) _Pragma("unroll") for (int k = 0; k < 2; ++k) dst[n][k] = *(const PG8_LAS bf16x8*)(lds + PG8_SB(b, h) + boff + n * 2048 + k * 1024); } while (0)
; #define PG8_MMA(ai, bj, At, Bt) do { __builtin_amdgcn_s_setprio(1); _Pragma("unroll") for (int m = 0; m < 4; ++m) _Pragma("unroll") for (int n = 0; n < 2; ++n) _Pragma("unroll") for (int k = 0; k < 2; ++k) \
;         acc[ai][bj][m][n] = __builtin_amdgcn_mfma_f32_16x16x32_bf16(Bt[n][k], At[m][k], acc[ai][bj][m][n], 0, 0, 0); __builtin_amdgcn_s_setprio(0); } while (0)
; #define PG8_WAIT_V(n) asm volatile("s_waitcnt vmcnt(" #n ")" ::: "memory")
; #define PG8_BAR __builtin_amdgcn_s_barrier()
; template <class Epi, class Sched, bool ALIGN_EPI = false, bool SP2 = false>
; __device__ __forceinline__ void gemm_phase(PG8_LAS unsigned char* lds, const Gemm g, const Sched& S, const Epi& E) {
;     ...
;         for (int t = 0; t < nt; t += 2) {
;             const bool last = (t == nt - 2);
;             const char* a1 = cA + (size_t)(t + 1) * kstep;
;             const char* a2 = last ? nA : cA + (size_t)(t + 2) * kstep; const char* b2 = last ? nB : cB + (size_t)(t + 2) * kstep;
;             const char* a3 = a2 + kstep; const char* b3 = b2 + kstep;
;             if (last && has_next) S.a_ready(nxt);
;             if constexpr (SP2) {
;             PG8_LDB(B0, 0, 0); PG8_LDB(B1, 0, 1); PG8_SCHED; PG8_LDA(At, 0, 0); PG8_STAGE(PG8_SA(1, 1), a1 + hstepA, voffA);
;             PG8_WAIT_V(8); PG8_WAIT_L(0); PG8_BAR; PG8_MMA(0, 0, At, B0); PG8_MMA(0, 1, At, B1); PG8_BAR; PG8_SCHED;
;             PG8_LDA(At, 0, 1); PG8_STAGE(PG8_SB(0, 0), b2, voffB); PG8_STAGE(PG8_SB(0, 1), b2 + hstepB, voffB); PG8_STAGE(PG8_SA(0, 0), a2, voffA);
;             PG8_WAIT_V(8); PG8_WAIT_L(0); PG8_BAR; PG8_MMA(1, 0, At, B0); PG8_MMA(1, 1, At, B1); PG8_BAR; PG8_SCHED;
.LBB0_775:
	s_add_u32 s4, s28, 0x100
	s_addc_u32 s53, s29, 0
	s_mov_b32 s54, -2
	s_waitcnt lgkmcnt(0)
	ds_read_b128 v[130:133], v164
	ds_read_b128 v[134:137], v164 offset:1024
	ds_read_b128 v[154:157], v164 offset:2048
	ds_read_b128 v[158:161], v164 offset:3072
	ds_read_b128 v[168:171], v165
	ds_read_b128 v[172:175], v165 offset:1024
	ds_read_b128 v[176:179], v165 offset:2048
	ds_read_b128 v[180:183], v165 offset:3072
	s_add_u32 s28, s26, 0x100
	s_addc_u32 s29, s27, 0
	s_cmp_eq_u32 s54, 40
	s_cselect_b32 s35, s13, s29
	s_cselect_b32 s34, s12, s28
	s_cselect_b32 s31, s25, s53
	s_cselect_b32 s30, s24, s4
	v_lshl_add_u64 v[216:217], s[26:27], 0, v[146:147]
	s_add_i32 m0, s1, 0xc000
	ds_read_b128 v[184:187], v166
	ds_read_b128 v[188:191], v166 offset:1024
	ds_read_b128 v[192:195], v166 offset:2048
	ds_read_b128 v[196:199], v166 offset:3072
	ds_read_b128 v[200:203], v166 offset:4096
	ds_read_b128 v[204:207], v166 offset:5120
	ds_read_b128 v[208:211], v166 offset:6144
	ds_read_b128 v[212:215], v166 offset:7168
	global_load_lds_dwordx4 v[216:217], off
	v_lshl_add_u64 v[216:217], s[26:27], 0, v[148:149]
	s_add_i32 m0, s1, 0xe000
	s_nop 0
	global_load_lds_dwordx4 v[216:217], off
	s_waitcnt vmcnt(8)
	s_waitcnt lgkmcnt(0)
	s_barrier
	s_setprio 1
	s_waitcnt lgkmcnt(0)
	v_mfma_f32_16x16x32_bf16 v[126:129], v[130:133], v[184:187], 0
	v_mfma_f32_16x16x32_bf16 v[122:125], v[154:157], v[184:187], 0
	v_mfma_f32_16x16x32_bf16 v[110:113], v[130:133], v[192:195], 0
	v_mfma_f32_16x16x32_bf16 v[106:109], v[154:157], v[192:195], 0
	v_mfma_f32_16x16x32_bf16 v[94:97], v[130:133], v[200:203], 0
	v_mfma_f32_16x16x32_bf16 v[90:93], v[154:157], v[200:203], 0
	v_mfma_f32_16x16x32_bf16 v[78:81], v[130:133], v[208:211], 0
	v_mfma_f32_16x16x32_bf16 v[74:77], v[154:157], v[208:211], 0
	v_mfma_f32_16x16x32_bf16 v[126:129], v[134:137], v[188:191], v[126:129]
	v_mfma_f32_16x16x32_bf16 v[122:125], v[158:161], v[188:191], v[122:125]
	v_mfma_f32_16x16x32_bf16 v[110:113], v[134:137], v[196:199], v[110:113]
	v_mfma_f32_16x16x32_bf16 v[106:109], v[158:161], v[196:199], v[106:109]
	v_mfma_f32_16x16x32_bf16 v[94:97], v[134:137], v[204:207], v[94:97]
	v_mfma_f32_16x16x32_bf16 v[90:93], v[158:161], v[204:207], v[90:93]
	v_mfma_f32_16x16x32_bf16 v[78:81], v[134:137], v[212:215], v[78:81]
	v_mfma_f32_16x16x32_bf16 v[74:77], v[158:161], v[212:215], v[74:77]
	s_setprio 0
	s_setprio 1
	v_mfma_f32_16x16x32_bf16 v[118:121], v[168:171], v[184:187], 0
	v_mfma_f32_16x16x32_bf16 v[114:117], v[176:179], v[184:187], 0
	v_mfma_f32_16x16x32_bf16 v[102:105], v[168:171], v[192:195], 0
	v_mfma_f32_16x16x32_bf16 v[98:101], v[176:179], v[192:195], 0
	v_mfma_f32_16x16x32_bf16 v[86:89], v[168:171], v[200:203], 0
	v_mfma_f32_16x16x32_bf16 v[82:85], v[176:179], v[200:203], 0
	v_mfma_f32_16x16x32_bf16 v[70:73], v[168:171], v[208:211], 0
	v_mfma_f32_16x16x32_bf16 v[66:69], v[176:179], v[208:211], 0
	v_mfma_f32_16x16x32_bf16 v[118:121], v[172:175], v[188:191], v[118:121]
	v_mfma_f32_16x16x32_bf16 v[114:117], v[180:183], v[188:191], v[114:117]
	v_mfma_f32_16x16x32_bf16 v[102:105], v[172:175], v[196:199], v[102:105]
	v_mfma_f32_16x16x32_bf16 v[98:101], v[180:183], v[196:199], v[98:101]
	v_mfma_f32_16x16x32_bf16 v[86:89], v[172:175], v[204:207], v[86:89]
	v_mfma_f32_16x16x32_bf16 v[82:85], v[180:183], v[204:207], v[82:85]
	v_mfma_f32_16x16x32_bf16 v[70:73], v[172:175], v[212:215], v[70:73]
	v_mfma_f32_16x16x32_bf16 v[66:69], v[180:183], v[212:215], v[66:69]
	s_setprio 0
	s_barrier
	s_add_i32 s26, s46, s0
	v_lshl_add_u64 v[216:217], s[30:31], 0, v[140:141]
	s_mov_b32 m0, s26
	ds_read_b128 v[184:187], v166 offset:16384
	ds_read_b128 v[188:191], v166 offset:17408
	ds_read_b128 v[192:195], v166 offset:18432
	ds_read_b128 v[196:199], v166 offset:19456
	ds_read_b128 v[200:203], v166 offset:20480
	ds_read_b128 v[204:207], v166 offset:21504
	ds_read_b128 v[208:211], v166 offset:22528
	ds_read_b128 v[212:215], v166 offset:23552
	global_load_lds_dwordx4 v[216:217], off
	s_add_i32 m0, s26, 0x2000
	s_add_u32 s26, s30, 0xb0000
	v_lshl_add_u64 v[218:219], s[30:31], 0, v[144:145]
	s_addc_u32 s27, s31, 0
	s_add_i32 s55, s47, s0
	global_load_lds_dwordx4 v[218:219], off
	v_lshl_add_u64 v[220:221], s[26:27], 0, v[140:141]
	s_mov_b32 m0, s55
	v_lshl_add_u64 v[222:223], s[34:35], 0, v[142:143]
	global_load_lds_dwordx4 v[220:221], off
	v_lshl_add_u64 v[220:221], s[26:27], 0, v[144:145]
	s_add_i32 m0, s55, 0x2000
	s_nop 0
	global_load_lds_dwordx4 v[220:221], off
	v_lshl_add_u64 v[220:221], s[34:35], 0, v[138:139]
	s_mov_b32 m0, s1
	s_nop 0
	global_load_lds_dwordx4 v[220:221], off
	s_mov_b32 m0, s37
	s_nop 0
	global_load_lds_dwordx4 v[222:223], off
	s_waitcnt vmcnt(8)
	s_waitcnt lgkmcnt(0)
	s_barrier
; #define PG8_STAGE(bufoff, gbase, voff) do { _Pragma("unroll") for (int _i = 0; _i < 2; ++_i) \
;         __builtin_amdgcn_global_load_lds((const unsigned*)((const char*)(gbase) + (voff)[_i]), (PG8_LAS unsigned*)(lds + (bufoff) + ldsw + _i * 8192), 16, 0, 0); } while (0)
; #define PG8_LDA(dst, b, h) do { _Pragma("unroll") for (int m = 0; m < 4; ++m) _Pragma("unroll") for (int k = 0; k < 2; ++k) dst[m][k] = *(const PG8_LAS bf16x8*)(lds + PG8_SA(b, h) + aoff + m * 2048 + k * 1024); } while (0)
; #define PG8_LDB(dst, b, h) do { _Pragma("unroll") for (int n = 0; n < 2; ++n) _Pragma("unroll") for (int k = 0; k < 2; ++k) dst[n][k] = *(const PG8_LAS bf16x8*)(lds + PG8_SB(b, h) + boff + n * 2048 + k * 1024); } while (0)
; #define PG8_MMA(ai, bj, At, Bt) do { __builtin_amdgcn_s_setprio(1); _Pragma("unroll") for (int m = 0; m < 4; ++m) _Pragma("unroll") for (int n = 0; n < 2; ++n) _Pragma("unroll") for (int k = 0; k < 2; ++k) \
;         acc[ai][bj][m][n] = __builtin_amdgcn_mfma_f32_16x16x32_bf16(Bt[n][k], At[m][k], acc[ai][bj][m][n], 0, 0, 0); __builtin_amdgcn_s_setprio(0); } while (0)
; #define PG8_WAIT_V(n) asm volatile("s_waitcnt vmcnt(" #n ")" ::: "memory")
; #define PG8_WAIT_L(n) asm volatile("s_waitcnt lgkmcnt(" #n ")" ::: "memory")
; #define PG8_BAR __builtin_amdgcn_s_barrier()
; #define PG8_SCHED __builtin_amdgcn_sched_barrier(0)
; template <class Epi, class Sched, bool ALIGN_EPI = false, bool SP2 = false>
; __device__ __forceinline__ void gemm_phase(PG8_LAS unsigned char* lds, const Gemm g, const Sched& S, const Epi& E) {
;     ...
;             PG8_WAIT_V(8); PG8_WAIT_L(0); PG8_BAR; PG8_MMA(1, 0, At, B0); PG8_MMA(1, 1, At, B1); PG8_BAR; PG8_SCHED;
;             PG8_LDB(B0, 1, 0); PG8_LDB(B1, 1, 1); PG8_SCHED; PG8_LDA(At, 1, 0); PG8_STAGE(PG8_SA(0, 1), a2 + hstepA, voffA);
;             PG8_WAIT_V(8); PG8_WAIT_L(0); PG8_BAR; PG8_MMA(0, 0, At, B0); PG8_MMA(0, 1, At, B1); PG8_BAR; PG8_SCHED;
	s_setprio 1
	s_waitcnt lgkmcnt(0)
	v_mfma_f32_16x16x32_bf16 v[62:65], v[130:133], v[184:187], 0
	v_mfma_f32_16x16x32_bf16 v[58:61], v[154:157], v[184:187], 0
	v_mfma_f32_16x16x32_bf16 v[46:49], v[130:133], v[192:195], 0
	v_mfma_f32_16x16x32_bf16 v[42:45], v[154:157], v[192:195], 0
	v_mfma_f32_16x16x32_bf16 v[30:33], v[130:133], v[200:203], 0
	v_mfma_f32_16x16x32_bf16 v[26:29], v[154:157], v[200:203], 0
	v_mfma_f32_16x16x32_bf16 v[14:17], v[130:133], v[208:211], 0
	v_mfma_f32_16x16x32_bf16 v[10:13], v[154:157], v[208:211], 0
	v_mfma_f32_16x16x32_bf16 v[62:65], v[134:137], v[188:191], v[62:65]
	v_mfma_f32_16x16x32_bf16 v[58:61], v[158:161], v[188:191], v[58:61]
	v_mfma_f32_16x16x32_bf16 v[46:49], v[134:137], v[196:199], v[46:49]
	v_mfma_f32_16x16x32_bf16 v[42:45], v[158:161], v[196:199], v[42:45]
	v_mfma_f32_16x16x32_bf16 v[30:33], v[134:137], v[204:207], v[30:33]
	v_mfma_f32_16x16x32_bf16 v[26:29], v[158:161], v[204:207], v[26:29]
	v_mfma_f32_16x16x32_bf16 v[14:17], v[134:137], v[212:215], v[14:17]
	v_mfma_f32_16x16x32_bf16 v[10:13], v[158:161], v[212:215], v[10:13]
	s_setprio 0
	s_setprio 1
	v_mfma_f32_16x16x32_bf16 v[54:57], v[168:171], v[184:187], 0
	v_mfma_f32_16x16x32_bf16 v[50:53], v[176:179], v[184:187], 0
	v_mfma_f32_16x16x32_bf16 v[38:41], v[168:171], v[192:195], 0
	v_mfma_f32_16x16x32_bf16 v[34:37], v[176:179], v[192:195], 0
	v_mfma_f32_16x16x32_bf16 v[22:25], v[168:171], v[200:203], 0
	v_mfma_f32_16x16x32_bf16 v[18:21], v[176:179], v[200:203], 0
	v_mfma_f32_16x16x32_bf16 v[6:9], v[168:171], v[208:211], 0
	v_mfma_f32_16x16x32_bf16 v[2:5], v[176:179], v[208:211], 0
	v_mfma_f32_16x16x32_bf16 v[54:57], v[172:175], v[188:191], v[54:57]
	v_mfma_f32_16x16x32_bf16 v[50:53], v[180:183], v[188:191], v[50:53]
	v_mfma_f32_16x16x32_bf16 v[38:41], v[172:175], v[196:199], v[38:41]
	v_mfma_f32_16x16x32_bf16 v[34:37], v[180:183], v[196:199], v[34:37]
	v_mfma_f32_16x16x32_bf16 v[22:25], v[172:175], v[204:207], v[22:25]
	v_mfma_f32_16x16x32_bf16 v[18:21], v[180:183], v[204:207], v[18:21]
	v_mfma_f32_16x16x32_bf16 v[6:9], v[172:175], v[212:215], v[6:9]
	v_mfma_f32_16x16x32_bf16 v[2:5], v[180:183], v[212:215], v[2:5]
	s_setprio 0
	s_barrier
	s_add_i32 s55, 0, 0x18000
	s_add_i32 s56, 0, 0x1c000
	v_add_u32_e32 v158, s55, v162
	v_add_u32_e32 v180, s56, v162
	ds_read_b128 v[130:133], v158
	ds_read_b128 v[134:137], v158 offset:1024
	ds_read_b128 v[154:157], v158 offset:2048
	ds_read_b128 v[158:161], v158 offset:3072
	ds_read_b128 v[168:171], v180
	ds_read_b128 v[172:175], v180 offset:1024
	ds_read_b128 v[176:179], v180 offset:2048
	ds_read_b128 v[180:183], v180 offset:3072
	s_add_u32 s26, s34, 0xb0000
	s_addc_u32 s27, s35, 0
	s_mov_b32 m0, s38
	v_lshl_add_u64 v[224:225], s[26:27], 0, v[138:139]
	ds_read_b128 v[184:187], v166 offset:32768
	ds_read_b128 v[188:191], v166 offset:33792
	ds_read_b128 v[192:195], v166 offset:34816
	ds_read_b128 v[196:199], v166 offset:35840
	ds_read_b128 v[200:203], v166 offset:36864
	ds_read_b128 v[204:207], v166 offset:37888
	ds_read_b128 v[208:211], v166 offset:38912
	ds_read_b128 v[212:215], v166 offset:39936
	global_load_lds_dwordx4 v[224:225], off
	v_lshl_add_u64 v[224:225], s[26:27], 0, v[142:143]
	s_mov_b32 m0, s39
	s_nop 0
	global_load_lds_dwordx4 v[224:225], off
	s_waitcnt vmcnt(8)
	s_waitcnt lgkmcnt(0)
	s_barrier
	s_setprio 1
	s_waitcnt lgkmcnt(0)
	v_mfma_f32_16x16x32_bf16 v[126:129], v[130:133], v[184:187], v[126:129]
	v_mfma_f32_16x16x32_bf16 v[122:125], v[154:157], v[184:187], v[122:125]
	v_mfma_f32_16x16x32_bf16 v[110:113], v[130:133], v[192:195], v[110:113]
	v_mfma_f32_16x16x32_bf16 v[106:109], v[154:157], v[192:195], v[106:109]
	v_mfma_f32_16x16x32_bf16 v[94:97], v[130:133], v[200:203], v[94:97]
	v_mfma_f32_16x16x32_bf16 v[90:93], v[154:157], v[200:203], v[90:93]
	v_mfma_f32_16x16x32_bf16 v[78:81], v[130:133], v[208:211], v[78:81]
	v_mfma_f32_16x16x32_bf16 v[74:77], v[154:157], v[208:211], v[74:77]
	v_mfma_f32_16x16x32_bf16 v[126:129], v[134:137], v[188:191], v[126:129]
	v_mfma_f32_16x16x32_bf16 v[122:125], v[158:161], v[188:191], v[122:125]
	v_mfma_f32_16x16x32_bf16 v[110:113], v[134:137], v[196:199], v[110:113]
	v_mfma_f32_16x16x32_bf16 v[106:109], v[158:161], v[196:199], v[106:109]
	v_mfma_f32_16x16x32_bf16 v[94:97], v[134:137], v[204:207], v[94:97]
	v_mfma_f32_16x16x32_bf16 v[90:93], v[158:161], v[204:207], v[90:93]
	v_mfma_f32_16x16x32_bf16 v[78:81], v[134:137], v[212:215], v[78:81]
	v_mfma_f32_16x16x32_bf16 v[74:77], v[158:161], v[212:215], v[74:77]
	s_setprio 0
	s_setprio 1
	v_mfma_f32_16x16x32_bf16 v[118:121], v[168:171], v[184:187], v[118:121]
	v_mfma_f32_16x16x32_bf16 v[114:117], v[176:179], v[184:187], v[114:117]
	v_mfma_f32_16x16x32_bf16 v[102:105], v[168:171], v[192:195], v[102:105]
	v_mfma_f32_16x16x32_bf16 v[98:101], v[176:179], v[192:195], v[98:101]
	v_mfma_f32_16x16x32_bf16 v[86:89], v[168:171], v[200:203], v[86:89]
	v_mfma_f32_16x16x32_bf16 v[82:85], v[176:179], v[200:203], v[82:85]
	v_mfma_f32_16x16x32_bf16 v[70:73], v[168:171], v[208:211], v[70:73]
	v_mfma_f32_16x16x32_bf16 v[66:69], v[176:179], v[208:211], v[66:69]
	v_mfma_f32_16x16x32_bf16 v[118:121], v[172:175], v[188:191], v[118:121]
	v_mfma_f32_16x16x32_bf16 v[114:117], v[180:183], v[188:191], v[114:117]
	v_mfma_f32_16x16x32_bf16 v[102:105], v[172:175], v[196:199], v[102:105]
	v_mfma_f32_16x16x32_bf16 v[98:101], v[180:183], v[196:199], v[98:101]
	v_mfma_f32_16x16x32_bf16 v[86:89], v[172:175], v[204:207], v[86:89]
	v_mfma_f32_16x16x32_bf16 v[82:85], v[180:183], v[204:207], v[82:85]
	v_mfma_f32_16x16x32_bf16 v[70:73], v[172:175], v[212:215], v[70:73]
	v_mfma_f32_16x16x32_bf16 v[66:69], v[180:183], v[212:215], v[66:69]
	s_setprio 0
	s_barrier
; #define PG8_STAGE(bufoff, gbase, voff) do { _Pragma("unroll") for (int _i = 0; _i < 2; ++_i) \
;         __builtin_amdgcn_global_load_lds((const unsigned*)((const char*)(gbase) + (voff)[_i]), (PG8_LAS unsigned*)(lds + (bufoff) + ldsw + _i * 8192), 16, 0, 0); } while (0)
; #define PG8_LDA(dst, b, h) do { _Pragma("unroll") for (int m = 0; m < 4; ++m) _Pragma("unroll") for (int k = 0; k < 2; ++k) dst[m][k] = *(const PG8_LAS bf16x8*)(lds + PG8_SA(b, h) + aoff + m * 2048 + k * 1024); } while (0)
; #define PG8_MMA(ai, bj, At, Bt) do { __builtin_amdgcn_s_setprio(1); _Pragma("unroll") for (int m = 0; m < 4; ++m) _Pragma("unroll") for (int n = 0; n < 2; ++n) _Pragma("unroll") for (int k = 0; k < 2; ++k) \
;         acc[ai][bj][m][n] = __builtin_amdgcn_mfma_f32_16x16x32_bf16(Bt[n][k], At[m][k], acc[ai][bj][m][n], 0, 0, 0); __builtin_amdgcn_s_setprio(0); } while (0)
; #define PG8_WAIT_V(n) asm volatile("s_waitcnt vmcnt(" #n ")" ::: "memory")
; #define PG8_WAIT_L(n) asm volatile("s_waitcnt lgkmcnt(" #n ")" ::: "memory")
; #define PG8_BAR __builtin_amdgcn_s_barrier()
; #define PG8_SCHED __builtin_amdgcn_sched_barrier(0)
; template <class Epi, class Sched, bool ALIGN_EPI = false, bool SP2 = false>
; __device__ __forceinline__ void gemm_phase(PG8_LAS unsigned char* lds, const Gemm g, const Sched& S, const Epi& E) {
;     ...
;         for (int t = 0; t < nt; t += 2) {
;     ...
;             PG8_LDA(At, 1, 1); PG8_STAGE(PG8_SB(1, 0), b3, voffB); PG8_STAGE(PG8_SB(1, 1), b3 + hstepB, voffB); PG8_STAGE(PG8_SA(1, 0), a3, voffA);
;             PG8_WAIT_V(8); PG8_WAIT_L(0); PG8_BAR; PG8_MMA(1, 0, At, B0); PG8_MMA(1, 1, At, B1); PG8_BAR; PG8_SCHED;
	s_add_i32 s26, s55, s0
	v_lshl_add_u64 v[216:217], v[216:217], 0, s[20:21]
	s_mov_b32 m0, s26
	ds_read_b128 v[184:187], v166 offset:49152
	ds_read_b128 v[188:191], v166 offset:50176
	ds_read_b128 v[192:195], v166 offset:51200
	ds_read_b128 v[196:199], v166 offset:52224
	ds_read_b128 v[200:203], v166 offset:53248
	ds_read_b128 v[204:207], v166 offset:54272
	ds_read_b128 v[208:211], v166 offset:55296
	ds_read_b128 v[212:215], v166 offset:56320
	global_load_lds_dwordx4 v[216:217], off
	s_add_i32 m0, s26, 0x2000
	s_add_u32 s26, s30, 0xb0080
	v_lshl_add_u64 v[216:217], v[218:219], 0, s[20:21]
	s_addc_u32 s27, s31, 0
	s_add_i32 s30, s56, s0
	global_load_lds_dwordx4 v[216:217], off
	v_lshl_add_u64 v[216:217], s[26:27], 0, v[140:141]
	s_mov_b32 m0, s30
	s_nop 0
	global_load_lds_dwordx4 v[216:217], off
	v_lshl_add_u64 v[216:217], s[26:27], 0, v[144:145]
	s_add_i32 m0, s30, 0x2000
	s_nop 0
	global_load_lds_dwordx4 v[216:217], off
	v_lshl_add_u64 v[216:217], v[220:221], 0, s[20:21]
	s_mov_b32 m0, s41
	s_nop 0
	global_load_lds_dwordx4 v[216:217], off
	v_lshl_add_u64 v[216:217], v[222:223], 0, s[20:21]
	s_mov_b32 m0, s42
	s_nop 0
	global_load_lds_dwordx4 v[216:217], off
	s_waitcnt vmcnt(8)
	s_waitcnt lgkmcnt(0)
	s_barrier
	s_setprio 1
	s_waitcnt lgkmcnt(0)
	v_mfma_f32_16x16x32_bf16 v[62:65], v[130:133], v[184:187], v[62:65]
	v_mfma_f32_16x16x32_bf16 v[58:61], v[154:157], v[184:187], v[58:61]
	v_mfma_f32_16x16x32_bf16 v[46:49], v[130:133], v[192:195], v[46:49]
	v_mfma_f32_16x16x32_bf16 v[42:45], v[154:157], v[192:195], v[42:45]
	v_mfma_f32_16x16x32_bf16 v[30:33], v[130:133], v[200:203], v[30:33]
	v_mfma_f32_16x16x32_bf16 v[26:29], v[154:157], v[200:203], v[26:29]
	v_mfma_f32_16x16x32_bf16 v[14:17], v[130:133], v[208:211], v[14:17]
	v_mfma_f32_16x16x32_bf16 v[10:13], v[154:157], v[208:211], v[10:13]
	v_mfma_f32_16x16x32_bf16 v[62:65], v[134:137], v[188:191], v[62:65]
	v_mfma_f32_16x16x32_bf16 v[58:61], v[158:161], v[188:191], v[58:61]
	v_mfma_f32_16x16x32_bf16 v[46:49], v[134:137], v[196:199], v[46:49]
	v_mfma_f32_16x16x32_bf16 v[42:45], v[158:161], v[196:199], v[42:45]
	v_mfma_f32_16x16x32_bf16 v[30:33], v[134:137], v[204:207], v[30:33]
	v_mfma_f32_16x16x32_bf16 v[26:29], v[158:161], v[204:207], v[26:29]
	v_mfma_f32_16x16x32_bf16 v[14:17], v[134:137], v[212:215], v[14:17]
	v_mfma_f32_16x16x32_bf16 v[10:13], v[158:161], v[212:215], v[10:13]
	s_setprio 0
	s_setprio 1
	v_mfma_f32_16x16x32_bf16 v[54:57], v[168:171], v[184:187], v[54:57]
	v_mfma_f32_16x16x32_bf16 v[50:53], v[176:179], v[184:187], v[50:53]
	v_mfma_f32_16x16x32_bf16 v[38:41], v[168:171], v[192:195], v[38:41]
	v_mfma_f32_16x16x32_bf16 v[34:37], v[176:179], v[192:195], v[34:37]
	v_mfma_f32_16x16x32_bf16 v[22:25], v[168:171], v[200:203], v[22:25]
	v_mfma_f32_16x16x32_bf16 v[18:21], v[176:179], v[200:203], v[18:21]
	v_mfma_f32_16x16x32_bf16 v[6:9], v[168:171], v[208:211], v[6:9]
	v_mfma_f32_16x16x32_bf16 v[2:5], v[176:179], v[208:211], v[2:5]
	v_mfma_f32_16x16x32_bf16 v[54:57], v[172:175], v[188:191], v[54:57]
	v_mfma_f32_16x16x32_bf16 v[50:53], v[180:183], v[188:191], v[50:53]
	v_mfma_f32_16x16x32_bf16 v[38:41], v[172:175], v[196:199], v[38:41]
	v_mfma_f32_16x16x32_bf16 v[34:37], v[180:183], v[196:199], v[34:37]
	v_mfma_f32_16x16x32_bf16 v[22:25], v[172:175], v[204:207], v[22:25]
	v_mfma_f32_16x16x32_bf16 v[18:21], v[180:183], v[204:207], v[18:21]
	v_mfma_f32_16x16x32_bf16 v[6:9], v[172:175], v[212:215], v[6:9]
	v_mfma_f32_16x16x32_bf16 v[2:5], v[180:183], v[212:215], v[2:5]
	s_setprio 0
	s_barrier
	s_add_i32 s54, s54, 2
	s_add_u32 s4, s4, 0x100
	s_addc_u32 s53, s53, 0
	s_cmp_gt_u32 s54, 41
	s_mov_b64 s[26:27], s[28:29]

; #define PG8_STAGE(bufoff, gbase, voff) do { _Pragma("unroll") for (int _i = 0; _i < 2; ++_i) \
;         __builtin_amdgcn_global_load_lds((const unsigned*)((const char*)(gbase) + (voff)[_i]), (PG8_LAS unsigned*)(lds + (bufoff) + ldsw + _i * 8192), 16, 0, 0); } while (0)
; #define PG8_LDA(dst, b, h) do { _Pragma("unroll") for (int m = 0; m < 4; ++m) _Pragma("unroll") for (int k = 0; k < 2; ++k) dst[m][k] = *(const PG8_LAS bf16x8*)(lds + PG8_SA(b, h) + aoff + m * 2048 + k * 1024); } while (0)
; #define PG8_LDB(dst, b, h) do { _Pragma("unroll") for (int n = 0; n < 2; ++n) _Pragma("unroll") for (int k = 0; k < 2; ++k) dst[n][k] = *(const PG8_LAS bf16x8*)(lds + PG8_SB(b, h) + boff + n * 2048 + k * 1024); } while (0)
; #define PG8_MMA(ai, bj, At, Bt) do { __builtin_amdgcn_s_setprio(1); _Pragma("unroll") for (int m = 0; m < 4; ++m) _Pragma("unroll") for (int n = 0; n < 2; ++n) _Pragma("unroll") for (int k = 0; k < 2; ++k) \
;         acc[ai][bj][m][n] = __builtin_amdgcn_mfma_f32_16x16x32_bf16(Bt[n][k], At[m][k], acc[ai][bj][m][n], 0, 0, 0); __builtin_amdgcn_s_setprio(0); } while (0)
; #define PG8_WAIT_V(n) asm volatile("s_waitcnt vmcnt(" #n ")" ::: "memory")
; #define PG8_BAR __builtin_amdgcn_s_barrier()
; template <class Epi, class Sched, bool ALIGN_EPI = false, bool SP2 = false>
; __device__ __forceinline__ void gemm_phase(PG8_LAS unsigned char* lds, const Gemm g, const Sched& S, const Epi& E) {
;     ...
;         for (int t = 0; t < nt; t += 2) {
;             const bool last = (t == nt - 2);
;             const char* a1 = cA + (size_t)(t + 1) * kstep;
;             const char* a2 = last ? nA : cA + (size_t)(t + 2) * kstep; const char* b2 = last ? nB : cB + (size_t)(t + 2) * kstep;
;             const char* a3 = a2 + kstep; const char* b3 = b2 + kstep;
;             if (last && has_next) S.a_ready(nxt);
;             if constexpr (SP2) {
;             PG8_LDB(B0, 0, 0); PG8_LDB(B1, 0, 1); PG8_SCHED; PG8_LDA(At, 0, 0); PG8_STAGE(PG8_SA(1, 1), a1 + hstepA, voffA);
;             PG8_WAIT_V(8); PG8_WAIT_L(0); PG8_BAR; PG8_MMA(0, 0, At, B0); PG8_MMA(0, 1, At, B1); PG8_BAR; PG8_SCHED;
;     ...
;         for (int a = 0; a < 2; ++a)
; #pragma unroll
;             for (int b = 0; b < 2; ++b)
; #pragma unroll
;                 for (int m = 0; m < 4; ++m)
; #pragma unroll
;                     for (int n = 0; n < 2; ++n) acc[a][b][m][n] = (f32x4){0.f, 0.f, 0.f, 0.f};
.LBB0_819:
	v_mov_b32_e32 v125, 0
	s_andn2_b64 vcc, exec, s[22:23]
	v_mov_b32_e32 v124, v125
	v_mov_b32_e32 v123, v125
	v_mov_b32_e32 v122, v125
	v_mov_b32_e32 v129, v125
	v_mov_b32_e32 v128, v125
	v_mov_b32_e32 v127, v125
	v_mov_b32_e32 v126, v125
	v_mov_b32_e32 v113, v125
	v_mov_b32_e32 v112, v125
	v_mov_b32_e32 v111, v125
	v_mov_b32_e32 v110, v125
	v_mov_b32_e32 v109, v125
	v_mov_b32_e32 v108, v125
	v_mov_b32_e32 v107, v125
	v_mov_b32_e32 v106, v125
	v_mov_b32_e32 v97, v125
	v_mov_b32_e32 v96, v125
	v_mov_b32_e32 v95, v125
	v_mov_b32_e32 v94, v125
	v_mov_b32_e32 v93, v125
	v_mov_b32_e32 v92, v125
	v_mov_b32_e32 v91, v125
	v_mov_b32_e32 v90, v125
	v_mov_b32_e32 v81, v125
	v_mov_b32_e32 v80, v125
	v_mov_b32_e32 v79, v125
	v_mov_b32_e32 v78, v125
	v_mov_b32_e32 v77, v125
	v_mov_b32_e32 v76, v125
	v_mov_b32_e32 v75, v125
	v_mov_b32_e32 v74, v125
	v_mov_b32_e32 v121, v125
	v_mov_b32_e32 v120, v125
	v_mov_b32_e32 v119, v125
	v_mov_b32_e32 v118, v125
	v_mov_b32_e32 v117, v125
	v_mov_b32_e32 v116, v125
	v_mov_b32_e32 v115, v125
	v_mov_b32_e32 v114, v125
	v_mov_b32_e32 v105, v125
	v_mov_b32_e32 v104, v125
	v_mov_b32_e32 v103, v125
	v_mov_b32_e32 v102, v125
	v_mov_b32_e32 v101, v125
	v_mov_b32_e32 v100, v125
	v_mov_b32_e32 v99, v125
	v_mov_b32_e32 v98, v125
	v_mov_b32_e32 v89, v125
	v_mov_b32_e32 v88, v125
	v_mov_b32_e32 v87, v125
	v_mov_b32_e32 v86, v125
	v_mov_b32_e32 v85, v125
	v_mov_b32_e32 v84, v125
	v_mov_b32_e32 v83, v125
	v_mov_b32_e32 v82, v125
	v_mov_b32_e32 v73, v125
	v_mov_b32_e32 v72, v125
	v_mov_b32_e32 v71, v125
	v_mov_b32_e32 v70, v125
	v_mov_b32_e32 v69, v125
	v_mov_b32_e32 v68, v125
	v_mov_b32_e32 v67, v125
	v_mov_b32_e32 v66, v125
	v_mov_b32_e32 v65, v125
	v_mov_b32_e32 v64, v125
	v_mov_b32_e32 v63, v125
	v_mov_b32_e32 v62, v125
	v_mov_b32_e32 v61, v125
	v_mov_b32_e32 v60, v125
	v_mov_b32_e32 v59, v125
	v_mov_b32_e32 v58, v125
	v_mov_b32_e32 v49, v125
	v_mov_b32_e32 v48, v125
	v_mov_b32_e32 v47, v125
	v_mov_b32_e32 v46, v125
	v_mov_b32_e32 v45, v125
	v_mov_b32_e32 v44, v125
	v_mov_b32_e32 v43, v125
	v_mov_b32_e32 v42, v125
	v_mov_b32_e32 v33, v125
	v_mov_b32_e32 v32, v125
	v_mov_b32_e32 v31, v125
	v_mov_b32_e32 v30, v125
	v_mov_b32_e32 v29, v125
	v_mov_b32_e32 v28, v125
	v_mov_b32_e32 v27, v125
	v_mov_b32_e32 v26, v125
	v_mov_b32_e32 v17, v125
	v_mov_b32_e32 v16, v125
	v_mov_b32_e32 v15, v125
	v_mov_b32_e32 v14, v125
	v_mov_b32_e32 v13, v125
	v_mov_b32_e32 v12, v125
	v_mov_b32_e32 v11, v125
	v_mov_b32_e32 v10, v125
	v_mov_b32_e32 v57, v125
	v_mov_b32_e32 v56, v125
	v_mov_b32_e32 v55, v125
	v_mov_b32_e32 v54, v125
	v_mov_b32_e32 v53, v125
	v_mov_b32_e32 v52, v125
	v_mov_b32_e32 v51, v125
	v_mov_b32_e32 v50, v125
	v_mov_b32_e32 v41, v125
	v_mov_b32_e32 v40, v125
	v_mov_b32_e32 v39, v125
	v_mov_b32_e32 v38, v125
	v_mov_b32_e32 v37, v125
	v_mov_b32_e32 v36, v125
	v_mov_b32_e32 v35, v125
	v_mov_b32_e32 v34, v125
	v_mov_b32_e32 v25, v125
	v_mov_b32_e32 v24, v125
	v_mov_b32_e32 v23, v125
	v_mov_b32_e32 v22, v125
	v_mov_b32_e32 v21, v125
	v_mov_b32_e32 v20, v125
	v_mov_b32_e32 v19, v125
	v_mov_b32_e32 v18, v125
	v_mov_b32_e32 v9, v125
	v_mov_b32_e32 v8, v125
	v_mov_b32_e32 v7, v125
	v_mov_b32_e32 v6, v125
	v_mov_b32_e32 v5, v125
	v_mov_b32_e32 v4, v125
	v_mov_b32_e32 v3, v125
	v_mov_b32_e32 v2, v125
	s_cbranch_vccnz .LBB0_822
	s_add_u32 s38, s38, 0x80
	s_addc_u32 s39, s39, 0
	s_add_u32 s63, s40, 0x100
	s_addc_u32 s64, s41, 0
	s_mov_b32 s40, 0
	ds_read_b128 v[152:155], v148
	ds_read_b128 v[156:159], v148 offset:1024
	ds_read_b128 v[160:163], v148 offset:2048
	ds_read_b128 v[164:167], v148 offset:3072
	ds_read_b128 v[168:171], v149
	ds_read_b128 v[172:175], v149 offset:1024
	ds_read_b128 v[176:179], v149 offset:2048
	ds_read_b128 v[180:183], v149 offset:3072
	s_add_i32 s65, s40, 2
	s_add_u32 s66, s38, 0x80
	s_addc_u32 s41, s39, 0
	s_cmp_eq_u32 s51, s40
	s_cselect_b32 s40, s8, s66
	s_cselect_b32 s41, s9, s41
	s_cselect_b32 s67, s37, s64
	s_cselect_b32 s66, s36, s63
	v_lshl_add_u64 v[216:217], s[38:39], 0, v[138:139]
	s_add_i32 m0, s43, 0xc000
	ds_read_b128 v[184:187], v150
	ds_read_b128 v[188:191], v150 offset:1024
	ds_read_b128 v[192:195], v150 offset:2048
	ds_read_b128 v[196:199], v150 offset:3072
	ds_read_b128 v[200:203], v150 offset:4096
	ds_read_b128 v[204:207], v150 offset:5120
	ds_read_b128 v[208:211], v150 offset:6144
	ds_read_b128 v[212:215], v150 offset:7168
	global_load_lds_dwordx4 v[216:217], off
	v_lshl_add_u64 v[216:217], s[38:39], 0, v[140:141]
	s_add_i32 m0, s43, 0xe000
	s_nop 0
	global_load_lds_dwordx4 v[216:217], off
	s_waitcnt vmcnt(8)
	s_waitcnt lgkmcnt(0)
	s_barrier
; #define PG8_STAGE(bufoff, gbase, voff) do { _Pragma("unroll") for (int _i = 0; _i < 2; ++_i) \
;         __builtin_amdgcn_global_load_lds((const unsigned*)((const char*)(gbase) + (voff)[_i]), (PG8_LAS unsigned*)(lds + (bufoff) + ldsw + _i * 8192), 16, 0, 0); } while (0)
; #define PG8_LDA(dst, b, h) do { _Pragma("unroll") for (int m = 0; m < 4; ++m) _Pragma("unroll") for (int k = 0; k < 2; ++k) dst[m][k] = *(const PG8_LAS bf16x8*)(lds + PG8_SA(b, h) + aoff + m * 2048 + k * 1024); } while (0)
; #define PG8_MMA(ai, bj, At, Bt) do { __builtin_amdgcn_s_setprio(1); _Pragma("unroll") for (int m = 0; m < 4; ++m) _Pragma("unroll") for (int n = 0; n < 2; ++n) _Pragma("unroll") for (int k = 0; k < 2; ++k) \
;         acc[ai][bj][m][n] = __builtin_amdgcn_mfma_f32_16x16x32_bf16(Bt[n][k], At[m][k], acc[ai][bj][m][n], 0, 0, 0); __builtin_amdgcn_s_setprio(0); } while (0)
; #define PG8_WAIT_V(n) asm volatile("s_waitcnt vmcnt(" #n ")" ::: "memory")
; #define PG8_WAIT_L(n) asm volatile("s_waitcnt lgkmcnt(" #n ")" ::: "memory")
; #define PG8_BAR __builtin_amdgcn_s_barrier()
; #define PG8_SCHED __builtin_amdgcn_sched_barrier(0)
; template <class Epi, class Sched, bool ALIGN_EPI = false, bool SP2 = false>
; __device__ __forceinline__ void gemm_phase(PG8_LAS unsigned char* lds, const Gemm g, const Sched& S, const Epi& E) {
;     ...
;             PG8_WAIT_V(8); PG8_WAIT_L(0); PG8_BAR; PG8_MMA(0, 0, At, B0); PG8_MMA(0, 1, At, B1); PG8_BAR; PG8_SCHED;
;             PG8_LDA(At, 0, 1); PG8_STAGE(PG8_SB(0, 0), b2, voffB); PG8_STAGE(PG8_SB(0, 1), b2 + hstepB, voffB); PG8_STAGE(PG8_SA(0, 0), a2, voffA);
;             PG8_WAIT_V(8); PG8_WAIT_L(0); PG8_BAR; PG8_MMA(1, 0, At, B0); PG8_MMA(1, 1, At, B1); PG8_BAR; PG8_SCHED;
	s_setprio 1
	s_waitcnt lgkmcnt(0)
	v_mfma_f32_16x16x32_bf16 v[122:125], v[152:155], v[184:187], 0
	v_mfma_f32_16x16x32_bf16 v[126:129], v[160:163], v[184:187], 0
	v_mfma_f32_16x16x32_bf16 v[110:113], v[152:155], v[192:195], 0
	v_mfma_f32_16x16x32_bf16 v[106:109], v[160:163], v[192:195], 0
	v_mfma_f32_16x16x32_bf16 v[94:97], v[152:155], v[200:203], 0
	v_mfma_f32_16x16x32_bf16 v[90:93], v[160:163], v[200:203], 0
	v_mfma_f32_16x16x32_bf16 v[78:81], v[152:155], v[208:211], 0
	v_mfma_f32_16x16x32_bf16 v[74:77], v[160:163], v[208:211], 0
	v_mfma_f32_16x16x32_bf16 v[122:125], v[156:159], v[188:191], v[122:125]
	v_mfma_f32_16x16x32_bf16 v[126:129], v[164:167], v[188:191], v[126:129]
	v_mfma_f32_16x16x32_bf16 v[110:113], v[156:159], v[196:199], v[110:113]
	v_mfma_f32_16x16x32_bf16 v[106:109], v[164:167], v[196:199], v[106:109]
	v_mfma_f32_16x16x32_bf16 v[94:97], v[156:159], v[204:207], v[94:97]
	v_mfma_f32_16x16x32_bf16 v[90:93], v[164:167], v[204:207], v[90:93]
	v_mfma_f32_16x16x32_bf16 v[78:81], v[156:159], v[212:215], v[78:81]
	v_mfma_f32_16x16x32_bf16 v[74:77], v[164:167], v[212:215], v[74:77]
	s_setprio 0
	s_setprio 1
	v_mfma_f32_16x16x32_bf16 v[118:121], v[168:171], v[184:187], 0
	v_mfma_f32_16x16x32_bf16 v[114:117], v[176:179], v[184:187], 0
	v_mfma_f32_16x16x32_bf16 v[102:105], v[168:171], v[192:195], 0
	v_mfma_f32_16x16x32_bf16 v[98:101], v[176:179], v[192:195], 0
	v_mfma_f32_16x16x32_bf16 v[86:89], v[168:171], v[200:203], 0
	v_mfma_f32_16x16x32_bf16 v[82:85], v[176:179], v[200:203], 0
	v_mfma_f32_16x16x32_bf16 v[70:73], v[168:171], v[208:211], 0
	v_mfma_f32_16x16x32_bf16 v[66:69], v[176:179], v[208:211], 0
	v_mfma_f32_16x16x32_bf16 v[118:121], v[172:175], v[188:191], v[118:121]
	v_mfma_f32_16x16x32_bf16 v[114:117], v[180:183], v[188:191], v[114:117]
	v_mfma_f32_16x16x32_bf16 v[102:105], v[172:175], v[196:199], v[102:105]
	v_mfma_f32_16x16x32_bf16 v[98:101], v[180:183], v[196:199], v[98:101]
	v_mfma_f32_16x16x32_bf16 v[86:89], v[172:175], v[204:207], v[86:89]
	v_mfma_f32_16x16x32_bf16 v[82:85], v[180:183], v[204:207], v[82:85]
	v_mfma_f32_16x16x32_bf16 v[70:73], v[172:175], v[212:215], v[70:73]
	v_mfma_f32_16x16x32_bf16 v[66:69], v[180:183], v[212:215], v[66:69]
	s_setprio 0
	s_barrier
	s_add_i32 s68, s54, s42
	v_lshl_add_u64 v[216:217], s[66:67], 0, v[132:133]
	s_mov_b32 m0, s68
	ds_read_b128 v[184:187], v150 offset:16384
	ds_read_b128 v[188:191], v150 offset:17408
	ds_read_b128 v[192:195], v150 offset:18432
	ds_read_b128 v[196:199], v150 offset:19456
	ds_read_b128 v[200:203], v150 offset:20480
	ds_read_b128 v[204:207], v150 offset:21504
	ds_read_b128 v[208:211], v150 offset:22528
	ds_read_b128 v[212:215], v150 offset:23552
	global_load_lds_dwordx4 v[216:217], off
	s_add_i32 m0, s68, 0x2000
	v_lshl_add_u64 v[218:219], s[66:67], 0, v[136:137]
	s_add_u32 s66, s66, s10
	s_addc_u32 s67, s67, s11
	s_add_i32 s68, s55, s42
	global_load_lds_dwordx4 v[218:219], off
	v_lshl_add_u64 v[220:221], s[66:67], 0, v[132:133]
	s_mov_b32 m0, s68
	v_lshl_add_u64 v[222:223], s[66:67], 0, v[136:137]
	global_load_lds_dwordx4 v[220:221], off
	s_add_i32 m0, s68, 0x2000
	v_lshl_add_u64 v[224:225], s[40:41], 0, v[130:131]
	global_load_lds_dwordx4 v[222:223], off
	s_mov_b32 m0, s43
	v_lshl_add_u64 v[226:227], s[40:41], 0, v[134:135]
	global_load_lds_dwordx4 v[224:225], off
	s_mov_b32 m0, s44
	s_nop 0
	global_load_lds_dwordx4 v[226:227], off
	s_waitcnt vmcnt(8)
	s_waitcnt lgkmcnt(0)
	s_barrier
	s_setprio 1
	s_waitcnt lgkmcnt(0)
	v_mfma_f32_16x16x32_bf16 v[62:65], v[152:155], v[184:187], 0
	v_mfma_f32_16x16x32_bf16 v[58:61], v[160:163], v[184:187], 0
	v_mfma_f32_16x16x32_bf16 v[46:49], v[152:155], v[192:195], 0
	v_mfma_f32_16x16x32_bf16 v[42:45], v[160:163], v[192:195], 0
	v_mfma_f32_16x16x32_bf16 v[30:33], v[152:155], v[200:203], 0
	v_mfma_f32_16x16x32_bf16 v[26:29], v[160:163], v[200:203], 0
	v_mfma_f32_16x16x32_bf16 v[14:17], v[152:155], v[208:211], 0
	v_mfma_f32_16x16x32_bf16 v[10:13], v[160:163], v[208:211], 0
	v_mfma_f32_16x16x32_bf16 v[62:65], v[156:159], v[188:191], v[62:65]
	v_mfma_f32_16x16x32_bf16 v[58:61], v[164:167], v[188:191], v[58:61]
	v_mfma_f32_16x16x32_bf16 v[46:49], v[156:159], v[196:199], v[46:49]
	v_mfma_f32_16x16x32_bf16 v[42:45], v[164:167], v[196:199], v[42:45]
	v_mfma_f32_16x16x32_bf16 v[30:33], v[156:159], v[204:207], v[30:33]
	v_mfma_f32_16x16x32_bf16 v[26:29], v[164:167], v[204:207], v[26:29]
	v_mfma_f32_16x16x32_bf16 v[14:17], v[156:159], v[212:215], v[14:17]
	v_mfma_f32_16x16x32_bf16 v[10:13], v[164:167], v[212:215], v[10:13]
	s_setprio 0
	s_setprio 1
	v_mfma_f32_16x16x32_bf16 v[54:57], v[168:171], v[184:187], 0
	v_mfma_f32_16x16x32_bf16 v[50:53], v[176:179], v[184:187], 0
	v_mfma_f32_16x16x32_bf16 v[38:41], v[168:171], v[192:195], 0
	v_mfma_f32_16x16x32_bf16 v[34:37], v[176:179], v[192:195], 0
	v_mfma_f32_16x16x32_bf16 v[22:25], v[168:171], v[200:203], 0
	v_mfma_f32_16x16x32_bf16 v[18:21], v[176:179], v[200:203], 0
	v_mfma_f32_16x16x32_bf16 v[6:9], v[168:171], v[208:211], 0
	v_mfma_f32_16x16x32_bf16 v[2:5], v[176:179], v[208:211], 0
	v_mfma_f32_16x16x32_bf16 v[54:57], v[172:175], v[188:191], v[54:57]
	v_mfma_f32_16x16x32_bf16 v[50:53], v[180:183], v[188:191], v[50:53]
	v_mfma_f32_16x16x32_bf16 v[38:41], v[172:175], v[196:199], v[38:41]
	v_mfma_f32_16x16x32_bf16 v[34:37], v[180:183], v[196:199], v[34:37]
	v_mfma_f32_16x16x32_bf16 v[22:25], v[172:175], v[204:207], v[22:25]
	v_mfma_f32_16x16x32_bf16 v[18:21], v[180:183], v[204:207], v[18:21]
	v_mfma_f32_16x16x32_bf16 v[6:9], v[172:175], v[212:215], v[6:9]
	v_mfma_f32_16x16x32_bf16 v[2:5], v[180:183], v[212:215], v[2:5]
	s_setprio 0
	s_barrier
; #define PG8_STAGE(bufoff, gbase, voff) do { _Pragma("unroll") for (int _i = 0; _i < 2; ++_i) \
;         __builtin_amdgcn_global_load_lds((const unsigned*)((const char*)(gbase) + (voff)[_i]), (PG8_LAS unsigned*)(lds + (bufoff) + ldsw + _i * 8192), 16, 0, 0); } while (0)
; #define PG8_LDA(dst, b, h) do { _Pragma("unroll") for (int m = 0; m < 4; ++m) _Pragma("unroll") for (int k = 0; k < 2; ++k) dst[m][k] = *(const PG8_LAS bf16x8*)(lds + PG8_SA(b, h) + aoff + m * 2048 + k * 1024); } while (0)
; #define PG8_LDB(dst, b, h) do { _Pragma("unroll") for (int n = 0; n < 2; ++n) _Pragma("unroll") for (int k = 0; k < 2; ++k) dst[n][k] = *(const PG8_LAS bf16x8*)(lds + PG8_SB(b, h) + boff + n * 2048 + k * 1024); } while (0)
; #define PG8_MMA(ai, bj, At, Bt) do { __builtin_amdgcn_s_setprio(1); _Pragma("unroll") for (int m = 0; m < 4; ++m) _Pragma("unroll") for (int n = 0; n < 2; ++n) _Pragma("unroll") for (int k = 0; k < 2; ++k) \
;         acc[ai][bj][m][n] = __builtin_amdgcn_mfma_f32_16x16x32_bf16(Bt[n][k], At[m][k], acc[ai][bj][m][n], 0, 0, 0); __builtin_amdgcn_s_setprio(0); } while (0)
; #define PG8_WAIT_V(n) asm volatile("s_waitcnt vmcnt(" #n ")" ::: "memory")
; #define PG8_WAIT_L(n) asm volatile("s_waitcnt lgkmcnt(" #n ")" ::: "memory")
; #define PG8_BAR __builtin_amdgcn_s_barrier()
; #define PG8_SCHED __builtin_amdgcn_sched_barrier(0)
; template <class Epi, class Sched, bool ALIGN_EPI = false, bool SP2 = false>
; __device__ __forceinline__ void gemm_phase(PG8_LAS unsigned char* lds, const Gemm g, const Sched& S, const Epi& E) {
;     ...
;             PG8_LDB(B0, 1, 0); PG8_LDB(B1, 1, 1); PG8_SCHED; PG8_LDA(At, 1, 0); PG8_STAGE(PG8_SA(0, 1), a2 + hstepA, voffA);
;             PG8_WAIT_V(8); PG8_WAIT_L(0); PG8_BAR; PG8_MMA(0, 0, At, B0); PG8_MMA(0, 1, At, B1); PG8_BAR; PG8_SCHED;
	s_add_i32 s66, 0, 0x18000
	v_add_u32_e32 v151, s66, v146
	s_add_i32 s67, 0, 0x1c000
	ds_read_b128 v[152:155], v151
	ds_read_b128 v[156:159], v151 offset:1024
	ds_read_b128 v[160:163], v151 offset:2048
	ds_read_b128 v[164:167], v151 offset:3072
	v_add_u32_e32 v151, s67, v146
	ds_read_b128 v[168:171], v151
	ds_read_b128 v[172:175], v151 offset:1024
	ds_read_b128 v[176:179], v151 offset:2048
	ds_read_b128 v[180:183], v151 offset:3072
	s_add_u32 s40, s40, s4
	s_addc_u32 s41, s41, s5
	s_mov_b32 m0, s45
	v_lshl_add_u64 v[228:229], s[40:41], 0, v[130:131]
	ds_read_b128 v[184:187], v150 offset:32768
	ds_read_b128 v[188:191], v150 offset:33792
	ds_read_b128 v[192:195], v150 offset:34816
	ds_read_b128 v[196:199], v150 offset:35840
	ds_read_b128 v[200:203], v150 offset:36864
	ds_read_b128 v[204:207], v150 offset:37888
	ds_read_b128 v[208:211], v150 offset:38912
	ds_read_b128 v[212:215], v150 offset:39936
	global_load_lds_dwordx4 v[228:229], off
	v_lshl_add_u64 v[228:229], s[40:41], 0, v[134:135]
	s_mov_b32 m0, s46
	s_nop 0
	global_load_lds_dwordx4 v[228:229], off
	s_waitcnt vmcnt(8)
	s_waitcnt lgkmcnt(0)
	s_barrier
	s_setprio 1
	s_waitcnt lgkmcnt(0)
	v_mfma_f32_16x16x32_bf16 v[122:125], v[152:155], v[184:187], v[122:125]
	v_mfma_f32_16x16x32_bf16 v[126:129], v[160:163], v[184:187], v[126:129]
	v_mfma_f32_16x16x32_bf16 v[110:113], v[152:155], v[192:195], v[110:113]
	v_mfma_f32_16x16x32_bf16 v[106:109], v[160:163], v[192:195], v[106:109]
	v_mfma_f32_16x16x32_bf16 v[94:97], v[152:155], v[200:203], v[94:97]
	v_mfma_f32_16x16x32_bf16 v[90:93], v[160:163], v[200:203], v[90:93]
	v_mfma_f32_16x16x32_bf16 v[78:81], v[152:155], v[208:211], v[78:81]
	v_mfma_f32_16x16x32_bf16 v[74:77], v[160:163], v[208:211], v[74:77]
	v_mfma_f32_16x16x32_bf16 v[122:125], v[156:159], v[188:191], v[122:125]
	v_mfma_f32_16x16x32_bf16 v[126:129], v[164:167], v[188:191], v[126:129]
	v_mfma_f32_16x16x32_bf16 v[110:113], v[156:159], v[196:199], v[110:113]
	v_mfma_f32_16x16x32_bf16 v[106:109], v[164:167], v[196:199], v[106:109]
	v_mfma_f32_16x16x32_bf16 v[94:97], v[156:159], v[204:207], v[94:97]
	v_mfma_f32_16x16x32_bf16 v[90:93], v[164:167], v[204:207], v[90:93]
	v_mfma_f32_16x16x32_bf16 v[78:81], v[156:159], v[212:215], v[78:81]
	v_mfma_f32_16x16x32_bf16 v[74:77], v[164:167], v[212:215], v[74:77]
	s_setprio 0
	s_setprio 1
	v_mfma_f32_16x16x32_bf16 v[118:121], v[168:171], v[184:187], v[118:121]
	v_mfma_f32_16x16x32_bf16 v[114:117], v[176:179], v[184:187], v[114:117]
	v_mfma_f32_16x16x32_bf16 v[102:105], v[168:171], v[192:195], v[102:105]
	v_mfma_f32_16x16x32_bf16 v[98:101], v[176:179], v[192:195], v[98:101]
	v_mfma_f32_16x16x32_bf16 v[86:89], v[168:171], v[200:203], v[86:89]
	v_mfma_f32_16x16x32_bf16 v[82:85], v[176:179], v[200:203], v[82:85]
	v_mfma_f32_16x16x32_bf16 v[70:73], v[168:171], v[208:211], v[70:73]
	v_mfma_f32_16x16x32_bf16 v[66:69], v[176:179], v[208:211], v[66:69]
	v_mfma_f32_16x16x32_bf16 v[118:121], v[172:175], v[188:191], v[118:121]
	v_mfma_f32_16x16x32_bf16 v[114:117], v[180:183], v[188:191], v[114:117]
	v_mfma_f32_16x16x32_bf16 v[102:105], v[172:175], v[196:199], v[102:105]
	v_mfma_f32_16x16x32_bf16 v[98:101], v[180:183], v[196:199], v[98:101]
	v_mfma_f32_16x16x32_bf16 v[86:89], v[172:175], v[204:207], v[86:89]
	v_mfma_f32_16x16x32_bf16 v[82:85], v[180:183], v[204:207], v[82:85]
	v_mfma_f32_16x16x32_bf16 v[70:73], v[172:175], v[212:215], v[70:73]
	v_mfma_f32_16x16x32_bf16 v[66:69], v[180:183], v[212:215], v[66:69]
	s_setprio 0
	s_barrier
; #define PG8_STAGE(bufoff, gbase, voff) do { _Pragma("unroll") for (int _i = 0; _i < 2; ++_i) \
;         __builtin_amdgcn_global_load_lds((const unsigned*)((const char*)(gbase) + (voff)[_i]), (PG8_LAS unsigned*)(lds + (bufoff) + ldsw + _i * 8192), 16, 0, 0); } while (0)
; #define PG8_LDA(dst, b, h) do { _Pragma("unroll") for (int m = 0; m < 4; ++m) _Pragma("unroll") for (int k = 0; k < 2; ++k) dst[m][k] = *(const PG8_LAS bf16x8*)(lds + PG8_SA(b, h) + aoff + m * 2048 + k * 1024); } while (0)
; #define PG8_MMA(ai, bj, At, Bt) do { __builtin_amdgcn_s_setprio(1); _Pragma("unroll") for (int m = 0; m < 4; ++m) _Pragma("unroll") for (int n = 0; n < 2; ++n) _Pragma("unroll") for (int k = 0; k < 2; ++k) \
;         acc[ai][bj][m][n] = __builtin_amdgcn_mfma_f32_16x16x32_bf16(Bt[n][k], At[m][k], acc[ai][bj][m][n], 0, 0, 0); __builtin_amdgcn_s_setprio(0); } while (0)
; #define PG8_WAIT_V(n) asm volatile("s_waitcnt vmcnt(" #n ")" ::: "memory")
; #define PG8_WAIT_L(n) asm volatile("s_waitcnt lgkmcnt(" #n ")" ::: "memory")
; #define PG8_BAR __builtin_amdgcn_s_barrier()
; #define PG8_SCHED __builtin_amdgcn_sched_barrier(0)
; template <class Epi, class Sched, bool ALIGN_EPI = false, bool SP2 = false>
; __device__ __forceinline__ void gemm_phase(PG8_LAS unsigned char* lds, const Gemm g, const Sched& S, const Epi& E) {
;     ...
;         for (int t = 0; t < nt; t += 2) {
;     ...
;             PG8_LDA(At, 1, 1); PG8_STAGE(PG8_SB(1, 0), b3, voffB); PG8_STAGE(PG8_SB(1, 1), b3 + hstepB, voffB); PG8_STAGE(PG8_SA(1, 0), a3, voffA);
;             PG8_WAIT_V(8); PG8_WAIT_L(0); PG8_BAR; PG8_MMA(1, 0, At, B0); PG8_MMA(1, 1, At, B1); PG8_BAR; PG8_SCHED;
	s_add_i32 s40, s66, s42
	v_lshl_add_u64 v[216:217], v[216:217], 0, s[20:21]
	s_mov_b32 m0, s40
	ds_read_b128 v[184:187], v150 offset:49152
	ds_read_b128 v[188:191], v150 offset:50176
	ds_read_b128 v[192:195], v150 offset:51200
	ds_read_b128 v[196:199], v150 offset:52224
	ds_read_b128 v[200:203], v150 offset:53248
	ds_read_b128 v[204:207], v150 offset:54272
	ds_read_b128 v[208:211], v150 offset:55296
	ds_read_b128 v[212:215], v150 offset:56320
	global_load_lds_dwordx4 v[216:217], off
	v_lshl_add_u64 v[216:217], v[218:219], 0, s[20:21]
	s_add_i32 m0, s40, 0x2000
	s_add_i32 s40, s67, s42
	global_load_lds_dwordx4 v[216:217], off
	v_lshl_add_u64 v[216:217], v[220:221], 0, s[20:21]
	s_mov_b32 m0, s40
	s_nop 0
	global_load_lds_dwordx4 v[216:217], off
	v_lshl_add_u64 v[216:217], v[222:223], 0, s[20:21]
	s_add_i32 m0, s40, 0x2000
	s_nop 0
	global_load_lds_dwordx4 v[216:217], off
	v_lshl_add_u64 v[216:217], v[224:225], 0, s[20:21]
	s_mov_b32 m0, s48
	s_nop 0
	global_load_lds_dwordx4 v[216:217], off
	v_lshl_add_u64 v[216:217], v[226:227], 0, s[20:21]
	s_mov_b32 m0, s49
	s_nop 0
	global_load_lds_dwordx4 v[216:217], off
	s_waitcnt vmcnt(8)
	s_waitcnt lgkmcnt(0)
	s_barrier
	s_setprio 1
	s_waitcnt lgkmcnt(0)
	v_mfma_f32_16x16x32_bf16 v[62:65], v[152:155], v[184:187], v[62:65]
	v_mfma_f32_16x16x32_bf16 v[58:61], v[160:163], v[184:187], v[58:61]
	v_mfma_f32_16x16x32_bf16 v[46:49], v[152:155], v[192:195], v[46:49]
	v_mfma_f32_16x16x32_bf16 v[42:45], v[160:163], v[192:195], v[42:45]
	v_mfma_f32_16x16x32_bf16 v[30:33], v[152:155], v[200:203], v[30:33]
	v_mfma_f32_16x16x32_bf16 v[26:29], v[160:163], v[200:203], v[26:29]
	v_mfma_f32_16x16x32_bf16 v[14:17], v[152:155], v[208:211], v[14:17]
	v_mfma_f32_16x16x32_bf16 v[10:13], v[160:163], v[208:211], v[10:13]
	v_mfma_f32_16x16x32_bf16 v[62:65], v[156:159], v[188:191], v[62:65]
	v_mfma_f32_16x16x32_bf16 v[58:61], v[164:167], v[188:191], v[58:61]
	v_mfma_f32_16x16x32_bf16 v[46:49], v[156:159], v[196:199], v[46:49]
	v_mfma_f32_16x16x32_bf16 v[42:45], v[164:167], v[196:199], v[42:45]
	v_mfma_f32_16x16x32_bf16 v[30:33], v[156:159], v[204:207], v[30:33]
	v_mfma_f32_16x16x32_bf16 v[26:29], v[164:167], v[204:207], v[26:29]
	v_mfma_f32_16x16x32_bf16 v[14:17], v[156:159], v[212:215], v[14:17]
	v_mfma_f32_16x16x32_bf16 v[10:13], v[164:167], v[212:215], v[10:13]
	s_setprio 0
	s_setprio 1
	v_mfma_f32_16x16x32_bf16 v[54:57], v[168:171], v[184:187], v[54:57]
	v_mfma_f32_16x16x32_bf16 v[50:53], v[176:179], v[184:187], v[50:53]
	v_mfma_f32_16x16x32_bf16 v[38:41], v[168:171], v[192:195], v[38:41]
	v_mfma_f32_16x16x32_bf16 v[34:37], v[176:179], v[192:195], v[34:37]
	v_mfma_f32_16x16x32_bf16 v[22:25], v[168:171], v[200:203], v[22:25]
	v_mfma_f32_16x16x32_bf16 v[18:21], v[176:179], v[200:203], v[18:21]
	v_mfma_f32_16x16x32_bf16 v[6:9], v[168:171], v[208:211], v[6:9]
	v_mfma_f32_16x16x32_bf16 v[2:5], v[176:179], v[208:211], v[2:5]
	v_mfma_f32_16x16x32_bf16 v[54:57], v[172:175], v[188:191], v[54:57]
	v_mfma_f32_16x16x32_bf16 v[50:53], v[180:183], v[188:191], v[50:53]
	v_mfma_f32_16x16x32_bf16 v[38:41], v[172:175], v[196:199], v[38:41]
	v_mfma_f32_16x16x32_bf16 v[34:37], v[180:183], v[196:199], v[34:37]
	v_mfma_f32_16x16x32_bf16 v[22:25], v[172:175], v[204:207], v[22:25]
	v_mfma_f32_16x16x32_bf16 v[18:21], v[180:183], v[204:207], v[18:21]
	v_mfma_f32_16x16x32_bf16 v[6:9], v[172:175], v[212:215], v[6:9]
	v_mfma_f32_16x16x32_bf16 v[2:5], v[180:183], v[212:215], v[2:5]
	s_setprio 0
	s_barrier
	s_add_u32 s38, s38, 0x100
	s_addc_u32 s39, s39, 0
	s_add_u32 s63, s63, 0x100
	s_addc_u32 s64, s64, 0
	s_cmp_ge_i32 s65, s50
	s_mov_b32 s40, s65

; #define PG8_STAGE(bufoff, gbase, voff) do { _Pragma("unroll") for (int _i = 0; _i < 2; ++_i) \
;         __builtin_amdgcn_global_load_lds((const unsigned*)((const char*)(gbase) + (voff)[_i]), (PG8_LAS unsigned*)(lds + (bufoff) + ldsw + _i * 8192), 16, 0, 0); } while (0)
; #define PG8_LDA(dst, b, h) do { _Pragma("unroll") for (int m = 0; m < 4; ++m) _Pragma("unroll") for (int k = 0; k < 2; ++k) dst[m][k] = *(const PG8_LAS bf16x8*)(lds + PG8_SA(b, h) + aoff + m * 2048 + k * 1024); } while (0)
; #define PG8_LDB(dst, b, h) do { _Pragma("unroll") for (int n = 0; n < 2; ++n) _Pragma("unroll") for (int k = 0; k < 2; ++k) dst[n][k] = *(const PG8_LAS bf16x8*)(lds + PG8_SB(b, h) + boff + n * 2048 + k * 1024); } while (0)
; #define PG8_WAIT_V(n) asm volatile("s_waitcnt vmcnt(" #n ")" ::: "memory")
; #define PG8_WAIT_L(n) asm volatile("s_waitcnt lgkmcnt(" #n ")" ::: "memory")
; #define PG8_BAR __builtin_amdgcn_s_barrier()
; template <class Epi, class Sched, bool ALIGN_EPI = false, bool SP2 = false>
; __device__ __forceinline__ void gemm_phase(PG8_LAS unsigned char* lds, const Gemm g, const Sched& S, const Epi& E) {
;     ...
;         const bool has_next = S.next(ui + 1, nxt);
;         const char* nA = has_next ? (const char*)g.A + (size_t)nxt.g * g.gsA * 2 + (size_t)nxt.pm * tstepA : cA; const char* nB = has_next ? (const char*)g.Bt + (size_t)nxt.g * g.gsB * 2 + (size_t)nxt.pn * tstepB : cB;
;         for (int t = 0; t < nt; t += 2) {
;             const bool last = (t == nt - 2);
;             const char* a1 = cA + (size_t)(t + 1) * kstep;
;             const char* a2 = last ? nA : cA + (size_t)(t + 2) * kstep; const char* b2 = last ? nB : cB + (size_t)(t + 2) * kstep;
;             const char* a3 = a2 + kstep; const char* b3 = b2 + kstep;
;             if (last && has_next) S.a_ready(nxt);
;             if constexpr (SP2) {
;             PG8_LDB(B0, 0, 0); PG8_LDB(B1, 0, 1); PG8_SCHED; PG8_LDA(At, 0, 0); PG8_STAGE(PG8_SA(1, 1), a1 + hstepA, voffA);
;             PG8_WAIT_V(8); PG8_WAIT_L(0); PG8_BAR; PG8_MMA(0, 0, At, B0); PG8_MMA(0, 1, At, B1); PG8_BAR; PG8_SCHED;
;             PG8_LDA(At, 0, 1); PG8_STAGE(PG8_SB(0, 0), b2, voffB); PG8_STAGE(PG8_SB(0, 1), b2 + hstepB, voffB); PG8_STAGE(PG8_SA(0, 0), a2, voffA);
;             PG8_WAIT_V(8); PG8_WAIT_L(0); PG8_BAR; PG8_MMA(1, 0, At, B0); PG8_MMA(1, 1, At, B1); PG8_BAR; PG8_SCHED;
.LBB0_902:
	s_ashr_i32 s29, s28, 31
	s_lshl_b64 s[0:1], s[28:29], 19
	s_add_u32 s30, s10, s0
	s_addc_u32 s31, s11, s1
	s_and_b64 s[0:1], s[8:9], exec
	s_cselect_b32 s0, s31, s37
	s_cselect_b32 s1, s30, s36
	s_ashr_i32 s27, s26, 31
	s_lshl_b64 s[34:35], s[26:27], 19
	s_add_u32 s34, s3, s34
	s_addc_u32 s35, s42, s35
	s_and_b64 s[40:41], s[8:9], exec
	s_cselect_b32 s2, s35, s39
	s_cselect_b32 s5, s34, s38
	s_add_u32 s36, s36, 0x40080
	s_addc_u32 s37, s37, 0
	s_add_u32 s27, s38, 0x100
	s_addc_u32 s29, s39, 0
	s_mov_b32 s33, -2
	s_waitcnt lgkmcnt(0)
	ds_read_b128 v[130:133], v186
	ds_read_b128 v[134:137], v186 offset:1024
	ds_read_b128 v[138:141], v186 offset:2048
	ds_read_b128 v[142:145], v186 offset:3072
	ds_read_b128 v[164:167], v187
	ds_read_b128 v[168:171], v187 offset:1024
	ds_read_b128 v[172:175], v187 offset:2048
	ds_read_b128 v[176:179], v187 offset:3072
	s_add_u32 s38, s36, 0xfffc0080
	s_addc_u32 s39, s37, -1
	s_cmp_eq_u32 s33, 12
	s_cselect_b32 s41, s0, s39
	s_cselect_b32 s40, s1, s38
	s_cselect_b32 s39, s2, s29
	s_cselect_b32 s38, s5, s27
	v_lshl_add_u64 v[220:221], s[36:37], 0, v[156:157]
	s_add_i32 m0, s44, 0xc000
	ds_read_b128 v[180:183], v188
	ds_read_b128 v[192:195], v188 offset:1024
	ds_read_b128 v[196:199], v188 offset:2048
	ds_read_b128 v[200:203], v188 offset:3072
	ds_read_b128 v[204:207], v188 offset:4096
	ds_read_b128 v[208:211], v188 offset:5120
	ds_read_b128 v[212:215], v188 offset:6144
	ds_read_b128 v[216:219], v188 offset:7168
	global_load_lds_dwordx4 v[220:221], off
	v_lshl_add_u64 v[220:221], s[36:37], 0, v[158:159]
	s_add_i32 m0, s44, 0xe000
	s_nop 0
	global_load_lds_dwordx4 v[220:221], off
	s_waitcnt vmcnt(8)
	s_waitcnt lgkmcnt(0)
	s_barrier
	s_setprio 1
	s_waitcnt lgkmcnt(0)
	v_mfma_f32_16x16x32_bf16 v[126:129], v[130:133], v[180:183], 0
	v_mfma_f32_16x16x32_bf16 v[122:125], v[138:141], v[180:183], 0
	v_mfma_f32_16x16x32_bf16 v[110:113], v[130:133], v[196:199], 0
	v_mfma_f32_16x16x32_bf16 v[106:109], v[138:141], v[196:199], 0
	v_mfma_f32_16x16x32_bf16 v[94:97], v[130:133], v[204:207], 0
	v_mfma_f32_16x16x32_bf16 v[90:93], v[138:141], v[204:207], 0
	v_mfma_f32_16x16x32_bf16 v[78:81], v[130:133], v[212:215], 0
	v_mfma_f32_16x16x32_bf16 v[74:77], v[138:141], v[212:215], 0
	v_mfma_f32_16x16x32_bf16 v[126:129], v[134:137], v[192:195], v[126:129]
	v_mfma_f32_16x16x32_bf16 v[122:125], v[142:145], v[192:195], v[122:125]
	v_mfma_f32_16x16x32_bf16 v[110:113], v[134:137], v[200:203], v[110:113]
	v_mfma_f32_16x16x32_bf16 v[106:109], v[142:145], v[200:203], v[106:109]
	v_mfma_f32_16x16x32_bf16 v[94:97], v[134:137], v[208:211], v[94:97]
	v_mfma_f32_16x16x32_bf16 v[90:93], v[142:145], v[208:211], v[90:93]
	v_mfma_f32_16x16x32_bf16 v[78:81], v[134:137], v[216:219], v[78:81]
	v_mfma_f32_16x16x32_bf16 v[74:77], v[142:145], v[216:219], v[74:77]
	s_setprio 0
	s_setprio 1
	v_mfma_f32_16x16x32_bf16 v[118:121], v[164:167], v[180:183], 0
	v_mfma_f32_16x16x32_bf16 v[114:117], v[172:175], v[180:183], 0
	v_mfma_f32_16x16x32_bf16 v[102:105], v[164:167], v[196:199], 0
	v_mfma_f32_16x16x32_bf16 v[98:101], v[172:175], v[196:199], 0
	v_mfma_f32_16x16x32_bf16 v[86:89], v[164:167], v[204:207], 0
	v_mfma_f32_16x16x32_bf16 v[82:85], v[172:175], v[204:207], 0
	v_mfma_f32_16x16x32_bf16 v[70:73], v[164:167], v[212:215], 0
	v_mfma_f32_16x16x32_bf16 v[66:69], v[172:175], v[212:215], 0
	v_mfma_f32_16x16x32_bf16 v[118:121], v[168:171], v[192:195], v[118:121]
	v_mfma_f32_16x16x32_bf16 v[114:117], v[176:179], v[192:195], v[114:117]
	v_mfma_f32_16x16x32_bf16 v[102:105], v[168:171], v[200:203], v[102:105]
	v_mfma_f32_16x16x32_bf16 v[98:101], v[176:179], v[200:203], v[98:101]
	v_mfma_f32_16x16x32_bf16 v[86:89], v[168:171], v[208:211], v[86:89]
	v_mfma_f32_16x16x32_bf16 v[82:85], v[176:179], v[208:211], v[82:85]
	v_mfma_f32_16x16x32_bf16 v[70:73], v[168:171], v[216:219], v[70:73]
	v_mfma_f32_16x16x32_bf16 v[66:69], v[176:179], v[216:219], v[66:69]
	s_setprio 0
	s_barrier
	s_add_i32 s58, s55, s43
	v_lshl_add_u64 v[220:221], s[38:39], 0, v[148:149]
	s_mov_b32 m0, s58
	ds_read_b128 v[180:183], v188 offset:16384
	ds_read_b128 v[192:195], v188 offset:17408
	ds_read_b128 v[196:199], v188 offset:18432
	ds_read_b128 v[200:203], v188 offset:19456
	ds_read_b128 v[204:207], v188 offset:20480
	ds_read_b128 v[208:211], v188 offset:21504
	ds_read_b128 v[212:215], v188 offset:22528
	ds_read_b128 v[216:219], v188 offset:23552
	global_load_lds_dwordx4 v[220:221], off
	s_add_i32 m0, s58, 0x2000
	s_add_u32 s58, s38, 0x40000
	v_lshl_add_u64 v[222:223], s[38:39], 0, v[152:153]
	s_addc_u32 s59, s39, 0
	s_add_i32 s60, s56, s43
	global_load_lds_dwordx4 v[222:223], off
	v_lshl_add_u64 v[224:225], s[58:59], 0, v[148:149]
	s_mov_b32 m0, s60
	v_lshl_add_u64 v[226:227], s[40:41], 0, v[150:151]
	global_load_lds_dwordx4 v[224:225], off
	v_lshl_add_u64 v[224:225], s[58:59], 0, v[152:153]
	s_add_i32 m0, s60, 0x2000
	s_nop 0
	global_load_lds_dwordx4 v[224:225], off
	v_lshl_add_u64 v[224:225], s[40:41], 0, v[146:147]
	s_mov_b32 m0, s44
	s_nop 0
	global_load_lds_dwordx4 v[224:225], off
	s_mov_b32 m0, s45
	s_nop 0
	global_load_lds_dwordx4 v[226:227], off
	s_waitcnt vmcnt(8)
	s_waitcnt lgkmcnt(0)
	s_barrier
; #define PG8_STAGE(bufoff, gbase, voff) do { _Pragma("unroll") for (int _i = 0; _i < 2; ++_i) \
;         __builtin_amdgcn_global_load_lds((const unsigned*)((const char*)(gbase) + (voff)[_i]), (PG8_LAS unsigned*)(lds + (bufoff) + ldsw + _i * 8192), 16, 0, 0); } while (0)
; #define PG8_LDA(dst, b, h) do { _Pragma("unroll") for (int m = 0; m < 4; ++m) _Pragma("unroll") for (int k = 0; k < 2; ++k) dst[m][k] = *(const PG8_LAS bf16x8*)(lds + PG8_SA(b, h) + aoff + m * 2048 + k * 1024); } while (0)
; #define PG8_LDB(dst, b, h) do { _Pragma("unroll") for (int n = 0; n < 2; ++n) _Pragma("unroll") for (int k = 0; k < 2; ++k) dst[n][k] = *(const PG8_LAS bf16x8*)(lds + PG8_SB(b, h) + boff + n * 2048 + k * 1024); } while (0)
; #define PG8_MMA(ai, bj, At, Bt) do { __builtin_amdgcn_s_setprio(1); _Pragma("unroll") for (int m = 0; m < 4; ++m) _Pragma("unroll") for (int n = 0; n < 2; ++n) _Pragma("unroll") for (int k = 0; k < 2; ++k) \
;         acc[ai][bj][m][n] = __builtin_amdgcn_mfma_f32_16x16x32_bf16(Bt[n][k], At[m][k], acc[ai][bj][m][n], 0, 0, 0); __builtin_amdgcn_s_setprio(0); } while (0)
; #define PG8_WAIT_V(n) asm volatile("s_waitcnt vmcnt(" #n ")" ::: "memory")
; #define PG8_WAIT_L(n) asm volatile("s_waitcnt lgkmcnt(" #n ")" ::: "memory")
; #define PG8_BAR __builtin_amdgcn_s_barrier()
; #define PG8_SCHED __builtin_amdgcn_sched_barrier(0)
; template <class Epi, class Sched, bool ALIGN_EPI = false, bool SP2 = false>
; __device__ __forceinline__ void gemm_phase(PG8_LAS unsigned char* lds, const Gemm g, const Sched& S, const Epi& E) {
;     ...
;             PG8_WAIT_V(8); PG8_WAIT_L(0); PG8_BAR; PG8_MMA(1, 0, At, B0); PG8_MMA(1, 1, At, B1); PG8_BAR; PG8_SCHED;
;             PG8_LDB(B0, 1, 0); PG8_LDB(B1, 1, 1); PG8_SCHED; PG8_LDA(At, 1, 0); PG8_STAGE(PG8_SA(0, 1), a2 + hstepA, voffA);
;             PG8_WAIT_V(8); PG8_WAIT_L(0); PG8_BAR; PG8_MMA(0, 0, At, B0); PG8_MMA(0, 1, At, B1); PG8_BAR; PG8_SCHED;
	s_setprio 1
	s_waitcnt lgkmcnt(0)
	v_mfma_f32_16x16x32_bf16 v[62:65], v[130:133], v[180:183], 0
	v_mfma_f32_16x16x32_bf16 v[58:61], v[138:141], v[180:183], 0
	v_mfma_f32_16x16x32_bf16 v[46:49], v[130:133], v[196:199], 0
	v_mfma_f32_16x16x32_bf16 v[42:45], v[138:141], v[196:199], 0
	v_mfma_f32_16x16x32_bf16 v[30:33], v[130:133], v[204:207], 0
	v_mfma_f32_16x16x32_bf16 v[26:29], v[138:141], v[204:207], 0
	v_mfma_f32_16x16x32_bf16 v[14:17], v[130:133], v[212:215], 0
	v_mfma_f32_16x16x32_bf16 v[10:13], v[138:141], v[212:215], 0
	v_mfma_f32_16x16x32_bf16 v[62:65], v[134:137], v[192:195], v[62:65]
	v_mfma_f32_16x16x32_bf16 v[58:61], v[142:145], v[192:195], v[58:61]
	v_mfma_f32_16x16x32_bf16 v[46:49], v[134:137], v[200:203], v[46:49]
	v_mfma_f32_16x16x32_bf16 v[42:45], v[142:145], v[200:203], v[42:45]
	v_mfma_f32_16x16x32_bf16 v[30:33], v[134:137], v[208:211], v[30:33]
	v_mfma_f32_16x16x32_bf16 v[26:29], v[142:145], v[208:211], v[26:29]
	v_mfma_f32_16x16x32_bf16 v[14:17], v[134:137], v[216:219], v[14:17]
	v_mfma_f32_16x16x32_bf16 v[10:13], v[142:145], v[216:219], v[10:13]
	s_setprio 0
	s_setprio 1
	v_mfma_f32_16x16x32_bf16 v[54:57], v[164:167], v[180:183], 0
	v_mfma_f32_16x16x32_bf16 v[50:53], v[172:175], v[180:183], 0
	v_mfma_f32_16x16x32_bf16 v[38:41], v[164:167], v[196:199], 0
	v_mfma_f32_16x16x32_bf16 v[34:37], v[172:175], v[196:199], 0
	v_mfma_f32_16x16x32_bf16 v[22:25], v[164:167], v[204:207], 0
	v_mfma_f32_16x16x32_bf16 v[18:21], v[172:175], v[204:207], 0
	v_mfma_f32_16x16x32_bf16 v[6:9], v[164:167], v[212:215], 0
	v_mfma_f32_16x16x32_bf16 v[2:5], v[172:175], v[212:215], 0
	v_mfma_f32_16x16x32_bf16 v[54:57], v[168:171], v[192:195], v[54:57]
	v_mfma_f32_16x16x32_bf16 v[50:53], v[176:179], v[192:195], v[50:53]
	v_mfma_f32_16x16x32_bf16 v[38:41], v[168:171], v[200:203], v[38:41]
	v_mfma_f32_16x16x32_bf16 v[34:37], v[176:179], v[200:203], v[34:37]
	v_mfma_f32_16x16x32_bf16 v[22:25], v[168:171], v[208:211], v[22:25]
	v_mfma_f32_16x16x32_bf16 v[18:21], v[176:179], v[208:211], v[18:21]
	v_mfma_f32_16x16x32_bf16 v[6:9], v[168:171], v[216:219], v[6:9]
	v_mfma_f32_16x16x32_bf16 v[2:5], v[176:179], v[216:219], v[2:5]
	s_setprio 0
	s_barrier
	s_add_i32 s58, 0, 0x18000
	s_add_i32 s59, 0, 0x1c000
	v_add_u32_e32 v142, s58, v184
	v_add_u32_e32 v176, s59, v184
	ds_read_b128 v[130:133], v142
	ds_read_b128 v[134:137], v142 offset:1024
	ds_read_b128 v[138:141], v142 offset:2048
	ds_read_b128 v[142:145], v142 offset:3072
	ds_read_b128 v[164:167], v176
	ds_read_b128 v[168:171], v176 offset:1024
	ds_read_b128 v[172:175], v176 offset:2048
	ds_read_b128 v[176:179], v176 offset:3072
	s_add_u32 s40, s40, 0x40000
	s_addc_u32 s41, s41, 0
	s_mov_b32 m0, s46
	v_lshl_add_u64 v[228:229], s[40:41], 0, v[146:147]
	ds_read_b128 v[180:183], v188 offset:32768
	ds_read_b128 v[192:195], v188 offset:33792
	ds_read_b128 v[196:199], v188 offset:34816
	ds_read_b128 v[200:203], v188 offset:35840
	ds_read_b128 v[204:207], v188 offset:36864
	ds_read_b128 v[208:211], v188 offset:37888
	ds_read_b128 v[212:215], v188 offset:38912
	ds_read_b128 v[216:219], v188 offset:39936
	global_load_lds_dwordx4 v[228:229], off
	v_lshl_add_u64 v[228:229], s[40:41], 0, v[150:151]
	s_mov_b32 m0, s47
	s_nop 0
	global_load_lds_dwordx4 v[228:229], off
	s_waitcnt vmcnt(8)
	s_waitcnt lgkmcnt(0)
	s_barrier
	s_setprio 1
	s_waitcnt lgkmcnt(0)
	v_mfma_f32_16x16x32_bf16 v[126:129], v[130:133], v[180:183], v[126:129]
	v_mfma_f32_16x16x32_bf16 v[122:125], v[138:141], v[180:183], v[122:125]
	v_mfma_f32_16x16x32_bf16 v[110:113], v[130:133], v[196:199], v[110:113]
	v_mfma_f32_16x16x32_bf16 v[106:109], v[138:141], v[196:199], v[106:109]
	v_mfma_f32_16x16x32_bf16 v[94:97], v[130:133], v[204:207], v[94:97]
	v_mfma_f32_16x16x32_bf16 v[90:93], v[138:141], v[204:207], v[90:93]
	v_mfma_f32_16x16x32_bf16 v[78:81], v[130:133], v[212:215], v[78:81]
	v_mfma_f32_16x16x32_bf16 v[74:77], v[138:141], v[212:215], v[74:77]
	v_mfma_f32_16x16x32_bf16 v[126:129], v[134:137], v[192:195], v[126:129]
	v_mfma_f32_16x16x32_bf16 v[122:125], v[142:145], v[192:195], v[122:125]
	v_mfma_f32_16x16x32_bf16 v[110:113], v[134:137], v[200:203], v[110:113]
	v_mfma_f32_16x16x32_bf16 v[106:109], v[142:145], v[200:203], v[106:109]
	v_mfma_f32_16x16x32_bf16 v[94:97], v[134:137], v[208:211], v[94:97]
	v_mfma_f32_16x16x32_bf16 v[90:93], v[142:145], v[208:211], v[90:93]
	v_mfma_f32_16x16x32_bf16 v[78:81], v[134:137], v[216:219], v[78:81]
	v_mfma_f32_16x16x32_bf16 v[74:77], v[142:145], v[216:219], v[74:77]
	s_setprio 0
	s_setprio 1
	v_mfma_f32_16x16x32_bf16 v[118:121], v[164:167], v[180:183], v[118:121]
	v_mfma_f32_16x16x32_bf16 v[114:117], v[172:175], v[180:183], v[114:117]
	v_mfma_f32_16x16x32_bf16 v[102:105], v[164:167], v[196:199], v[102:105]
	v_mfma_f32_16x16x32_bf16 v[98:101], v[172:175], v[196:199], v[98:101]
	v_mfma_f32_16x16x32_bf16 v[86:89], v[164:167], v[204:207], v[86:89]
	v_mfma_f32_16x16x32_bf16 v[82:85], v[172:175], v[204:207], v[82:85]
	v_mfma_f32_16x16x32_bf16 v[70:73], v[164:167], v[212:215], v[70:73]
	v_mfma_f32_16x16x32_bf16 v[66:69], v[172:175], v[212:215], v[66:69]
	v_mfma_f32_16x16x32_bf16 v[118:121], v[168:171], v[192:195], v[118:121]
	v_mfma_f32_16x16x32_bf16 v[114:117], v[176:179], v[192:195], v[114:117]
	v_mfma_f32_16x16x32_bf16 v[102:105], v[168:171], v[200:203], v[102:105]
	v_mfma_f32_16x16x32_bf16 v[98:101], v[176:179], v[200:203], v[98:101]
	v_mfma_f32_16x16x32_bf16 v[86:89], v[168:171], v[208:211], v[86:89]
	v_mfma_f32_16x16x32_bf16 v[82:85], v[176:179], v[208:211], v[82:85]
	v_mfma_f32_16x16x32_bf16 v[70:73], v[168:171], v[216:219], v[70:73]
	v_mfma_f32_16x16x32_bf16 v[66:69], v[176:179], v[216:219], v[66:69]
	s_setprio 0
	s_barrier
; #define PG8_STAGE(bufoff, gbase, voff) do { _Pragma("unroll") for (int _i = 0; _i < 2; ++_i) \
;         __builtin_amdgcn_global_load_lds((const unsigned*)((const char*)(gbase) + (voff)[_i]), (PG8_LAS unsigned*)(lds + (bufoff) + ldsw + _i * 8192), 16, 0, 0); } while (0)
; #define PG8_LDA(dst, b, h) do { _Pragma("unroll") for (int m = 0; m < 4; ++m) _Pragma("unroll") for (int k = 0; k < 2; ++k) dst[m][k] = *(const PG8_LAS bf16x8*)(lds + PG8_SA(b, h) + aoff + m * 2048 + k * 1024); } while (0)
; #define PG8_MMA(ai, bj, At, Bt) do { __builtin_amdgcn_s_setprio(1); _Pragma("unroll") for (int m = 0; m < 4; ++m) _Pragma("unroll") for (int n = 0; n < 2; ++n) _Pragma("unroll") for (int k = 0; k < 2; ++k) \
;         acc[ai][bj][m][n] = __builtin_amdgcn_mfma_f32_16x16x32_bf16(Bt[n][k], At[m][k], acc[ai][bj][m][n], 0, 0, 0); __builtin_amdgcn_s_setprio(0); } while (0)
; #define PG8_WAIT_V(n) asm volatile("s_waitcnt vmcnt(" #n ")" ::: "memory")
; #define PG8_WAIT_L(n) asm volatile("s_waitcnt lgkmcnt(" #n ")" ::: "memory")
; #define PG8_BAR __builtin_amdgcn_s_barrier()
; #define PG8_SCHED __builtin_amdgcn_sched_barrier(0)
; template <class Epi, class Sched, bool ALIGN_EPI = false, bool SP2 = false>
; __device__ __forceinline__ void gemm_phase(PG8_LAS unsigned char* lds, const Gemm g, const Sched& S, const Epi& E) {
;     ...
;         for (int t = 0; t < nt; t += 2) {
;     ...
;             PG8_LDA(At, 1, 1); PG8_STAGE(PG8_SB(1, 0), b3, voffB); PG8_STAGE(PG8_SB(1, 1), b3 + hstepB, voffB); PG8_STAGE(PG8_SA(1, 0), a3, voffA);
;             PG8_WAIT_V(8); PG8_WAIT_L(0); PG8_BAR; PG8_MMA(1, 0, At, B0); PG8_MMA(1, 1, At, B1); PG8_BAR; PG8_SCHED;
	s_add_i32 s40, s58, s43
	v_lshl_add_u64 v[220:221], v[220:221], 0, s[22:23]
	s_mov_b32 m0, s40
	ds_read_b128 v[180:183], v188 offset:49152
	ds_read_b128 v[192:195], v188 offset:50176
	ds_read_b128 v[196:199], v188 offset:51200
	ds_read_b128 v[200:203], v188 offset:52224
	ds_read_b128 v[204:207], v188 offset:53248
	ds_read_b128 v[208:211], v188 offset:54272
	ds_read_b128 v[212:215], v188 offset:55296
	ds_read_b128 v[216:219], v188 offset:56320
	global_load_lds_dwordx4 v[220:221], off
	s_add_i32 m0, s40, 0x2000
	s_add_u32 s38, s38, 0x40080
	v_lshl_add_u64 v[220:221], v[222:223], 0, s[22:23]
	s_addc_u32 s39, s39, 0
	s_add_i32 s40, s59, s43
	global_load_lds_dwordx4 v[220:221], off
	v_lshl_add_u64 v[220:221], s[38:39], 0, v[148:149]
	s_mov_b32 m0, s40
	s_nop 0
	global_load_lds_dwordx4 v[220:221], off
	v_lshl_add_u64 v[220:221], s[38:39], 0, v[152:153]
	s_add_i32 m0, s40, 0x2000
	s_nop 0
	global_load_lds_dwordx4 v[220:221], off
	v_lshl_add_u64 v[220:221], v[224:225], 0, s[22:23]
	s_mov_b32 m0, s50
	s_nop 0
	global_load_lds_dwordx4 v[220:221], off
	v_lshl_add_u64 v[220:221], v[226:227], 0, s[22:23]
	s_mov_b32 m0, s51
	s_nop 0
	global_load_lds_dwordx4 v[220:221], off
	s_waitcnt vmcnt(8)
	s_waitcnt lgkmcnt(0)
	s_barrier
	s_setprio 1
	s_waitcnt lgkmcnt(0)
	v_mfma_f32_16x16x32_bf16 v[62:65], v[130:133], v[180:183], v[62:65]
	v_mfma_f32_16x16x32_bf16 v[58:61], v[138:141], v[180:183], v[58:61]
	v_mfma_f32_16x16x32_bf16 v[46:49], v[130:133], v[196:199], v[46:49]
	v_mfma_f32_16x16x32_bf16 v[42:45], v[138:141], v[196:199], v[42:45]
	v_mfma_f32_16x16x32_bf16 v[30:33], v[130:133], v[204:207], v[30:33]
	v_mfma_f32_16x16x32_bf16 v[26:29], v[138:141], v[204:207], v[26:29]
	v_mfma_f32_16x16x32_bf16 v[14:17], v[130:133], v[212:215], v[14:17]
	v_mfma_f32_16x16x32_bf16 v[10:13], v[138:141], v[212:215], v[10:13]
	v_mfma_f32_16x16x32_bf16 v[62:65], v[134:137], v[192:195], v[62:65]
	v_mfma_f32_16x16x32_bf16 v[58:61], v[142:145], v[192:195], v[58:61]
	v_mfma_f32_16x16x32_bf16 v[46:49], v[134:137], v[200:203], v[46:49]
	v_mfma_f32_16x16x32_bf16 v[42:45], v[142:145], v[200:203], v[42:45]
	v_mfma_f32_16x16x32_bf16 v[30:33], v[134:137], v[208:211], v[30:33]
	v_mfma_f32_16x16x32_bf16 v[26:29], v[142:145], v[208:211], v[26:29]
	v_mfma_f32_16x16x32_bf16 v[14:17], v[134:137], v[216:219], v[14:17]
	v_mfma_f32_16x16x32_bf16 v[10:13], v[142:145], v[216:219], v[10:13]
	s_setprio 0
	s_setprio 1
	v_mfma_f32_16x16x32_bf16 v[54:57], v[164:167], v[180:183], v[54:57]
	v_mfma_f32_16x16x32_bf16 v[50:53], v[172:175], v[180:183], v[50:53]
	v_mfma_f32_16x16x32_bf16 v[38:41], v[164:167], v[196:199], v[38:41]
	v_mfma_f32_16x16x32_bf16 v[34:37], v[172:175], v[196:199], v[34:37]
	v_mfma_f32_16x16x32_bf16 v[22:25], v[164:167], v[204:207], v[22:25]
	v_mfma_f32_16x16x32_bf16 v[18:21], v[172:175], v[204:207], v[18:21]
	v_mfma_f32_16x16x32_bf16 v[6:9], v[164:167], v[212:215], v[6:9]
	v_mfma_f32_16x16x32_bf16 v[2:5], v[172:175], v[212:215], v[2:5]
	v_mfma_f32_16x16x32_bf16 v[54:57], v[168:171], v[192:195], v[54:57]
	v_mfma_f32_16x16x32_bf16 v[50:53], v[176:179], v[192:195], v[50:53]
	v_mfma_f32_16x16x32_bf16 v[38:41], v[168:171], v[200:203], v[38:41]
	v_mfma_f32_16x16x32_bf16 v[34:37], v[176:179], v[200:203], v[34:37]
	v_mfma_f32_16x16x32_bf16 v[22:25], v[168:171], v[208:211], v[22:25]
	v_mfma_f32_16x16x32_bf16 v[18:21], v[176:179], v[208:211], v[18:21]
	v_mfma_f32_16x16x32_bf16 v[6:9], v[168:171], v[216:219], v[6:9]
	v_mfma_f32_16x16x32_bf16 v[2:5], v[176:179], v[216:219], v[2:5]
	s_setprio 0
	s_barrier
	s_add_i32 s33, s33, 2
	s_add_u32 s36, s36, 0x100
	s_addc_u32 s37, s37, 0
	s_add_u32 s27, s27, 0x100
	s_addc_u32 s29, s29, 0
	s_cmp_gt_u32 s33, 13

; #define PG8_STAGE(bufoff, gbase, voff) do { _Pragma("unroll") for (int _i = 0; _i < 2; ++_i) \
;         __builtin_amdgcn_global_load_lds((const unsigned*)((const char*)(gbase) + (voff)[_i]), (PG8_LAS unsigned*)(lds + (bufoff) + ldsw + _i * 8192), 16, 0, 0); } while (0)
; #define PG8_LDA(dst, b, h) do { _Pragma("unroll") for (int m = 0; m < 4; ++m) _Pragma("unroll") for (int k = 0; k < 2; ++k) dst[m][k] = *(const PG8_LAS bf16x8*)(lds + PG8_SA(b, h) + aoff + m * 2048 + k * 1024); } while (0)
; #define PG8_LDB(dst, b, h) do { _Pragma("unroll") for (int n = 0; n < 2; ++n) _Pragma("unroll") for (int k = 0; k < 2; ++k) dst[n][k] = *(const PG8_LAS bf16x8*)(lds + PG8_SB(b, h) + boff + n * 2048 + k * 1024); } while (0)
; #define PG8_WAIT_V(n) asm volatile("s_waitcnt vmcnt(" #n ")" ::: "memory")
; #define PG8_WAIT_L(n) asm volatile("s_waitcnt lgkmcnt(" #n ")" ::: "memory")
; #define PG8_BAR __builtin_amdgcn_s_barrier()
; template <class Epi, class Sched, bool ALIGN_EPI = false, bool SP2 = false>
; __device__ __forceinline__ void gemm_phase(PG8_LAS unsigned char* lds, const Gemm g, const Sched& S, const Epi& E) {
;     ...
;         const bool has_next = S.next(ui + 1, nxt);
;         const char* nA = has_next ? (const char*)g.A + (size_t)nxt.g * g.gsA * 2 + (size_t)nxt.pm * tstepA : cA; const char* nB = has_next ? (const char*)g.Bt + (size_t)nxt.g * g.gsB * 2 + (size_t)nxt.pn * tstepB : cB;
;         for (int t = 0; t < nt; t += 2) {
;             const bool last = (t == nt - 2);
;             const char* a1 = cA + (size_t)(t + 1) * kstep;
;             const char* a2 = last ? nA : cA + (size_t)(t + 2) * kstep; const char* b2 = last ? nB : cB + (size_t)(t + 2) * kstep;
;             const char* a3 = a2 + kstep; const char* b3 = b2 + kstep;
;             if (last && has_next) S.a_ready(nxt);
;             if constexpr (SP2) {
;             PG8_LDB(B0, 0, 0); PG8_LDB(B1, 0, 1); PG8_SCHED; PG8_LDA(At, 0, 0); PG8_STAGE(PG8_SA(1, 1), a1 + hstepA, voffA);
;             PG8_WAIT_V(8); PG8_WAIT_L(0); PG8_BAR; PG8_MMA(0, 0, At, B0); PG8_MMA(0, 1, At, B1); PG8_BAR; PG8_SCHED;
;             PG8_LDA(At, 0, 1); PG8_STAGE(PG8_SB(0, 0), b2, voffB); PG8_STAGE(PG8_SB(0, 1), b2 + hstepB, voffB); PG8_STAGE(PG8_SA(0, 0), a2, voffA);
;             PG8_WAIT_V(8); PG8_WAIT_L(0); PG8_BAR; PG8_MMA(1, 0, At, B0); PG8_MMA(1, 1, At, B1); PG8_BAR; PG8_SCHED;
.LBB0_988:
	s_ashr_i32 s19, s18, 31
	s_lshl_b64 s[20:21], s[18:19], 19
	s_add_u32 s20, s3, s20
	s_addc_u32 s21, s30, s21
	s_and_b64 s[22:23], s[6:7], exec
	s_cselect_b32 s1, s21, s25
	s_cselect_b32 s5, s20, s24
	s_ashr_i32 s17, s16, 31
	s_lshl_b64 s[22:23], s[16:17], 19
	s_add_u32 s22, s31, s22
	s_addc_u32 s23, s34, s23
	s_and_b64 s[28:29], s[6:7], exec
	s_cselect_b32 s17, s23, s27
	s_cselect_b32 s19, s22, s26
	s_add_u32 s24, s24, 0x40080
	s_addc_u32 s25, s25, 0
	s_add_u32 s55, s26, 0x100
	s_addc_u32 s56, s27, 0
	s_mov_b32 s57, -2
	ds_read_b128 v[164:167], v157
	ds_read_b128 v[174:177], v157 offset:1024
	ds_read_b128 v[178:181], v157 offset:2048
	ds_read_b128 v[182:185], v157 offset:3072
	ds_read_b128 v[186:189], v159
	ds_read_b128 v[190:193], v159 offset:1024
	ds_read_b128 v[194:197], v159 offset:2048
	ds_read_b128 v[198:201], v159 offset:3072
	s_add_u32 s26, s24, 0xfffc0080
	s_addc_u32 s27, s25, -1
	s_cmp_eq_u32 s57, 12
	s_cselect_b32 s29, s1, s27
	s_cselect_b32 s28, s5, s26
	s_cselect_b32 s27, s17, s56
	s_cselect_b32 s26, s19, s55
	v_lshl_add_u64 v[154:155], s[24:25], 0, v[144:145]
	s_add_i32 m0, s38, 0xc000
	ds_read_b128 v[202:205], v161
	ds_read_b128 v[206:209], v161 offset:1024
	ds_read_b128 v[210:213], v161 offset:2048
	ds_read_b128 v[214:217], v161 offset:3072
	ds_read_b128 v[218:221], v161 offset:4096
	ds_read_b128 v[222:225], v161 offset:5120
	ds_read_b128 v[226:229], v161 offset:6144
	ds_read_b128 v[230:233], v161 offset:7168
	global_load_lds_dwordx4 v[154:155], off
	v_lshl_add_u64 v[154:155], s[24:25], 0, v[146:147]
	s_add_i32 m0, s38, 0xe000
	s_nop 0
	global_load_lds_dwordx4 v[154:155], off
	s_waitcnt vmcnt(8)
	s_waitcnt lgkmcnt(0)
	s_barrier
	s_setprio 1
	s_waitcnt lgkmcnt(0)
	v_mfma_f32_16x16x32_bf16 v[126:129], v[164:167], v[202:205], 0
	v_mfma_f32_16x16x32_bf16 v[122:125], v[178:181], v[202:205], 0
	v_mfma_f32_16x16x32_bf16 v[110:113], v[164:167], v[210:213], 0
	v_mfma_f32_16x16x32_bf16 v[106:109], v[178:181], v[210:213], 0
	v_mfma_f32_16x16x32_bf16 v[94:97], v[164:167], v[218:221], 0
	v_mfma_f32_16x16x32_bf16 v[90:93], v[178:181], v[218:221], 0
	v_mfma_f32_16x16x32_bf16 v[78:81], v[164:167], v[226:229], 0
	v_mfma_f32_16x16x32_bf16 v[74:77], v[178:181], v[226:229], 0
	v_mfma_f32_16x16x32_bf16 v[126:129], v[174:177], v[206:209], v[126:129]
	v_mfma_f32_16x16x32_bf16 v[122:125], v[182:185], v[206:209], v[122:125]
	v_mfma_f32_16x16x32_bf16 v[110:113], v[174:177], v[214:217], v[110:113]
	v_mfma_f32_16x16x32_bf16 v[106:109], v[182:185], v[214:217], v[106:109]
	v_mfma_f32_16x16x32_bf16 v[94:97], v[174:177], v[222:225], v[94:97]
	v_mfma_f32_16x16x32_bf16 v[90:93], v[182:185], v[222:225], v[90:93]
	v_mfma_f32_16x16x32_bf16 v[78:81], v[174:177], v[230:233], v[78:81]
	v_mfma_f32_16x16x32_bf16 v[74:77], v[182:185], v[230:233], v[74:77]
	s_setprio 0
	s_setprio 1
	v_mfma_f32_16x16x32_bf16 v[118:121], v[186:189], v[202:205], 0
	v_mfma_f32_16x16x32_bf16 v[114:117], v[194:197], v[202:205], 0
	v_mfma_f32_16x16x32_bf16 v[102:105], v[186:189], v[210:213], 0
	v_mfma_f32_16x16x32_bf16 v[98:101], v[194:197], v[210:213], 0
	v_mfma_f32_16x16x32_bf16 v[86:89], v[186:189], v[218:221], 0
	v_mfma_f32_16x16x32_bf16 v[82:85], v[194:197], v[218:221], 0
	v_mfma_f32_16x16x32_bf16 v[70:73], v[186:189], v[226:229], 0
	v_mfma_f32_16x16x32_bf16 v[66:69], v[194:197], v[226:229], 0
	v_mfma_f32_16x16x32_bf16 v[118:121], v[190:193], v[206:209], v[118:121]
	v_mfma_f32_16x16x32_bf16 v[114:117], v[198:201], v[206:209], v[114:117]
	v_mfma_f32_16x16x32_bf16 v[102:105], v[190:193], v[214:217], v[102:105]
	v_mfma_f32_16x16x32_bf16 v[98:101], v[198:201], v[214:217], v[98:101]
	v_mfma_f32_16x16x32_bf16 v[86:89], v[190:193], v[222:225], v[86:89]
	v_mfma_f32_16x16x32_bf16 v[82:85], v[198:201], v[222:225], v[82:85]
	v_mfma_f32_16x16x32_bf16 v[70:73], v[190:193], v[230:233], v[70:73]
	v_mfma_f32_16x16x32_bf16 v[66:69], v[198:201], v[230:233], v[66:69]
	s_setprio 0
	s_barrier
	s_add_i32 s58, s49, s35
	v_lshl_add_u64 v[154:155], s[26:27], 0, v[134:135]
	s_mov_b32 m0, s58
	ds_read_b128 v[202:205], v161 offset:16384
	ds_read_b128 v[206:209], v161 offset:17408
	ds_read_b128 v[210:213], v161 offset:18432
	ds_read_b128 v[214:217], v161 offset:19456
	ds_read_b128 v[218:221], v161 offset:20480
	ds_read_b128 v[222:225], v161 offset:21504
	ds_read_b128 v[226:229], v161 offset:22528
	ds_read_b128 v[230:233], v161 offset:23552
	global_load_lds_dwordx4 v[154:155], off
	s_add_i32 m0, s58, 0x2000
	s_add_u32 s58, s26, 0x40000
	v_lshl_add_u64 v[168:169], s[26:27], 0, v[130:131]
	s_addc_u32 s59, s27, 0
	s_add_i32 s60, s50, s35
	global_load_lds_dwordx4 v[168:169], off
	v_lshl_add_u64 v[234:235], s[58:59], 0, v[134:135]
	s_mov_b32 m0, s60
	v_lshl_add_u64 v[236:237], s[28:29], 0, v[132:133]
	global_load_lds_dwordx4 v[234:235], off
	v_lshl_add_u64 v[234:235], s[58:59], 0, v[130:131]
	s_add_i32 m0, s60, 0x2000
	s_nop 0
	global_load_lds_dwordx4 v[234:235], off
	v_lshl_add_u64 v[234:235], s[28:29], 0, v[136:137]
	s_mov_b32 m0, s38
	s_nop 0
	global_load_lds_dwordx4 v[234:235], off
	s_mov_b32 m0, s39
	s_nop 0
	global_load_lds_dwordx4 v[236:237], off
	s_waitcnt vmcnt(8)
	s_waitcnt lgkmcnt(0)
	s_barrier
; #define PG8_STAGE(bufoff, gbase, voff) do { _Pragma("unroll") for (int _i = 0; _i < 2; ++_i) \
;         __builtin_amdgcn_global_load_lds((const unsigned*)((const char*)(gbase) + (voff)[_i]), (PG8_LAS unsigned*)(lds + (bufoff) + ldsw + _i * 8192), 16, 0, 0); } while (0)
; #define PG8_LDA(dst, b, h) do { _Pragma("unroll") for (int m = 0; m < 4; ++m) _Pragma("unroll") for (int k = 0; k < 2; ++k) dst[m][k] = *(const PG8_LAS bf16x8*)(lds + PG8_SA(b, h) + aoff + m * 2048 + k * 1024); } while (0)
; #define PG8_LDB(dst, b, h) do { _Pragma("unroll") for (int n = 0; n < 2; ++n) _Pragma("unroll") for (int k = 0; k < 2; ++k) dst[n][k] = *(const PG8_LAS bf16x8*)(lds + PG8_SB(b, h) + boff + n * 2048 + k * 1024); } while (0)
; #define PG8_MMA(ai, bj, At, Bt) do { __builtin_amdgcn_s_setprio(1); _Pragma("unroll") for (int m = 0; m < 4; ++m) _Pragma("unroll") for (int n = 0; n < 2; ++n) _Pragma("unroll") for (int k = 0; k < 2; ++k) \
;         acc[ai][bj][m][n] = __builtin_amdgcn_mfma_f32_16x16x32_bf16(Bt[n][k], At[m][k], acc[ai][bj][m][n], 0, 0, 0); __builtin_amdgcn_s_setprio(0); } while (0)
; #define PG8_WAIT_V(n) asm volatile("s_waitcnt vmcnt(" #n ")" ::: "memory")
; #define PG8_WAIT_L(n) asm volatile("s_waitcnt lgkmcnt(" #n ")" ::: "memory")
; #define PG8_BAR __builtin_amdgcn_s_barrier()
; #define PG8_SCHED __builtin_amdgcn_sched_barrier(0)
; template <class Epi, class Sched, bool ALIGN_EPI = false, bool SP2 = false>
; __device__ __forceinline__ void gemm_phase(PG8_LAS unsigned char* lds, const Gemm g, const Sched& S, const Epi& E) {
;     ...
;             PG8_WAIT_V(8); PG8_WAIT_L(0); PG8_BAR; PG8_MMA(1, 0, At, B0); PG8_MMA(1, 1, At, B1); PG8_BAR; PG8_SCHED;
;             PG8_LDB(B0, 1, 0); PG8_LDB(B1, 1, 1); PG8_SCHED; PG8_LDA(At, 1, 0); PG8_STAGE(PG8_SA(0, 1), a2 + hstepA, voffA);
;             PG8_WAIT_V(8); PG8_WAIT_L(0); PG8_BAR; PG8_MMA(0, 0, At, B0); PG8_MMA(0, 1, At, B1); PG8_BAR; PG8_SCHED;
	s_setprio 1
	s_waitcnt lgkmcnt(0)
	v_mfma_f32_16x16x32_bf16 v[62:65], v[164:167], v[202:205], 0
	v_mfma_f32_16x16x32_bf16 v[58:61], v[178:181], v[202:205], 0
	v_mfma_f32_16x16x32_bf16 v[46:49], v[164:167], v[210:213], 0
	v_mfma_f32_16x16x32_bf16 v[42:45], v[178:181], v[210:213], 0
	v_mfma_f32_16x16x32_bf16 v[30:33], v[164:167], v[218:221], 0
	v_mfma_f32_16x16x32_bf16 v[26:29], v[178:181], v[218:221], 0
	v_mfma_f32_16x16x32_bf16 v[14:17], v[164:167], v[226:229], 0
	v_mfma_f32_16x16x32_bf16 v[10:13], v[178:181], v[226:229], 0
	v_mfma_f32_16x16x32_bf16 v[62:65], v[174:177], v[206:209], v[62:65]
	v_mfma_f32_16x16x32_bf16 v[58:61], v[182:185], v[206:209], v[58:61]
	v_mfma_f32_16x16x32_bf16 v[46:49], v[174:177], v[214:217], v[46:49]
	v_mfma_f32_16x16x32_bf16 v[42:45], v[182:185], v[214:217], v[42:45]
	v_mfma_f32_16x16x32_bf16 v[30:33], v[174:177], v[222:225], v[30:33]
	v_mfma_f32_16x16x32_bf16 v[26:29], v[182:185], v[222:225], v[26:29]
	v_mfma_f32_16x16x32_bf16 v[14:17], v[174:177], v[230:233], v[14:17]
	v_mfma_f32_16x16x32_bf16 v[10:13], v[182:185], v[230:233], v[10:13]
	s_setprio 0
	s_setprio 1
	v_mfma_f32_16x16x32_bf16 v[54:57], v[186:189], v[202:205], 0
	v_mfma_f32_16x16x32_bf16 v[50:53], v[194:197], v[202:205], 0
	v_mfma_f32_16x16x32_bf16 v[38:41], v[186:189], v[210:213], 0
	v_mfma_f32_16x16x32_bf16 v[34:37], v[194:197], v[210:213], 0
	v_mfma_f32_16x16x32_bf16 v[22:25], v[186:189], v[218:221], 0
	v_mfma_f32_16x16x32_bf16 v[18:21], v[194:197], v[218:221], 0
	v_mfma_f32_16x16x32_bf16 v[6:9], v[186:189], v[226:229], 0
	v_mfma_f32_16x16x32_bf16 v[2:5], v[194:197], v[226:229], 0
	v_mfma_f32_16x16x32_bf16 v[54:57], v[190:193], v[206:209], v[54:57]
	v_mfma_f32_16x16x32_bf16 v[50:53], v[198:201], v[206:209], v[50:53]
	v_mfma_f32_16x16x32_bf16 v[38:41], v[190:193], v[214:217], v[38:41]
	v_mfma_f32_16x16x32_bf16 v[34:37], v[198:201], v[214:217], v[34:37]
	v_mfma_f32_16x16x32_bf16 v[22:25], v[190:193], v[222:225], v[22:25]
	v_mfma_f32_16x16x32_bf16 v[18:21], v[198:201], v[222:225], v[18:21]
	v_mfma_f32_16x16x32_bf16 v[6:9], v[190:193], v[230:233], v[6:9]
	v_mfma_f32_16x16x32_bf16 v[2:5], v[198:201], v[230:233], v[2:5]
	s_setprio 0
	s_barrier
	s_add_i32 s58, 0, 0x18000
	v_add_u32_e32 v138, s58, v141
	s_add_i32 s59, 0, 0x1c000
	ds_read_b128 v[164:167], v138
	ds_read_b128 v[174:177], v138 offset:1024
	ds_read_b128 v[178:181], v138 offset:2048
	ds_read_b128 v[182:185], v138 offset:3072
	v_add_u32_e32 v138, s59, v141
	ds_read_b128 v[186:189], v138
	ds_read_b128 v[190:193], v138 offset:1024
	ds_read_b128 v[194:197], v138 offset:2048
	ds_read_b128 v[198:201], v138 offset:3072
	s_add_u32 s28, s28, 0x40000
	s_addc_u32 s29, s29, 0
	s_mov_b32 m0, s40
	v_lshl_add_u64 v[238:239], s[28:29], 0, v[136:137]
	ds_read_b128 v[202:205], v161 offset:32768
	ds_read_b128 v[206:209], v161 offset:33792
	ds_read_b128 v[210:213], v161 offset:34816
	ds_read_b128 v[214:217], v161 offset:35840
	ds_read_b128 v[218:221], v161 offset:36864
	ds_read_b128 v[222:225], v161 offset:37888
	ds_read_b128 v[226:229], v161 offset:38912
	ds_read_b128 v[230:233], v161 offset:39936
	global_load_lds_dwordx4 v[238:239], off
	v_lshl_add_u64 v[238:239], s[28:29], 0, v[132:133]
	s_mov_b32 m0, s41
	s_nop 0
	global_load_lds_dwordx4 v[238:239], off
	s_waitcnt vmcnt(8)
	s_waitcnt lgkmcnt(0)
	s_barrier
	s_setprio 1
	s_waitcnt lgkmcnt(0)
	v_mfma_f32_16x16x32_bf16 v[126:129], v[164:167], v[202:205], v[126:129]
	v_mfma_f32_16x16x32_bf16 v[122:125], v[178:181], v[202:205], v[122:125]
	v_mfma_f32_16x16x32_bf16 v[110:113], v[164:167], v[210:213], v[110:113]
	v_mfma_f32_16x16x32_bf16 v[106:109], v[178:181], v[210:213], v[106:109]
	v_mfma_f32_16x16x32_bf16 v[94:97], v[164:167], v[218:221], v[94:97]
	v_mfma_f32_16x16x32_bf16 v[90:93], v[178:181], v[218:221], v[90:93]
	v_mfma_f32_16x16x32_bf16 v[78:81], v[164:167], v[226:229], v[78:81]
	v_mfma_f32_16x16x32_bf16 v[74:77], v[178:181], v[226:229], v[74:77]
	v_mfma_f32_16x16x32_bf16 v[126:129], v[174:177], v[206:209], v[126:129]
	v_mfma_f32_16x16x32_bf16 v[122:125], v[182:185], v[206:209], v[122:125]
	v_mfma_f32_16x16x32_bf16 v[110:113], v[174:177], v[214:217], v[110:113]
	v_mfma_f32_16x16x32_bf16 v[106:109], v[182:185], v[214:217], v[106:109]
	v_mfma_f32_16x16x32_bf16 v[94:97], v[174:177], v[222:225], v[94:97]
	v_mfma_f32_16x16x32_bf16 v[90:93], v[182:185], v[222:225], v[90:93]
	v_mfma_f32_16x16x32_bf16 v[78:81], v[174:177], v[230:233], v[78:81]
	v_mfma_f32_16x16x32_bf16 v[74:77], v[182:185], v[230:233], v[74:77]
	s_setprio 0
	s_setprio 1
	v_mfma_f32_16x16x32_bf16 v[118:121], v[186:189], v[202:205], v[118:121]
	v_mfma_f32_16x16x32_bf16 v[114:117], v[194:197], v[202:205], v[114:117]
	v_mfma_f32_16x16x32_bf16 v[102:105], v[186:189], v[210:213], v[102:105]
	v_mfma_f32_16x16x32_bf16 v[98:101], v[194:197], v[210:213], v[98:101]
	v_mfma_f32_16x16x32_bf16 v[86:89], v[186:189], v[218:221], v[86:89]
	v_mfma_f32_16x16x32_bf16 v[82:85], v[194:197], v[218:221], v[82:85]
	v_mfma_f32_16x16x32_bf16 v[70:73], v[186:189], v[226:229], v[70:73]
	v_mfma_f32_16x16x32_bf16 v[66:69], v[194:197], v[226:229], v[66:69]
	v_mfma_f32_16x16x32_bf16 v[118:121], v[190:193], v[206:209], v[118:121]
	v_mfma_f32_16x16x32_bf16 v[114:117], v[198:201], v[206:209], v[114:117]
	v_mfma_f32_16x16x32_bf16 v[102:105], v[190:193], v[214:217], v[102:105]
	v_mfma_f32_16x16x32_bf16 v[98:101], v[198:201], v[214:217], v[98:101]
	v_mfma_f32_16x16x32_bf16 v[86:89], v[190:193], v[222:225], v[86:89]
	v_mfma_f32_16x16x32_bf16 v[82:85], v[198:201], v[222:225], v[82:85]
	v_mfma_f32_16x16x32_bf16 v[70:73], v[190:193], v[230:233], v[70:73]
	v_mfma_f32_16x16x32_bf16 v[66:69], v[198:201], v[230:233], v[66:69]
	s_setprio 0
	s_barrier
; #define PG8_STAGE(bufoff, gbase, voff) do { _Pragma("unroll") for (int _i = 0; _i < 2; ++_i) \
;         __builtin_amdgcn_global_load_lds((const unsigned*)((const char*)(gbase) + (voff)[_i]), (PG8_LAS unsigned*)(lds + (bufoff) + ldsw + _i * 8192), 16, 0, 0); } while (0)
; #define PG8_LDA(dst, b, h) do { _Pragma("unroll") for (int m = 0; m < 4; ++m) _Pragma("unroll") for (int k = 0; k < 2; ++k) dst[m][k] = *(const PG8_LAS bf16x8*)(lds + PG8_SA(b, h) + aoff + m * 2048 + k * 1024); } while (0)
; #define PG8_MMA(ai, bj, At, Bt) do { __builtin_amdgcn_s_setprio(1); _Pragma("unroll") for (int m = 0; m < 4; ++m) _Pragma("unroll") for (int n = 0; n < 2; ++n) _Pragma("unroll") for (int k = 0; k < 2; ++k) \
;         acc[ai][bj][m][n] = __builtin_amdgcn_mfma_f32_16x16x32_bf16(Bt[n][k], At[m][k], acc[ai][bj][m][n], 0, 0, 0); __builtin_amdgcn_s_setprio(0); } while (0)
; #define PG8_WAIT_V(n) asm volatile("s_waitcnt vmcnt(" #n ")" ::: "memory")
; #define PG8_WAIT_L(n) asm volatile("s_waitcnt lgkmcnt(" #n ")" ::: "memory")
; #define PG8_BAR __builtin_amdgcn_s_barrier()
; #define PG8_SCHED __builtin_amdgcn_sched_barrier(0)
; template <class Epi, class Sched, bool ALIGN_EPI = false, bool SP2 = false>
; __device__ __forceinline__ void gemm_phase(PG8_LAS unsigned char* lds, const Gemm g, const Sched& S, const Epi& E) {
;     ...
;         for (int t = 0; t < nt; t += 2) {
;     ...
;             PG8_LDA(At, 1, 1); PG8_STAGE(PG8_SB(1, 0), b3, voffB); PG8_STAGE(PG8_SB(1, 1), b3 + hstepB, voffB); PG8_STAGE(PG8_SA(1, 0), a3, voffA);
;             PG8_WAIT_V(8); PG8_WAIT_L(0); PG8_BAR; PG8_MMA(1, 0, At, B0); PG8_MMA(1, 1, At, B1); PG8_BAR; PG8_SCHED;
	s_add_i32 s28, s58, s35
	v_lshl_add_u64 v[154:155], v[154:155], 0, s[12:13]
	s_mov_b32 m0, s28
	ds_read_b128 v[202:205], v161 offset:49152
	ds_read_b128 v[206:209], v161 offset:50176
	ds_read_b128 v[210:213], v161 offset:51200
	ds_read_b128 v[214:217], v161 offset:52224
	ds_read_b128 v[218:221], v161 offset:53248
	ds_read_b128 v[222:225], v161 offset:54272
	ds_read_b128 v[226:229], v161 offset:55296
	ds_read_b128 v[230:233], v161 offset:56320
	global_load_lds_dwordx4 v[154:155], off
	s_add_i32 m0, s28, 0x2000
	s_add_u32 s26, s26, 0x40080
	v_lshl_add_u64 v[154:155], v[168:169], 0, s[12:13]
	s_addc_u32 s27, s27, 0
	s_add_i32 s28, s59, s35
	global_load_lds_dwordx4 v[154:155], off
	v_lshl_add_u64 v[154:155], s[26:27], 0, v[134:135]
	s_mov_b32 m0, s28
	s_nop 0
	global_load_lds_dwordx4 v[154:155], off
	v_lshl_add_u64 v[154:155], s[26:27], 0, v[130:131]
	s_add_i32 m0, s28, 0x2000
	s_nop 0
	global_load_lds_dwordx4 v[154:155], off
	v_lshl_add_u64 v[154:155], v[234:235], 0, s[12:13]
	s_mov_b32 m0, s2
	s_nop 0
	global_load_lds_dwordx4 v[154:155], off
	v_lshl_add_u64 v[154:155], v[236:237], 0, s[12:13]
	s_mov_b32 m0, s33
	s_nop 0
	global_load_lds_dwordx4 v[154:155], off
	s_waitcnt vmcnt(8)
	s_waitcnt lgkmcnt(0)
	s_barrier
	s_setprio 1
	s_waitcnt lgkmcnt(0)
	v_mfma_f32_16x16x32_bf16 v[62:65], v[164:167], v[202:205], v[62:65]
	v_mfma_f32_16x16x32_bf16 v[58:61], v[178:181], v[202:205], v[58:61]
	v_mfma_f32_16x16x32_bf16 v[46:49], v[164:167], v[210:213], v[46:49]
	v_mfma_f32_16x16x32_bf16 v[42:45], v[178:181], v[210:213], v[42:45]
	v_mfma_f32_16x16x32_bf16 v[30:33], v[164:167], v[218:221], v[30:33]
	v_mfma_f32_16x16x32_bf16 v[26:29], v[178:181], v[218:221], v[26:29]
	v_mfma_f32_16x16x32_bf16 v[14:17], v[164:167], v[226:229], v[14:17]
	v_mfma_f32_16x16x32_bf16 v[10:13], v[178:181], v[226:229], v[10:13]
	v_mfma_f32_16x16x32_bf16 v[62:65], v[174:177], v[206:209], v[62:65]
	v_mfma_f32_16x16x32_bf16 v[58:61], v[182:185], v[206:209], v[58:61]
	v_mfma_f32_16x16x32_bf16 v[46:49], v[174:177], v[214:217], v[46:49]
	v_mfma_f32_16x16x32_bf16 v[42:45], v[182:185], v[214:217], v[42:45]
	v_mfma_f32_16x16x32_bf16 v[30:33], v[174:177], v[222:225], v[30:33]
	v_mfma_f32_16x16x32_bf16 v[26:29], v[182:185], v[222:225], v[26:29]
	v_mfma_f32_16x16x32_bf16 v[14:17], v[174:177], v[230:233], v[14:17]
	v_mfma_f32_16x16x32_bf16 v[10:13], v[182:185], v[230:233], v[10:13]
	s_setprio 0
	s_setprio 1
	v_mfma_f32_16x16x32_bf16 v[54:57], v[186:189], v[202:205], v[54:57]
	v_mfma_f32_16x16x32_bf16 v[50:53], v[194:197], v[202:205], v[50:53]
	v_mfma_f32_16x16x32_bf16 v[38:41], v[186:189], v[210:213], v[38:41]
	v_mfma_f32_16x16x32_bf16 v[34:37], v[194:197], v[210:213], v[34:37]
	v_mfma_f32_16x16x32_bf16 v[22:25], v[186:189], v[218:221], v[22:25]
	v_mfma_f32_16x16x32_bf16 v[18:21], v[194:197], v[218:221], v[18:21]
	v_mfma_f32_16x16x32_bf16 v[6:9], v[186:189], v[226:229], v[6:9]
	v_mfma_f32_16x16x32_bf16 v[2:5], v[194:197], v[226:229], v[2:5]
	v_mfma_f32_16x16x32_bf16 v[54:57], v[190:193], v[206:209], v[54:57]
	v_mfma_f32_16x16x32_bf16 v[50:53], v[198:201], v[206:209], v[50:53]
	v_mfma_f32_16x16x32_bf16 v[38:41], v[190:193], v[214:217], v[38:41]
	v_mfma_f32_16x16x32_bf16 v[34:37], v[198:201], v[214:217], v[34:37]
	v_mfma_f32_16x16x32_bf16 v[22:25], v[190:193], v[222:225], v[22:25]
	v_mfma_f32_16x16x32_bf16 v[18:21], v[198:201], v[222:225], v[18:21]
	v_mfma_f32_16x16x32_bf16 v[6:9], v[190:193], v[230:233], v[6:9]
	v_mfma_f32_16x16x32_bf16 v[2:5], v[198:201], v[230:233], v[2:5]
	s_setprio 0
	s_barrier
	s_add_i32 s57, s57, 2
	s_add_u32 s24, s24, 0x100
	s_addc_u32 s25, s25, 0
	s_add_u32 s55, s55, 0x100
	s_addc_u32 s56, s56, 0
	s_cmp_gt_u32 s57, 13

; #define PG8_STAGE(bufoff, gbase, voff) do { _Pragma("unroll") for (int _i = 0; _i < 2; ++_i) \
;         __builtin_amdgcn_global_load_lds((const unsigned*)((const char*)(gbase) + (voff)[_i]), (PG8_LAS unsigned*)(lds + (bufoff) + ldsw + _i * 8192), 16, 0, 0); } while (0)
; #define PG8_LDA(dst, b, h) do { _Pragma("unroll") for (int m = 0; m < 4; ++m) _Pragma("unroll") for (int k = 0; k < 2; ++k) dst[m][k] = *(const PG8_LAS bf16x8*)(lds + PG8_SA(b, h) + aoff + m * 2048 + k * 1024); } while (0)
; #define PG8_LDB(dst, b, h) do { _Pragma("unroll") for (int n = 0; n < 2; ++n) _Pragma("unroll") for (int k = 0; k < 2; ++k) dst[n][k] = *(const PG8_LAS bf16x8*)(lds + PG8_SB(b, h) + boff + n * 2048 + k * 1024); } while (0)
; #define PG8_WAIT_V(n) asm volatile("s_waitcnt vmcnt(" #n ")" ::: "memory")
; #define PG8_WAIT_L(n) asm volatile("s_waitcnt lgkmcnt(" #n ")" ::: "memory")
; #define PG8_BAR __builtin_amdgcn_s_barrier()
; template <class Epi, class Sched, bool ALIGN_EPI = false, bool SP2 = false>
; __device__ __forceinline__ void gemm_phase(PG8_LAS unsigned char* lds, const Gemm g, const Sched& S, const Epi& E) {
;     ...
;         const bool has_next = S.next(ui + 1, nxt);
;         const char* nA = has_next ? (const char*)g.A + (size_t)nxt.g * g.gsA * 2 + (size_t)nxt.pm * tstepA : cA; const char* nB = has_next ? (const char*)g.Bt + (size_t)nxt.g * g.gsB * 2 + (size_t)nxt.pn * tstepB : cB;
;         for (int t = 0; t < nt; t += 2) {
;             const bool last = (t == nt - 2);
;             const char* a1 = cA + (size_t)(t + 1) * kstep;
;             const char* a2 = last ? nA : cA + (size_t)(t + 2) * kstep; const char* b2 = last ? nB : cB + (size_t)(t + 2) * kstep;
;             const char* a3 = a2 + kstep; const char* b3 = b2 + kstep;
;             if (last && has_next) S.a_ready(nxt);
;             if constexpr (SP2) {
;             PG8_LDB(B0, 0, 0); PG8_LDB(B1, 0, 1); PG8_SCHED; PG8_LDA(At, 0, 0); PG8_STAGE(PG8_SA(1, 1), a1 + hstepA, voffA);
;             PG8_WAIT_V(8); PG8_WAIT_L(0); PG8_BAR; PG8_MMA(0, 0, At, B0); PG8_MMA(0, 1, At, B1); PG8_BAR; PG8_SCHED;
;             PG8_LDA(At, 0, 1); PG8_STAGE(PG8_SB(0, 0), b2, voffB); PG8_STAGE(PG8_SB(0, 1), b2 + hstepB, voffB); PG8_STAGE(PG8_SA(0, 0), a2, voffA);
;             PG8_WAIT_V(8); PG8_WAIT_L(0); PG8_BAR; PG8_MMA(1, 0, At, B0); PG8_MMA(1, 1, At, B1); PG8_BAR; PG8_SCHED;
.LBB0_1466:
	s_ashr_i32 s23, s22, 31
	s_lshl_b64 s[24:25], s[22:23], 19
	s_add_u32 s24, s2, s24
	s_addc_u32 s25, s3, s25
	s_and_b64 s[26:27], s[8:9], exec
	s_cselect_b32 s23, s25, s31
	s_cselect_b32 s29, s24, s30
	s_ashr_i32 s21, s20, 31
	s_lshl_b64 s[26:27], s[20:21], 19
	s_add_u32 s26, s33, s26
	s_addc_u32 s27, s38, s27
	s_and_b64 s[36:37], s[8:9], exec
	s_cselect_b32 s21, s27, s35
	s_cselect_b32 s51, s26, s34
	s_add_u32 s30, s30, 0x40080
	s_addc_u32 s31, s31, 0
	s_add_u32 s52, s34, 0x100
	s_addc_u32 s53, s35, 0
	s_mov_b32 s54, -2
	s_waitcnt lgkmcnt(0)
	ds_read_b128 v[130:133], v164
	ds_read_b128 v[134:137], v164 offset:1024
	ds_read_b128 v[154:157], v164 offset:2048
	ds_read_b128 v[158:161], v164 offset:3072
	ds_read_b128 v[168:171], v165
	ds_read_b128 v[172:175], v165 offset:1024
	ds_read_b128 v[176:179], v165 offset:2048
	ds_read_b128 v[180:183], v165 offset:3072
	s_add_u32 s34, s30, 0xfffc0080
	s_addc_u32 s35, s31, -1
	s_cmp_eq_u32 s54, 12
	s_cselect_b32 s37, s23, s35
	s_cselect_b32 s36, s29, s34
	s_cselect_b32 s35, s21, s53
	s_cselect_b32 s34, s51, s52
	v_lshl_add_u64 v[216:217], s[30:31], 0, v[146:147]
	s_add_i32 m0, s1, 0xc000
	ds_read_b128 v[184:187], v166
	ds_read_b128 v[188:191], v166 offset:1024
	ds_read_b128 v[192:195], v166 offset:2048
	ds_read_b128 v[196:199], v166 offset:3072
	ds_read_b128 v[200:203], v166 offset:4096
	ds_read_b128 v[204:207], v166 offset:5120
	ds_read_b128 v[208:211], v166 offset:6144
	ds_read_b128 v[212:215], v166 offset:7168
	global_load_lds_dwordx4 v[216:217], off
	v_lshl_add_u64 v[216:217], s[30:31], 0, v[148:149]
	s_add_i32 m0, s1, 0xe000
	s_nop 0
	global_load_lds_dwordx4 v[216:217], off
	s_waitcnt vmcnt(8)
	s_waitcnt lgkmcnt(0)
	s_barrier
	s_setprio 1
	s_waitcnt lgkmcnt(0)
	v_mfma_f32_16x16x32_bf16 v[126:129], v[130:133], v[184:187], 0
	v_mfma_f32_16x16x32_bf16 v[122:125], v[154:157], v[184:187], 0
	v_mfma_f32_16x16x32_bf16 v[110:113], v[130:133], v[192:195], 0
	v_mfma_f32_16x16x32_bf16 v[106:109], v[154:157], v[192:195], 0
	v_mfma_f32_16x16x32_bf16 v[94:97], v[130:133], v[200:203], 0
	v_mfma_f32_16x16x32_bf16 v[90:93], v[154:157], v[200:203], 0
	v_mfma_f32_16x16x32_bf16 v[78:81], v[130:133], v[208:211], 0
	v_mfma_f32_16x16x32_bf16 v[74:77], v[154:157], v[208:211], 0
	v_mfma_f32_16x16x32_bf16 v[126:129], v[134:137], v[188:191], v[126:129]
	v_mfma_f32_16x16x32_bf16 v[122:125], v[158:161], v[188:191], v[122:125]
	v_mfma_f32_16x16x32_bf16 v[110:113], v[134:137], v[196:199], v[110:113]
	v_mfma_f32_16x16x32_bf16 v[106:109], v[158:161], v[196:199], v[106:109]
	v_mfma_f32_16x16x32_bf16 v[94:97], v[134:137], v[204:207], v[94:97]
	v_mfma_f32_16x16x32_bf16 v[90:93], v[158:161], v[204:207], v[90:93]
	v_mfma_f32_16x16x32_bf16 v[78:81], v[134:137], v[212:215], v[78:81]
	v_mfma_f32_16x16x32_bf16 v[74:77], v[158:161], v[212:215], v[74:77]
	s_setprio 0
	s_setprio 1
	v_mfma_f32_16x16x32_bf16 v[118:121], v[168:171], v[184:187], 0
	v_mfma_f32_16x16x32_bf16 v[114:117], v[176:179], v[184:187], 0
	v_mfma_f32_16x16x32_bf16 v[102:105], v[168:171], v[192:195], 0
	v_mfma_f32_16x16x32_bf16 v[98:101], v[176:179], v[192:195], 0
	v_mfma_f32_16x16x32_bf16 v[86:89], v[168:171], v[200:203], 0
	v_mfma_f32_16x16x32_bf16 v[82:85], v[176:179], v[200:203], 0
	v_mfma_f32_16x16x32_bf16 v[70:73], v[168:171], v[208:211], 0
	v_mfma_f32_16x16x32_bf16 v[66:69], v[176:179], v[208:211], 0
	v_mfma_f32_16x16x32_bf16 v[118:121], v[172:175], v[188:191], v[118:121]
	v_mfma_f32_16x16x32_bf16 v[114:117], v[180:183], v[188:191], v[114:117]
	v_mfma_f32_16x16x32_bf16 v[102:105], v[172:175], v[196:199], v[102:105]
	v_mfma_f32_16x16x32_bf16 v[98:101], v[180:183], v[196:199], v[98:101]
	v_mfma_f32_16x16x32_bf16 v[86:89], v[172:175], v[204:207], v[86:89]
	v_mfma_f32_16x16x32_bf16 v[82:85], v[180:183], v[204:207], v[82:85]
	v_mfma_f32_16x16x32_bf16 v[70:73], v[172:175], v[212:215], v[70:73]
	v_mfma_f32_16x16x32_bf16 v[66:69], v[180:183], v[212:215], v[66:69]
	s_setprio 0
	s_barrier
	s_add_i32 s55, s48, s0
	v_lshl_add_u64 v[216:217], s[34:35], 0, v[140:141]
	s_mov_b32 m0, s55
	ds_read_b128 v[184:187], v166 offset:16384
	ds_read_b128 v[188:191], v166 offset:17408
	ds_read_b128 v[192:195], v166 offset:18432
	ds_read_b128 v[196:199], v166 offset:19456
	ds_read_b128 v[200:203], v166 offset:20480
	ds_read_b128 v[204:207], v166 offset:21504
	ds_read_b128 v[208:211], v166 offset:22528
	ds_read_b128 v[212:215], v166 offset:23552
	global_load_lds_dwordx4 v[216:217], off
	s_add_i32 m0, s55, 0x2000
	s_add_u32 s56, s34, 0x40000
	v_lshl_add_u64 v[218:219], s[34:35], 0, v[144:145]
	s_addc_u32 s57, s35, 0
	s_add_i32 s55, s49, s0
	global_load_lds_dwordx4 v[218:219], off
	v_lshl_add_u64 v[220:221], s[56:57], 0, v[140:141]
	s_mov_b32 m0, s55
	v_lshl_add_u64 v[222:223], s[36:37], 0, v[142:143]
	global_load_lds_dwordx4 v[220:221], off
	v_lshl_add_u64 v[220:221], s[56:57], 0, v[144:145]
	s_add_i32 m0, s55, 0x2000
	s_nop 0
	global_load_lds_dwordx4 v[220:221], off
	v_lshl_add_u64 v[220:221], s[36:37], 0, v[138:139]
	s_mov_b32 m0, s1
	s_nop 0
	global_load_lds_dwordx4 v[220:221], off
	s_mov_b32 m0, s39
	s_nop 0
	global_load_lds_dwordx4 v[222:223], off
	s_waitcnt vmcnt(8)
	s_waitcnt lgkmcnt(0)
	s_barrier
; #define PG8_STAGE(bufoff, gbase, voff) do { _Pragma("unroll") for (int _i = 0; _i < 2; ++_i) \
;         __builtin_amdgcn_global_load_lds((const unsigned*)((const char*)(gbase) + (voff)[_i]), (PG8_LAS unsigned*)(lds + (bufoff) + ldsw + _i * 8192), 16, 0, 0); } while (0)
; #define PG8_LDA(dst, b, h) do { _Pragma("unroll") for (int m = 0; m < 4; ++m) _Pragma("unroll") for (int k = 0; k < 2; ++k) dst[m][k] = *(const PG8_LAS bf16x8*)(lds + PG8_SA(b, h) + aoff + m * 2048 + k * 1024); } while (0)
; #define PG8_LDB(dst, b, h) do { _Pragma("unroll") for (int n = 0; n < 2; ++n) _Pragma("unroll") for (int k = 0; k < 2; ++k) dst[n][k] = *(const PG8_LAS bf16x8*)(lds + PG8_SB(b, h) + boff + n * 2048 + k * 1024); } while (0)
; #define PG8_MMA(ai, bj, At, Bt) do { __builtin_amdgcn_s_setprio(1); _Pragma("unroll") for (int m = 0; m < 4; ++m) _Pragma("unroll") for (int n = 0; n < 2; ++n) _Pragma("unroll") for (int k = 0; k < 2; ++k) \
;         acc[ai][bj][m][n] = __builtin_amdgcn_mfma_f32_16x16x32_bf16(Bt[n][k], At[m][k], acc[ai][bj][m][n], 0, 0, 0); __builtin_amdgcn_s_setprio(0); } while (0)
; #define PG8_WAIT_V(n) asm volatile("s_waitcnt vmcnt(" #n ")" ::: "memory")
; #define PG8_WAIT_L(n) asm volatile("s_waitcnt lgkmcnt(" #n ")" ::: "memory")
; #define PG8_BAR __builtin_amdgcn_s_barrier()
; #define PG8_SCHED __builtin_amdgcn_sched_barrier(0)
; template <class Epi, class Sched, bool ALIGN_EPI = false, bool SP2 = false>
; __device__ __forceinline__ void gemm_phase(PG8_LAS unsigned char* lds, const Gemm g, const Sched& S, const Epi& E) {
;     ...
;             PG8_WAIT_V(8); PG8_WAIT_L(0); PG8_BAR; PG8_MMA(1, 0, At, B0); PG8_MMA(1, 1, At, B1); PG8_BAR; PG8_SCHED;
;             PG8_LDB(B0, 1, 0); PG8_LDB(B1, 1, 1); PG8_SCHED; PG8_LDA(At, 1, 0); PG8_STAGE(PG8_SA(0, 1), a2 + hstepA, voffA);
;             PG8_WAIT_V(8); PG8_WAIT_L(0); PG8_BAR; PG8_MMA(0, 0, At, B0); PG8_MMA(0, 1, At, B1); PG8_BAR; PG8_SCHED;
	s_setprio 1
	s_waitcnt lgkmcnt(0)
	v_mfma_f32_16x16x32_bf16 v[62:65], v[130:133], v[184:187], 0
	v_mfma_f32_16x16x32_bf16 v[58:61], v[154:157], v[184:187], 0
	v_mfma_f32_16x16x32_bf16 v[46:49], v[130:133], v[192:195], 0
	v_mfma_f32_16x16x32_bf16 v[42:45], v[154:157], v[192:195], 0
	v_mfma_f32_16x16x32_bf16 v[30:33], v[130:133], v[200:203], 0
	v_mfma_f32_16x16x32_bf16 v[26:29], v[154:157], v[200:203], 0
	v_mfma_f32_16x16x32_bf16 v[14:17], v[130:133], v[208:211], 0
	v_mfma_f32_16x16x32_bf16 v[10:13], v[154:157], v[208:211], 0
	v_mfma_f32_16x16x32_bf16 v[62:65], v[134:137], v[188:191], v[62:65]
	v_mfma_f32_16x16x32_bf16 v[58:61], v[158:161], v[188:191], v[58:61]
	v_mfma_f32_16x16x32_bf16 v[46:49], v[134:137], v[196:199], v[46:49]
	v_mfma_f32_16x16x32_bf16 v[42:45], v[158:161], v[196:199], v[42:45]
	v_mfma_f32_16x16x32_bf16 v[30:33], v[134:137], v[204:207], v[30:33]
	v_mfma_f32_16x16x32_bf16 v[26:29], v[158:161], v[204:207], v[26:29]
	v_mfma_f32_16x16x32_bf16 v[14:17], v[134:137], v[212:215], v[14:17]
	v_mfma_f32_16x16x32_bf16 v[10:13], v[158:161], v[212:215], v[10:13]
	s_setprio 0
	s_setprio 1
	v_mfma_f32_16x16x32_bf16 v[54:57], v[168:171], v[184:187], 0
	v_mfma_f32_16x16x32_bf16 v[50:53], v[176:179], v[184:187], 0
	v_mfma_f32_16x16x32_bf16 v[38:41], v[168:171], v[192:195], 0
	v_mfma_f32_16x16x32_bf16 v[34:37], v[176:179], v[192:195], 0
	v_mfma_f32_16x16x32_bf16 v[22:25], v[168:171], v[200:203], 0
	v_mfma_f32_16x16x32_bf16 v[18:21], v[176:179], v[200:203], 0
	v_mfma_f32_16x16x32_bf16 v[6:9], v[168:171], v[208:211], 0
	v_mfma_f32_16x16x32_bf16 v[2:5], v[176:179], v[208:211], 0
	v_mfma_f32_16x16x32_bf16 v[54:57], v[172:175], v[188:191], v[54:57]
	v_mfma_f32_16x16x32_bf16 v[50:53], v[180:183], v[188:191], v[50:53]
	v_mfma_f32_16x16x32_bf16 v[38:41], v[172:175], v[196:199], v[38:41]
	v_mfma_f32_16x16x32_bf16 v[34:37], v[180:183], v[196:199], v[34:37]
	v_mfma_f32_16x16x32_bf16 v[22:25], v[172:175], v[204:207], v[22:25]
	v_mfma_f32_16x16x32_bf16 v[18:21], v[180:183], v[204:207], v[18:21]
	v_mfma_f32_16x16x32_bf16 v[6:9], v[172:175], v[212:215], v[6:9]
	v_mfma_f32_16x16x32_bf16 v[2:5], v[180:183], v[212:215], v[2:5]
	s_setprio 0
	s_barrier
	s_add_i32 s55, 0, 0x18000
	s_add_i32 s56, 0, 0x1c000
	v_add_u32_e32 v158, s55, v162
	v_add_u32_e32 v180, s56, v162
	ds_read_b128 v[130:133], v158
	ds_read_b128 v[134:137], v158 offset:1024
	ds_read_b128 v[154:157], v158 offset:2048
	ds_read_b128 v[158:161], v158 offset:3072
	ds_read_b128 v[168:171], v180
	ds_read_b128 v[172:175], v180 offset:1024
	ds_read_b128 v[176:179], v180 offset:2048
	ds_read_b128 v[180:183], v180 offset:3072
	s_add_u32 s36, s36, 0x40000
	s_addc_u32 s37, s37, 0
	s_mov_b32 m0, s40
	v_lshl_add_u64 v[224:225], s[36:37], 0, v[138:139]
	ds_read_b128 v[184:187], v166 offset:32768
	ds_read_b128 v[188:191], v166 offset:33792
	ds_read_b128 v[192:195], v166 offset:34816
	ds_read_b128 v[196:199], v166 offset:35840
	ds_read_b128 v[200:203], v166 offset:36864
	ds_read_b128 v[204:207], v166 offset:37888
	ds_read_b128 v[208:211], v166 offset:38912
	ds_read_b128 v[212:215], v166 offset:39936
	global_load_lds_dwordx4 v[224:225], off
	v_lshl_add_u64 v[224:225], s[36:37], 0, v[142:143]
	s_mov_b32 m0, s41
	s_nop 0
	global_load_lds_dwordx4 v[224:225], off
	s_waitcnt vmcnt(8)
	s_waitcnt lgkmcnt(0)
	s_barrier
	s_setprio 1
	s_waitcnt lgkmcnt(0)
	v_mfma_f32_16x16x32_bf16 v[126:129], v[130:133], v[184:187], v[126:129]
	v_mfma_f32_16x16x32_bf16 v[122:125], v[154:157], v[184:187], v[122:125]
	v_mfma_f32_16x16x32_bf16 v[110:113], v[130:133], v[192:195], v[110:113]
	v_mfma_f32_16x16x32_bf16 v[106:109], v[154:157], v[192:195], v[106:109]
	v_mfma_f32_16x16x32_bf16 v[94:97], v[130:133], v[200:203], v[94:97]
	v_mfma_f32_16x16x32_bf16 v[90:93], v[154:157], v[200:203], v[90:93]
	v_mfma_f32_16x16x32_bf16 v[78:81], v[130:133], v[208:211], v[78:81]
	v_mfma_f32_16x16x32_bf16 v[74:77], v[154:157], v[208:211], v[74:77]
	v_mfma_f32_16x16x32_bf16 v[126:129], v[134:137], v[188:191], v[126:129]
	v_mfma_f32_16x16x32_bf16 v[122:125], v[158:161], v[188:191], v[122:125]
	v_mfma_f32_16x16x32_bf16 v[110:113], v[134:137], v[196:199], v[110:113]
	v_mfma_f32_16x16x32_bf16 v[106:109], v[158:161], v[196:199], v[106:109]
	v_mfma_f32_16x16x32_bf16 v[94:97], v[134:137], v[204:207], v[94:97]
	v_mfma_f32_16x16x32_bf16 v[90:93], v[158:161], v[204:207], v[90:93]
	v_mfma_f32_16x16x32_bf16 v[78:81], v[134:137], v[212:215], v[78:81]
	v_mfma_f32_16x16x32_bf16 v[74:77], v[158:161], v[212:215], v[74:77]
	s_setprio 0
	s_setprio 1
	v_mfma_f32_16x16x32_bf16 v[118:121], v[168:171], v[184:187], v[118:121]
	v_mfma_f32_16x16x32_bf16 v[114:117], v[176:179], v[184:187], v[114:117]
	v_mfma_f32_16x16x32_bf16 v[102:105], v[168:171], v[192:195], v[102:105]
	v_mfma_f32_16x16x32_bf16 v[98:101], v[176:179], v[192:195], v[98:101]
	v_mfma_f32_16x16x32_bf16 v[86:89], v[168:171], v[200:203], v[86:89]
	v_mfma_f32_16x16x32_bf16 v[82:85], v[176:179], v[200:203], v[82:85]
	v_mfma_f32_16x16x32_bf16 v[70:73], v[168:171], v[208:211], v[70:73]
	v_mfma_f32_16x16x32_bf16 v[66:69], v[176:179], v[208:211], v[66:69]
	v_mfma_f32_16x16x32_bf16 v[118:121], v[172:175], v[188:191], v[118:121]
	v_mfma_f32_16x16x32_bf16 v[114:117], v[180:183], v[188:191], v[114:117]
	v_mfma_f32_16x16x32_bf16 v[102:105], v[172:175], v[196:199], v[102:105]
	v_mfma_f32_16x16x32_bf16 v[98:101], v[180:183], v[196:199], v[98:101]
	v_mfma_f32_16x16x32_bf16 v[86:89], v[172:175], v[204:207], v[86:89]
	v_mfma_f32_16x16x32_bf16 v[82:85], v[180:183], v[204:207], v[82:85]
	v_mfma_f32_16x16x32_bf16 v[70:73], v[172:175], v[212:215], v[70:73]
	v_mfma_f32_16x16x32_bf16 v[66:69], v[180:183], v[212:215], v[66:69]
	s_setprio 0
	s_barrier
; #define PG8_STAGE(bufoff, gbase, voff) do { _Pragma("unroll") for (int _i = 0; _i < 2; ++_i) \
;         __builtin_amdgcn_global_load_lds((const unsigned*)((const char*)(gbase) + (voff)[_i]), (PG8_LAS unsigned*)(lds + (bufoff) + ldsw + _i * 8192), 16, 0, 0); } while (0)
; #define PG8_LDA(dst, b, h) do { _Pragma("unroll") for (int m = 0; m < 4; ++m) _Pragma("unroll") for (int k = 0; k < 2; ++k) dst[m][k] = *(const PG8_LAS bf16x8*)(lds + PG8_SA(b, h) + aoff + m * 2048 + k * 1024); } while (0)
; #define PG8_MMA(ai, bj, At, Bt) do { __builtin_amdgcn_s_setprio(1); _Pragma("unroll") for (int m = 0; m < 4; ++m) _Pragma("unroll") for (int n = 0; n < 2; ++n) _Pragma("unroll") for (int k = 0; k < 2; ++k) \
;         acc[ai][bj][m][n] = __builtin_amdgcn_mfma_f32_16x16x32_bf16(Bt[n][k], At[m][k], acc[ai][bj][m][n], 0, 0, 0); __builtin_amdgcn_s_setprio(0); } while (0)
; #define PG8_WAIT_V(n) asm volatile("s_waitcnt vmcnt(" #n ")" ::: "memory")
; #define PG8_WAIT_L(n) asm volatile("s_waitcnt lgkmcnt(" #n ")" ::: "memory")
; #define PG8_BAR __builtin_amdgcn_s_barrier()
; #define PG8_SCHED __builtin_amdgcn_sched_barrier(0)
; template <class Epi, class Sched, bool ALIGN_EPI = false, bool SP2 = false>
; __device__ __forceinline__ void gemm_phase(PG8_LAS unsigned char* lds, const Gemm g, const Sched& S, const Epi& E) {
;     ...
;         for (int t = 0; t < nt; t += 2) {
;     ...
;             PG8_LDA(At, 1, 1); PG8_STAGE(PG8_SB(1, 0), b3, voffB); PG8_STAGE(PG8_SB(1, 1), b3 + hstepB, voffB); PG8_STAGE(PG8_SA(1, 0), a3, voffA);
;             PG8_WAIT_V(8); PG8_WAIT_L(0); PG8_BAR; PG8_MMA(1, 0, At, B0); PG8_MMA(1, 1, At, B1); PG8_BAR; PG8_SCHED;
	s_add_i32 s36, s55, s0
	v_lshl_add_u64 v[216:217], v[216:217], 0, s[16:17]
	s_mov_b32 m0, s36
	ds_read_b128 v[184:187], v166 offset:49152
	ds_read_b128 v[188:191], v166 offset:50176
	ds_read_b128 v[192:195], v166 offset:51200
	ds_read_b128 v[196:199], v166 offset:52224
	ds_read_b128 v[200:203], v166 offset:53248
	ds_read_b128 v[204:207], v166 offset:54272
	ds_read_b128 v[208:211], v166 offset:55296
	ds_read_b128 v[212:215], v166 offset:56320
	global_load_lds_dwordx4 v[216:217], off
	s_add_i32 m0, s36, 0x2000
	s_add_u32 s34, s34, 0x40080
	v_lshl_add_u64 v[216:217], v[218:219], 0, s[16:17]
	s_addc_u32 s35, s35, 0
	s_add_i32 s36, s56, s0
	global_load_lds_dwordx4 v[216:217], off
	v_lshl_add_u64 v[216:217], s[34:35], 0, v[140:141]
	s_mov_b32 m0, s36
	s_nop 0
	global_load_lds_dwordx4 v[216:217], off
	v_lshl_add_u64 v[216:217], s[34:35], 0, v[144:145]
	s_add_i32 m0, s36, 0x2000
	s_nop 0
	global_load_lds_dwordx4 v[216:217], off
	v_lshl_add_u64 v[216:217], v[220:221], 0, s[16:17]
	s_mov_b32 m0, s43
	s_nop 0
	global_load_lds_dwordx4 v[216:217], off
	v_lshl_add_u64 v[216:217], v[222:223], 0, s[16:17]
	s_mov_b32 m0, s44
	s_nop 0
	global_load_lds_dwordx4 v[216:217], off
	s_waitcnt vmcnt(8)
	s_waitcnt lgkmcnt(0)
	s_barrier
	s_setprio 1
	s_waitcnt lgkmcnt(0)
	v_mfma_f32_16x16x32_bf16 v[62:65], v[130:133], v[184:187], v[62:65]
	v_mfma_f32_16x16x32_bf16 v[58:61], v[154:157], v[184:187], v[58:61]
	v_mfma_f32_16x16x32_bf16 v[46:49], v[130:133], v[192:195], v[46:49]
	v_mfma_f32_16x16x32_bf16 v[42:45], v[154:157], v[192:195], v[42:45]
	v_mfma_f32_16x16x32_bf16 v[30:33], v[130:133], v[200:203], v[30:33]
	v_mfma_f32_16x16x32_bf16 v[26:29], v[154:157], v[200:203], v[26:29]
	v_mfma_f32_16x16x32_bf16 v[14:17], v[130:133], v[208:211], v[14:17]
	v_mfma_f32_16x16x32_bf16 v[10:13], v[154:157], v[208:211], v[10:13]
	v_mfma_f32_16x16x32_bf16 v[62:65], v[134:137], v[188:191], v[62:65]
	v_mfma_f32_16x16x32_bf16 v[58:61], v[158:161], v[188:191], v[58:61]
	v_mfma_f32_16x16x32_bf16 v[46:49], v[134:137], v[196:199], v[46:49]
	v_mfma_f32_16x16x32_bf16 v[42:45], v[158:161], v[196:199], v[42:45]
	v_mfma_f32_16x16x32_bf16 v[30:33], v[134:137], v[204:207], v[30:33]
	v_mfma_f32_16x16x32_bf16 v[26:29], v[158:161], v[204:207], v[26:29]
	v_mfma_f32_16x16x32_bf16 v[14:17], v[134:137], v[212:215], v[14:17]
	v_mfma_f32_16x16x32_bf16 v[10:13], v[158:161], v[212:215], v[10:13]
	s_setprio 0
	s_setprio 1
	v_mfma_f32_16x16x32_bf16 v[54:57], v[168:171], v[184:187], v[54:57]
	v_mfma_f32_16x16x32_bf16 v[50:53], v[176:179], v[184:187], v[50:53]
	v_mfma_f32_16x16x32_bf16 v[38:41], v[168:171], v[192:195], v[38:41]
	v_mfma_f32_16x16x32_bf16 v[34:37], v[176:179], v[192:195], v[34:37]
	v_mfma_f32_16x16x32_bf16 v[22:25], v[168:171], v[200:203], v[22:25]
	v_mfma_f32_16x16x32_bf16 v[18:21], v[176:179], v[200:203], v[18:21]
	v_mfma_f32_16x16x32_bf16 v[6:9], v[168:171], v[208:211], v[6:9]
	v_mfma_f32_16x16x32_bf16 v[2:5], v[176:179], v[208:211], v[2:5]
	v_mfma_f32_16x16x32_bf16 v[54:57], v[172:175], v[188:191], v[54:57]
	v_mfma_f32_16x16x32_bf16 v[50:53], v[180:183], v[188:191], v[50:53]
	v_mfma_f32_16x16x32_bf16 v[38:41], v[172:175], v[196:199], v[38:41]
	v_mfma_f32_16x16x32_bf16 v[34:37], v[180:183], v[196:199], v[34:37]
	v_mfma_f32_16x16x32_bf16 v[22:25], v[172:175], v[204:207], v[22:25]
	v_mfma_f32_16x16x32_bf16 v[18:21], v[180:183], v[204:207], v[18:21]
	v_mfma_f32_16x16x32_bf16 v[6:9], v[172:175], v[212:215], v[6:9]
	v_mfma_f32_16x16x32_bf16 v[2:5], v[180:183], v[212:215], v[2:5]
	s_setprio 0
	s_barrier
	s_add_i32 s54, s54, 2
	s_add_u32 s30, s30, 0x100
	s_addc_u32 s31, s31, 0
	s_add_u32 s52, s52, 0x100
	s_addc_u32 s53, s53, 0
	s_cmp_gt_u32 s54, 13
